# GEMM loops: SALU-only LDS-DMA issue with saddr + counted lgkmcnt; NSA totl accumulator round trips batched
# speedup vs baseline: 1.0216x; 1.0216x over previous
; DEVI int opaque_tid() { int t = __builtin_amdgcn_workitem_id_x(); asm volatile("" : "+v"(t)); return t; }
;   const int tid = opaque_tid(), lane = tid & 63, wid = tid >> 6, wr = wid >> 1, wc = wid & 1, fr = lane & 15, fq = lane >> 4;
;   const int lrow = tid >> 3, lpos = tid & 7;
;   const int gch = (lpos ^ (lrow & 7)) * 8;
;   unsigned aoff[4], boff[NF];
; #pragma unroll
;   for (int i = 0; i < 4; ++i) aoff[i] = (unsigned)(arow(m0 + lrow + 32 * i) + gch);
; #pragma unroll
;   for (int i = 0; i < NF; ++i) boff[i] = (unsigned)((n0 + lrow + 32 * i) * ldb + gch);
;   const int nk = K >> 6;
;   if (!PRE) __syncthreads();
;     ...
;   if (!PRE) GL_ISSUE(0, 0)
;   asm volatile("s_waitcnt vmcnt(0)" ::: "memory");
;   __syncthreads();
.LBB0_37:
	s_andn2_b64 vcc, exec, s[6:7]
	s_cbranch_vccnz .LBB0_41
	v_mov_b32_e32 v18, v154
	s_lshl_b32 s6, s50, 7
	v_ashrrev_i32_e32 v20, 3, v18
	v_xor_b32_e32 v0, v20, v18
	v_lshlrev_b32_e32 v0, 3, v0
	v_and_b32_e32 v21, 56, v0
	v_add_u32_e32 v0, s6, v20
	s_lshl_b32 s36, s93, 7
	v_lshl_or_b32 v0, v0, 10, v21
	v_lshlrev_b32_e32 v66, 4, v18
	v_add_u32_e32 v2, 0x8000, v0
	v_add_u32_e32 v4, 0x10000, v0
	v_add_u32_e32 v6, 0x18000, v0
	v_add_u32_e32 v3, s36, v20
	v_lshl_add_u64 v[16:17], v[0:1], 1, s[8:9]
	v_readfirstlane_b32 s7, v66
	v_add_u32_e32 v0, 0x1000, v66
	v_lshl_or_b32 v8, v3, 10, v21
	s_mov_b32 m0, s7
	v_mov_b32_e32 v3, v1
	v_readfirstlane_b32 s7, v0
	v_add_u32_e32 v0, 0x2000, v66
	s_waitcnt lgkmcnt(0)
	s_barrier
	global_load_lds_dwordx4 v[16:17], off
	v_lshl_add_u64 v[2:3], v[2:3], 1, s[8:9]
	s_mov_b32 m0, s7
	v_mov_b32_e32 v5, v1
	v_readfirstlane_b32 s7, v0
	v_add_u32_e32 v0, 0x3000, v66
	global_load_lds_dwordx4 v[2:3], off
	v_lshl_add_u64 v[2:3], v[4:5], 1, s[8:9]
	s_mov_b32 m0, s7
	v_mov_b32_e32 v7, v1
	v_readfirstlane_b32 s7, v0
	v_add_u32_e32 v0, 0x4000, v66
	global_load_lds_dwordx4 v[2:3], off
	v_lshl_add_u64 v[2:3], v[6:7], 1, s[8:9]
	s_mov_b32 m0, s7
	v_mov_b32_e32 v9, v1
	v_readfirstlane_b32 s7, v0
	v_add_u32_e32 v0, 0x5000, v66
	v_add_u32_e32 v10, 0x8000, v8
	global_load_lds_dwordx4 v[2:3], off
	v_lshl_add_u64 v[2:3], v[8:9], 1, s[18:19]
	s_mov_b32 m0, s7
	v_mov_b32_e32 v11, v1
	v_readfirstlane_b32 s7, v0
	v_add_u32_e32 v0, 0x6000, v66
	v_add_u32_e32 v12, 0x10000, v8
	global_load_lds_dwordx4 v[2:3], off
	v_lshl_add_u64 v[2:3], v[10:11], 1, s[18:19]
	s_mov_b32 m0, s7
	v_mov_b32_e32 v13, v1
	v_readfirstlane_b32 s7, v0
	v_add_u32_e32 v0, 0x7000, v66
	v_add_u32_e32 v14, 0x18000, v8
	global_load_lds_dwordx4 v[2:3], off
	v_lshl_add_u64 v[2:3], v[12:13], 1, s[18:19]
	s_mov_b32 m0, s7
	v_mov_b32_e32 v15, v1
	v_readfirstlane_b32 s7, v0
	global_load_lds_dwordx4 v[2:3], off
	v_lshl_add_u64 v[2:3], v[14:15], 1, s[18:19]
	s_mov_b32 m0, s7
	v_bfe_u32 v0, v18, 4, 2
	global_load_lds_dwordx4 v[2:3], off
	v_and_b32_e32 v2, 7, v18
	v_bitop3_b32 v0, v0, v2, 4 bitop3:0x36
	v_lshlrev_b32_e32 v70, 4, v0
	v_lshlrev_b32_e32 v0, 10, v20
	s_lshl_b32 s7, s40, 10
	s_lshl_b32 s37, s41, 7
	v_lshrrev_b32_e32 v19, 4, v18
	v_and_b32_e32 v22, 15, v18
	s_waitcnt vmcnt(0)
	v_lshrrev_b32_e32 v3, 1, v18
	v_lshlrev_b32_e32 v4, 7, v18
	v_lshl_add_u32 v0, s93, 17, v0
	s_or_b32 s7, s37, s7
	v_and_or_b32 v3, v3, s79, v22
	v_and_b32_e32 v69, 0x2780, v4
	v_bitop3_b32 v4, v19, v2, 3 bitop3:0x6c
	v_or_b32_e32 v71, v0, v21
	v_add_u32_e32 v0, s7, v20
	v_mov_b32_e32 v2, 0
	v_lshlrev_b32_e32 v67, 4, v4
	v_lshlrev_b32_e32 v68, 7, v3
	v_lshl_or_b32 v72, v0, 10, v21
	s_mov_b32 s7, 0
	s_mov_b32 s37, 0
	v_mov_b32_e32 v3, v2
	v_mov_b32_e32 v4, v2
	v_mov_b32_e32 v5, v2
	v_mov_b32_e32 v6, v2
	v_mov_b32_e32 v7, v2
	v_mov_b32_e32 v8, v2
	v_mov_b32_e32 v9, v2
	v_mov_b32_e32 v10, v2
	v_mov_b32_e32 v11, v2
	v_mov_b32_e32 v12, v2
	v_mov_b32_e32 v13, v2
	v_mov_b32_e32 v14, v2
	v_mov_b32_e32 v15, v2
	v_mov_b32_e32 v16, v2
	v_mov_b32_e32 v17, v2
	v_mov_b32_e32 v18, v2
	v_mov_b32_e32 v19, v2
	v_mov_b32_e32 v20, v2
	v_mov_b32_e32 v21, v2
	v_mov_b32_e32 v22, v2
	v_mov_b32_e32 v23, v2
	v_mov_b32_e32 v24, v2
	v_mov_b32_e32 v25, v2
	v_mov_b32_e32 v26, v2
	v_mov_b32_e32 v27, v2
	v_mov_b32_e32 v28, v2
	v_mov_b32_e32 v29, v2
	v_mov_b32_e32 v30, v2
	v_mov_b32_e32 v31, v2
	v_mov_b32_e32 v32, v2
	v_mov_b32_e32 v33, v2
	v_mov_b32_e32 v34, v2
	v_mov_b32_e32 v35, v2
	v_mov_b32_e32 v36, v2
	v_mov_b32_e32 v37, v2
	v_mov_b32_e32 v38, v2
	v_mov_b32_e32 v39, v2
	v_mov_b32_e32 v40, v2
	v_mov_b32_e32 v41, v2
	v_mov_b32_e32 v42, v2
	v_mov_b32_e32 v43, v2
	v_mov_b32_e32 v44, v2
	v_mov_b32_e32 v45, v2
	v_mov_b32_e32 v46, v2
	v_mov_b32_e32 v47, v2
	v_mov_b32_e32 v48, v2
	v_mov_b32_e32 v49, v2
	v_mov_b32_e32 v58, v2
	v_mov_b32_e32 v59, v2
	v_mov_b32_e32 v60, v2
	v_mov_b32_e32 v61, v2
	v_mov_b32_e32 v62, v2
	v_mov_b32_e32 v63, v2
	v_mov_b32_e32 v64, v2
	v_mov_b32_e32 v65, v2
	v_mov_b32_e32 v50, v2
	v_mov_b32_e32 v51, v2
	v_mov_b32_e32 v52, v2
	v_mov_b32_e32 v53, v2
	v_mov_b32_e32 v54, v2
	v_mov_b32_e32 v55, v2
	v_mov_b32_e32 v56, v2
	v_mov_b32_e32 v57, v2
	v_lshlrev_b32_e32 v232, 1, v72
	v_add_u32_e32 v233, 0x10000, v232
	v_add_u32_e32 v234, 0x20000, v232
	v_add_u32_e32 v235, 0x30000, v232
	v_lshlrev_b32_e32 v236, 1, v71
	v_add_u32_e32 v237, 0x10000, v236
	v_add_u32_e32 v238, 0x20000, v236
	v_add_u32_e32 v239, 0x30000, v236
	v_readfirstlane_b32 s68, v66
	s_add_u32 s64, s8, 0x80
	s_addc_u32 s65, s9, 0
	s_add_u32 s66, s18, 0x80
	s_addc_u32 s67, s19, 0
	s_waitcnt vmcnt(0) lgkmcnt(0)
	s_barrier
;     ...
;   for (int kt = 0; kt < nk; ++kt) {
;     if (kt + 1 < nk) GL_ISSUE(kt + 1, (kt + 1) & 1)
;     const char* As = smem + (kt & 1) * 32768;
;     const char* Bs = As + 16384;
;     if (DEEP) {
;     bf16x8 af[2][4], bfr[2][NF];
; #pragma unroll
;     for (int ks = 0; ks < 2; ++ks) {
;       const int co = ((ks * 4 + fq) ^ swz) * 16;
; #pragma unroll
;       for (int m = 0; m < 4; ++m) af[ks][m] = *(const bf16x8*)(As + (wr * 64 + m * 16 + fr) * 128 + co);
; #pragma unroll
;       for (int n = 0; n < NF; ++n) bfr[ks][n] = *(const bf16x8*)(Bs + (wc * 16 * NF + n * 16 + fr) * 128 + co);
;     }
;     __builtin_amdgcn_s_setprio(1);
; #pragma unroll
;     for (int ks = 0; ks < 2; ++ks)
; #pragma unroll
;       for (int m = 0; m < 4; ++m)
; #pragma unroll
;         for (int n = 0; n < NF; ++n) {
;           if (SWAP) acc[m][n] = __builtin_amdgcn_mfma_f32_16x16x32_bf16(bfr[ks][n], af[ks][m], acc[m][n], 0, 0, 0);
;           else acc[m][n] = __builtin_amdgcn_mfma_f32_16x16x32_bf16(af[ks][m], bfr[ks][n], acc[m][n], 0, 0, 0);
;         }
;     __builtin_amdgcn_s_setprio(0);
;     __builtin_amdgcn_sched_group_barrier(0x100, 4 + NF, 0);
; #pragma unroll
;     for (int i = 0; i < 4 + NF; ++i) { __builtin_amdgcn_sched_group_barrier(0x008, 2, 0); __builtin_amdgcn_sched_group_barrier(0x100, 1, 0); }
;     __builtin_amdgcn_sched_group_barrier(0x008, 8 * NF - 2 * (4 + NF), 0);
.LBB0_39:
	s_and_b32 s37, s37, 0x8000
	v_or_b32_e32 v0, s37, v67
	v_add_u32_e32 v73, v0, v68
	v_add_u32_e32 v0, v0, v69
	ds_read_b128 v[90:93], v0 offset:16384
	ds_read_b128 v[94:97], v0 offset:18432
	ds_read_b128 v[98:101], v0 offset:20480
	ds_read_b128 v[102:105], v0 offset:22528
	v_or_b32_e32 v0, s37, v70
	ds_read_b128 v[74:77], v73
	ds_read_b128 v[78:81], v73 offset:2048
	ds_read_b128 v[82:85], v73 offset:4096
	ds_read_b128 v[86:89], v73 offset:6144
	s_add_i32 s38, s37, 0x8000
	s_and_b32 s69, s38, 0x8000
	s_add_i32 s69, s69, s68
	v_add_u32_e32 v73, v0, v68
	v_add_u32_e32 v0, v0, v69
	s_mov_b32 m0, s69
	s_nop 0
	global_load_lds_dwordx4 v232, s[64:65]
	ds_read_b128 v[106:109], v73
	s_add_i32 m0, s69, 0x1000
	s_nop 0
	global_load_lds_dwordx4 v233, s[64:65]
	ds_read_b128 v[110:113], v73 offset:2048
	s_add_i32 m0, s69, 0x2000
	s_nop 0
	global_load_lds_dwordx4 v234, s[64:65]
	ds_read_b128 v[114:117], v73 offset:4096
	s_add_i32 m0, s69, 0x3000
	s_nop 0
	global_load_lds_dwordx4 v235, s[64:65]
	ds_read_b128 v[118:121], v73 offset:6144
	s_add_i32 m0, s69, 0x4000
	s_nop 0
	global_load_lds_dwordx4 v236, s[66:67]
	ds_read_b128 v[126:129], v0 offset:16384
	s_add_i32 m0, s69, 0x5000
	s_nop 0
	global_load_lds_dwordx4 v237, s[66:67]
	ds_read_b128 v[130:133], v0 offset:18432
	s_add_i32 m0, s69, 0x6000
	s_nop 0
	global_load_lds_dwordx4 v238, s[66:67]
	ds_read_b128 v[134:137], v0 offset:20480
	s_add_i32 m0, s69, 0x7000
	s_nop 0
	global_load_lds_dwordx4 v239, s[66:67]
	ds_read_b128 v[138:141], v0 offset:22528
	s_add_u32 s64, s64, 0x80
	s_addc_u32 s65, s65, 0
	s_add_u32 s66, s66, 0x80
	s_addc_u32 s67, s67, 0
	s_setprio 1
	s_waitcnt lgkmcnt(11)
	v_mfma_f32_16x16x32_bf16 v[62:65], v[90:93], v[74:77], v[62:65]
	v_mfma_f32_16x16x32_bf16 v[58:61], v[94:97], v[74:77], v[58:61]
	v_mfma_f32_16x16x32_bf16 v[46:49], v[98:101], v[74:77], v[46:49]
	v_mfma_f32_16x16x32_bf16 v[42:45], v[102:105], v[74:77], v[42:45]
	s_waitcnt lgkmcnt(10)
	v_mfma_f32_16x16x32_bf16 v[38:41], v[90:93], v[78:81], v[38:41]
	v_mfma_f32_16x16x32_bf16 v[34:37], v[94:97], v[78:81], v[34:37]
	v_mfma_f32_16x16x32_bf16 v[30:33], v[98:101], v[78:81], v[30:33]
	v_mfma_f32_16x16x32_bf16 v[26:29], v[102:105], v[78:81], v[26:29]
	s_waitcnt lgkmcnt(9)
	v_mfma_f32_16x16x32_bf16 v[22:25], v[90:93], v[82:85], v[22:25]
	v_mfma_f32_16x16x32_bf16 v[18:21], v[94:97], v[82:85], v[18:21]
	v_mfma_f32_16x16x32_bf16 v[14:17], v[98:101], v[82:85], v[14:17]
	v_mfma_f32_16x16x32_bf16 v[10:13], v[102:105], v[82:85], v[10:13]
	s_waitcnt lgkmcnt(8)
	v_mfma_f32_16x16x32_bf16 v[6:9], v[90:93], v[86:89], v[6:9]
	v_mfma_f32_16x16x32_bf16 v[2:5], v[94:97], v[86:89], v[2:5]
	v_mfma_f32_16x16x32_bf16 v[50:53], v[98:101], v[86:89], v[50:53]
	v_mfma_f32_16x16x32_bf16 v[54:57], v[102:105], v[86:89], v[54:57]
	s_waitcnt lgkmcnt(3)
	v_mfma_f32_16x16x32_bf16 v[62:65], v[126:129], v[106:109], v[62:65]
	s_waitcnt lgkmcnt(2)
	v_mfma_f32_16x16x32_bf16 v[58:61], v[130:133], v[106:109], v[58:61]
	s_waitcnt lgkmcnt(1)
	v_mfma_f32_16x16x32_bf16 v[46:49], v[134:137], v[106:109], v[46:49]
	s_waitcnt lgkmcnt(0)
	v_mfma_f32_16x16x32_bf16 v[42:45], v[138:141], v[106:109], v[42:45]
	v_mfma_f32_16x16x32_bf16 v[38:41], v[126:129], v[110:113], v[38:41]
	v_mfma_f32_16x16x32_bf16 v[34:37], v[130:133], v[110:113], v[34:37]
	v_mfma_f32_16x16x32_bf16 v[30:33], v[134:137], v[110:113], v[30:33]
	v_mfma_f32_16x16x32_bf16 v[26:29], v[138:141], v[110:113], v[26:29]
	v_mfma_f32_16x16x32_bf16 v[22:25], v[126:129], v[114:117], v[22:25]
	v_mfma_f32_16x16x32_bf16 v[18:21], v[130:133], v[114:117], v[18:21]
	v_mfma_f32_16x16x32_bf16 v[14:17], v[134:137], v[114:117], v[14:17]
	v_mfma_f32_16x16x32_bf16 v[10:13], v[138:141], v[114:117], v[10:13]
	v_mfma_f32_16x16x32_bf16 v[6:9], v[126:129], v[118:121], v[6:9]
	v_mfma_f32_16x16x32_bf16 v[2:5], v[130:133], v[118:121], v[2:5]
	v_mfma_f32_16x16x32_bf16 v[50:53], v[134:137], v[118:121], v[50:53]
	v_mfma_f32_16x16x32_bf16 v[54:57], v[138:141], v[118:121], v[54:57]
	s_setprio 0
	s_waitcnt vmcnt(0)
	s_add_i32 s7, s7, 64
	s_cmpk_lg_i32 s7, 0x3c0
	s_mov_b32 s37, s38
	s_waitcnt vmcnt(0)
	s_barrier
	s_cbranch_scc1 .LBB0_39
	v_add_u32_e32 v0, v70, v69
	ds_read_b128 v[72:75], v0 offset:55296
	ds_read_b128 v[76:79], v0 offset:53248
	ds_read_b128 v[80:83], v0 offset:51200
	ds_read_b128 v[84:87], v0 offset:49152
	v_add_u32_e32 v0, v70, v68
	ds_read_b128 v[88:91], v0 offset:38912
	ds_read_b128 v[92:95], v0 offset:36864
	ds_read_b128 v[96:99], v0 offset:34816
	ds_read_b128 v[100:103], v0 offset:32768
	v_add_u32_e32 v0, v67, v69
	ds_read_b128 v[104:107], v0 offset:55296
	ds_read_b128 v[108:111], v0 offset:53248
	ds_read_b128 v[112:115], v0 offset:51200
	ds_read_b128 v[116:119], v0 offset:49152
	v_add_u32_e32 v0, v67, v68
	ds_read_b128 v[66:69], v0 offset:38912
	ds_read_b128 v[126:129], v0 offset:36864
	ds_read_b128 v[130:133], v0 offset:34816
	ds_read_b128 v[134:137], v0 offset:32768
	s_setprio 1
	s_waitcnt lgkmcnt(0)
; DEVI int opaque_tid() { int t = __builtin_amdgcn_workitem_id_x(); asm volatile("" : "+v"(t)); return t; }
;     ...
;     for (int ks = 0; ks < 2; ++ks)
; #pragma unroll
;       for (int m = 0; m < 4; ++m)
; #pragma unroll
;         for (int n = 0; n < NF; ++n) {
;           if (SWAP) acc[m][n] = __builtin_amdgcn_mfma_f32_16x16x32_bf16(bfr[ks][n], af[ks][m], acc[m][n], 0, 0, 0);
;           else acc[m][n] = __builtin_amdgcn_mfma_f32_16x16x32_bf16(af[ks][m], bfr[ks][n], acc[m][n], 0, 0, 0);
;         }
;     __builtin_amdgcn_s_setprio(0);
;     __builtin_amdgcn_sched_group_barrier(0x100, 4 + NF, 0);
; #pragma unroll
;     for (int i = 0; i < 4 + NF; ++i) { __builtin_amdgcn_sched_group_barrier(0x008, 2, 0); __builtin_amdgcn_sched_group_barrier(0x100, 1, 0); }
;     __builtin_amdgcn_sched_group_barrier(0x008, 8 * NF - 2 * (4 + NF), 0);
; DEVI void store_rm_sw(const f32x4 (&acc)[4][4], bf16* dst, long ld, int m0, int n0) {
;   const int tid = opaque_tid(), lane = tid & 63, wid = tid >> 6, wr = wid >> 1, wc = wid & 1, fr = lane & 15, fq = lane >> 4;
;   const int cofs = (fq & 1) * 16 + (fq & 2) * 4;
; #pragma unroll
;   for (int m = 0; m < 4; ++m) {
;     bf16* rp = dst + (long)(m0 + wr * 64 + m * 16 + fr) * ld + n0 + wc * 64 + cofs;
; #pragma unroll
;     for (int n = 0; n < 4; n += 2) {
;       const unsigned x0 = pack2(acc[m][n][0], acc[m][n][1]), x1 = pack2(acc[m][n][2], acc[m][n][3]);
;       const unsigned y0 = pack2(acc[m][n + 1][0], acc[m][n + 1][1]), y1 = pack2(acc[m][n + 1][2], acc[m][n + 1][3]);
;       const u32x2 s0 = __builtin_amdgcn_permlane16_swap(x0, y0, false, false);
;       const u32x2 s1 = __builtin_amdgcn_permlane16_swap(x1, y1, false, false);
;       *(u32x4*)(rp + n * 16) = u32x4{s0[0], s1[0], s0[1], s1[1]};
;     }
;   }
; }
	v_mfma_f32_16x16x32_bf16 v[62:65], v[116:119], v[134:137], v[62:65]
	v_mfma_f32_16x16x32_bf16 v[58:61], v[112:115], v[134:137], v[58:61]
	v_mfma_f32_16x16x32_bf16 v[46:49], v[108:111], v[134:137], v[46:49]
	v_mfma_f32_16x16x32_bf16 v[42:45], v[104:107], v[134:137], v[42:45]
	v_mfma_f32_16x16x32_bf16 v[38:41], v[116:119], v[130:133], v[38:41]
	v_mfma_f32_16x16x32_bf16 v[34:37], v[112:115], v[130:133], v[34:37]
	v_mfma_f32_16x16x32_bf16 v[30:33], v[108:111], v[130:133], v[30:33]
	v_mfma_f32_16x16x32_bf16 v[26:29], v[104:107], v[130:133], v[26:29]
	v_mfma_f32_16x16x32_bf16 v[22:25], v[116:119], v[126:129], v[22:25]
	v_mfma_f32_16x16x32_bf16 v[18:21], v[112:115], v[126:129], v[18:21]
	v_mfma_f32_16x16x32_bf16 v[14:17], v[108:111], v[126:129], v[14:17]
	v_mfma_f32_16x16x32_bf16 v[10:13], v[104:107], v[126:129], v[10:13]
	v_mfma_f32_16x16x32_bf16 v[6:9], v[116:119], v[66:69], v[6:9]
	v_mfma_f32_16x16x32_bf16 v[2:5], v[112:115], v[66:69], v[2:5]
	v_mfma_f32_16x16x32_bf16 v[50:53], v[108:111], v[66:69], v[50:53]
	v_mfma_f32_16x16x32_bf16 v[54:57], v[104:107], v[66:69], v[54:57]
	v_mfma_f32_16x16x32_bf16 v[62:65], v[84:87], v[100:103], v[62:65]
	v_mfma_f32_16x16x32_bf16 v[58:61], v[80:83], v[100:103], v[58:61]
	v_mfma_f32_16x16x32_bf16 v[46:49], v[76:79], v[100:103], v[46:49]
	v_mfma_f32_16x16x32_bf16 v[42:45], v[72:75], v[100:103], v[42:45]
	v_mfma_f32_16x16x32_bf16 v[38:41], v[84:87], v[96:99], v[38:41]
	v_mfma_f32_16x16x32_bf16 v[34:37], v[80:83], v[96:99], v[34:37]
	v_mfma_f32_16x16x32_bf16 v[30:33], v[76:79], v[96:99], v[30:33]
	v_mfma_f32_16x16x32_bf16 v[26:29], v[72:75], v[96:99], v[26:29]
	v_mfma_f32_16x16x32_bf16 v[22:25], v[84:87], v[92:95], v[22:25]
	v_mfma_f32_16x16x32_bf16 v[18:21], v[80:83], v[92:95], v[18:21]
	v_mfma_f32_16x16x32_bf16 v[14:17], v[76:79], v[92:95], v[14:17]
	v_mfma_f32_16x16x32_bf16 v[10:13], v[72:75], v[92:95], v[10:13]
	v_mfma_f32_16x16x32_bf16 v[6:9], v[84:87], v[88:91], v[6:9]
	v_mfma_f32_16x16x32_bf16 v[2:5], v[80:83], v[88:91], v[2:5]
	v_mfma_f32_16x16x32_bf16 v[50:53], v[76:79], v[88:91], v[50:53]
	v_mfma_f32_16x16x32_bf16 v[54:57], v[72:75], v[88:91], v[54:57]
	s_setprio 0
	v_mov_b32_e32 v0, v154
	s_waitcnt vmcnt(0)
	s_barrier
	s_ashr_i32 s37, s36, 31
	v_and_b32_e32 v67, 16, v0
	v_lshrrev_b32_e32 v68, 2, v0
	v_and_b32_e32 v66, 64, v0
	v_and_or_b32 v68, v68, 8, v67
	v_ashrrev_i32_e32 v67, 1, v0
	v_and_or_b32 v0, v0, 15, s6
	s_lshl_b64 s[6:7], s[36:37], 1
	v_and_b32_e32 v67, 0xffffffc0, v67
	s_add_u32 s6, s53, s6
	v_add_u32_e32 v70, v0, v67
	s_addc_u32 s7, s54, s7
	v_lshlrev_b32_e32 v0, 1, v66
	v_lshl_add_u64 v[66:67], s[6:7], 0, v[0:1]
	v_lshlrev_b32_e32 v0, 1, v68
	v_lshl_add_u64 v[66:67], v[66:67], 0, v[0:1]
	v_or_b32_e32 v0, 16, v70
	v_cvt_pk_bf16_f32 v46, v46, v47
	v_cvt_pk_bf16_f32 v47, v48, v49
	v_cvt_pk_bf16_f32 v48, v42, v43
	v_mad_i64_i32 v[42:43], s[6:7], v0, s48, v[66:67]
	v_or_b32_e32 v0, 32, v70
	v_cvt_pk_bf16_f32 v62, v62, v63
	v_cvt_pk_bf16_f32 v63, v64, v65
	v_cvt_pk_bf16_f32 v64, v58, v59
	v_cvt_pk_bf16_f32 v65, v60, v61
	v_cvt_pk_bf16_f32 v49, v44, v45
	v_cvt_pk_bf16_f32 v38, v38, v39
	v_cvt_pk_bf16_f32 v39, v40, v41
	v_cvt_pk_bf16_f32 v40, v34, v35
	v_cvt_pk_bf16_f32 v41, v36, v37
	v_cvt_pk_bf16_f32 v30, v30, v31
	v_cvt_pk_bf16_f32 v31, v32, v33
	v_cvt_pk_bf16_f32 v32, v26, v27
	v_cvt_pk_bf16_f32 v33, v28, v29
	v_mad_i64_i32 v[26:27], s[6:7], v0, s48, v[66:67]
	v_cvt_pk_bf16_f32 v22, v22, v23
	v_cvt_pk_bf16_f32 v23, v24, v25
	v_cvt_pk_bf16_f32 v24, v18, v19
	v_cvt_pk_bf16_f32 v25, v20, v21
	v_cvt_pk_bf16_f32 v14, v14, v15
	v_cvt_pk_bf16_f32 v15, v16, v17
	v_cvt_pk_bf16_f32 v16, v10, v11
	v_cvt_pk_bf16_f32 v17, v12, v13
	v_or_b32_e32 v0, 48, v70
	v_cvt_pk_bf16_f32 v6, v6, v7
	v_cvt_pk_bf16_f32 v7, v8, v9
	v_cvt_pk_bf16_f32 v8, v2, v3
	v_cvt_pk_bf16_f32 v9, v4, v5
	v_cvt_pk_bf16_f32 v2, v50, v51
	v_cvt_pk_bf16_f32 v3, v52, v53
	v_cvt_pk_bf16_f32 v4, v54, v55
	v_cvt_pk_bf16_f32 v5, v56, v57
	v_mad_i64_i32 v[68:69], s[6:7], v70, s48, v[66:67]
	v_permlane16_swap_b32_e32 v62, v64
	v_permlane16_swap_b32_e32 v63, v65
	v_permlane16_swap_b32_e32 v46, v48
	v_permlane16_swap_b32_e32 v47, v49
	v_permlane16_swap_b32_e32 v38, v40
	v_permlane16_swap_b32_e32 v39, v41
	v_permlane16_swap_b32_e32 v30, v32
	v_permlane16_swap_b32_e32 v31, v33
	v_permlane16_swap_b32_e32 v22, v24
	v_permlane16_swap_b32_e32 v23, v25
	v_permlane16_swap_b32_e32 v14, v16
	v_permlane16_swap_b32_e32 v15, v17
	v_mad_i64_i32 v[10:11], s[6:7], v0, s48, v[66:67]
	v_permlane16_swap_b32_e32 v6, v8
	v_permlane16_swap_b32_e32 v7, v9
	v_permlane16_swap_b32_e32 v2, v4
	v_permlane16_swap_b32_e32 v3, v5
	flat_store_dwordx4 v[68:69], v[62:65]
	flat_store_dwordx4 v[68:69], v[46:49] offset:64
	flat_store_dwordx4 v[42:43], v[38:41]
	flat_store_dwordx4 v[42:43], v[30:33] offset:64
	flat_store_dwordx4 v[26:27], v[22:25]
	flat_store_dwordx4 v[26:27], v[14:17] offset:64
	flat_store_dwordx4 v[10:11], v[6:9]
	flat_store_dwordx4 v[10:11], v[2:5] offset:64
	s_mov_b64 s[36:37], 0
; DEVI int opaque_tid() { int t = __builtin_amdgcn_workitem_id_x(); asm volatile("" : "+v"(t)); return t; }
;   const int tid = opaque_tid(), lane = tid & 63, wid = tid >> 6, wr = wid >> 1, wc = wid & 1, fr = lane & 15, fq = lane >> 4;
;   const int lrow = tid >> 3, lpos = tid & 7;
;   const int gch = (lpos ^ (lrow & 7)) * 8;
;   unsigned aoff[4], boff[NF];
; #pragma unroll
;   for (int i = 0; i < 4; ++i) aoff[i] = (unsigned)(arow(m0 + lrow + 32 * i) + gch);
; #pragma unroll
;   for (int i = 0; i < NF; ++i) boff[i] = (unsigned)((n0 + lrow + 32 * i) * ldb + gch);
;   const int nk = K >> 6;
;   if (!PRE) __syncthreads();
;     ...
;   if (!PRE) GL_ISSUE(0, 0)
;   asm volatile("s_waitcnt vmcnt(0)" ::: "memory");
;   __syncthreads();
.LBB0_41:
	s_and_b64 vcc, exec, s[36:37]
	s_cbranch_vccz .LBB0_22
	v_mov_b32_e32 v18, v154
	s_lshl_b32 s94, s50, 7
	v_ashrrev_i32_e32 v20, 3, v18
	v_xor_b32_e32 v0, v20, v18
	v_lshlrev_b32_e32 v0, 3, v0
	v_and_b32_e32 v21, 56, v0
	v_add_u32_e32 v0, s94, v20
	s_lshl_b32 s80, s93, 7
	v_lshl_or_b32 v0, v0, 10, v21
	v_lshlrev_b32_e32 v66, 4, v18
	v_add_u32_e32 v2, 0x8000, v0
	v_add_u32_e32 v4, 0x10000, v0
	v_add_u32_e32 v6, 0x18000, v0
	v_add_u32_e32 v3, s80, v20
	v_lshl_add_u64 v[16:17], v[0:1], 1, s[8:9]
	v_readfirstlane_b32 s6, v66
	v_add_u32_e32 v0, 0x1000, v66
	v_lshl_or_b32 v8, v3, 10, v21
	s_mov_b32 m0, s6
	v_mov_b32_e32 v3, v1
	v_readfirstlane_b32 s6, v0
	v_add_u32_e32 v0, 0x2000, v66
	s_waitcnt lgkmcnt(0)
	s_barrier
	global_load_lds_dwordx4 v[16:17], off
	v_lshl_add_u64 v[2:3], v[2:3], 1, s[8:9]
	s_mov_b32 m0, s6
	v_mov_b32_e32 v5, v1
	v_readfirstlane_b32 s6, v0
	v_add_u32_e32 v0, 0x3000, v66
	global_load_lds_dwordx4 v[2:3], off
	v_lshl_add_u64 v[2:3], v[4:5], 1, s[8:9]
	s_mov_b32 m0, s6
	v_mov_b32_e32 v7, v1
	v_readfirstlane_b32 s6, v0
	v_add_u32_e32 v0, 0x4000, v66
	global_load_lds_dwordx4 v[2:3], off
	v_lshl_add_u64 v[2:3], v[6:7], 1, s[8:9]
	s_mov_b32 m0, s6
	v_mov_b32_e32 v9, v1
	v_readfirstlane_b32 s6, v0
	v_add_u32_e32 v0, 0x5000, v66
	v_add_u32_e32 v10, 0x8000, v8
	global_load_lds_dwordx4 v[2:3], off
	v_lshl_add_u64 v[2:3], v[8:9], 1, s[18:19]
	s_mov_b32 m0, s6
	v_mov_b32_e32 v11, v1
	v_readfirstlane_b32 s6, v0
	v_add_u32_e32 v0, 0x6000, v66
	v_add_u32_e32 v12, 0x10000, v8
	global_load_lds_dwordx4 v[2:3], off
	v_lshl_add_u64 v[2:3], v[10:11], 1, s[18:19]
	s_mov_b32 m0, s6
	v_mov_b32_e32 v13, v1
	v_readfirstlane_b32 s6, v0
	v_add_u32_e32 v0, 0x7000, v66
	v_add_u32_e32 v14, 0x18000, v8
	global_load_lds_dwordx4 v[2:3], off
	v_lshl_add_u64 v[2:3], v[12:13], 1, s[18:19]
	s_mov_b32 m0, s6
	v_mov_b32_e32 v15, v1
	v_readfirstlane_b32 s6, v0
	global_load_lds_dwordx4 v[2:3], off
	v_lshl_add_u64 v[2:3], v[14:15], 1, s[18:19]
	s_mov_b32 m0, s6
	v_bfe_u32 v0, v18, 4, 2
	global_load_lds_dwordx4 v[2:3], off
	v_and_b32_e32 v2, 7, v18
	v_bitop3_b32 v0, v0, v2, 4 bitop3:0x36
	v_lshlrev_b32_e32 v70, 4, v0
	v_lshlrev_b32_e32 v0, 10, v20
	s_lshl_b32 s6, s40, 10
	s_lshl_b32 s7, s41, 7
	v_lshrrev_b32_e32 v19, 4, v18
	v_and_b32_e32 v22, 15, v18
	s_waitcnt vmcnt(0)
	v_lshrrev_b32_e32 v3, 1, v18
	v_lshlrev_b32_e32 v4, 7, v18
	v_lshl_add_u32 v0, s93, 17, v0
	s_or_b32 s6, s7, s6
	v_and_or_b32 v3, v3, s79, v22
	v_and_b32_e32 v69, 0x2780, v4
	v_bitop3_b32 v4, v19, v2, 3 bitop3:0x6c
	v_or_b32_e32 v71, v0, v21
	v_add_u32_e32 v0, s6, v20
	v_mov_b32_e32 v2, 0
	v_lshlrev_b32_e32 v67, 4, v4
	v_lshlrev_b32_e32 v68, 7, v3
	v_lshl_or_b32 v72, v0, 10, v21
	s_mov_b32 s6, 0
	s_mov_b32 s7, 0
	v_mov_b32_e32 v3, v2
	v_mov_b32_e32 v4, v2
	v_mov_b32_e32 v5, v2
	v_mov_b32_e32 v6, v2
	v_mov_b32_e32 v7, v2
	v_mov_b32_e32 v8, v2
	v_mov_b32_e32 v9, v2
	v_mov_b32_e32 v10, v2
	v_mov_b32_e32 v11, v2
	v_mov_b32_e32 v12, v2
	v_mov_b32_e32 v13, v2
	v_mov_b32_e32 v14, v2
	v_mov_b32_e32 v15, v2
	v_mov_b32_e32 v16, v2
	v_mov_b32_e32 v17, v2
	v_mov_b32_e32 v18, v2
	v_mov_b32_e32 v19, v2
	v_mov_b32_e32 v20, v2
	v_mov_b32_e32 v21, v2
	v_mov_b32_e32 v22, v2
	v_mov_b32_e32 v23, v2
	v_mov_b32_e32 v24, v2
	v_mov_b32_e32 v25, v2
	v_mov_b32_e32 v26, v2
	v_mov_b32_e32 v27, v2
	v_mov_b32_e32 v28, v2
	v_mov_b32_e32 v29, v2
	v_mov_b32_e32 v30, v2
	v_mov_b32_e32 v31, v2
	v_mov_b32_e32 v32, v2
	v_mov_b32_e32 v33, v2
	v_mov_b32_e32 v34, v2
	v_mov_b32_e32 v35, v2
	v_mov_b32_e32 v36, v2
	v_mov_b32_e32 v37, v2
	v_mov_b32_e32 v38, v2
	v_mov_b32_e32 v39, v2
	v_mov_b32_e32 v40, v2
	v_mov_b32_e32 v41, v2
	v_mov_b32_e32 v42, v2
	v_mov_b32_e32 v43, v2
	v_mov_b32_e32 v44, v2
	v_mov_b32_e32 v45, v2
	v_mov_b32_e32 v46, v2
	v_mov_b32_e32 v47, v2
	v_mov_b32_e32 v48, v2
	v_mov_b32_e32 v49, v2
	v_mov_b32_e32 v58, v2
	v_mov_b32_e32 v59, v2
	v_mov_b32_e32 v60, v2
	v_mov_b32_e32 v61, v2
	v_mov_b32_e32 v62, v2
	v_mov_b32_e32 v63, v2
	v_mov_b32_e32 v64, v2
	v_mov_b32_e32 v65, v2
	v_mov_b32_e32 v50, v2
	v_mov_b32_e32 v51, v2
	v_mov_b32_e32 v52, v2
	v_mov_b32_e32 v53, v2
	v_mov_b32_e32 v54, v2
	v_mov_b32_e32 v55, v2
	v_mov_b32_e32 v56, v2
	v_mov_b32_e32 v57, v2
	v_lshlrev_b32_e32 v232, 1, v72
	v_add_u32_e32 v233, 0x10000, v232
	v_add_u32_e32 v234, 0x20000, v232
	v_add_u32_e32 v235, 0x30000, v232
	v_lshlrev_b32_e32 v236, 1, v71
	v_add_u32_e32 v237, 0x10000, v236
	v_add_u32_e32 v238, 0x20000, v236
	v_add_u32_e32 v239, 0x30000, v236
	v_readfirstlane_b32 s68, v66
	s_add_u32 s64, s8, 0x80
	s_addc_u32 s65, s9, 0
	s_add_u32 s66, s18, 0x80
	s_addc_u32 s67, s19, 0
	s_waitcnt vmcnt(0) lgkmcnt(0)
	s_barrier
;     ...
;   for (int kt = 0; kt < nk; ++kt) {
;     if (kt + 1 < nk) GL_ISSUE(kt + 1, (kt + 1) & 1)
;     const char* As = smem + (kt & 1) * 32768;
;     const char* Bs = As + 16384;
;     if (DEEP) {
;     bf16x8 af[2][4], bfr[2][NF];
; #pragma unroll
;     for (int ks = 0; ks < 2; ++ks) {
;       const int co = ((ks * 4 + fq) ^ swz) * 16;
; #pragma unroll
;       for (int m = 0; m < 4; ++m) af[ks][m] = *(const bf16x8*)(As + (wr * 64 + m * 16 + fr) * 128 + co);
; #pragma unroll
;       for (int n = 0; n < NF; ++n) bfr[ks][n] = *(const bf16x8*)(Bs + (wc * 16 * NF + n * 16 + fr) * 128 + co);
;     }
;     __builtin_amdgcn_s_setprio(1);
; #pragma unroll
;     for (int ks = 0; ks < 2; ++ks)
; #pragma unroll
;       for (int m = 0; m < 4; ++m)
; #pragma unroll
;         for (int n = 0; n < NF; ++n) {
;           if (SWAP) acc[m][n] = __builtin_amdgcn_mfma_f32_16x16x32_bf16(bfr[ks][n], af[ks][m], acc[m][n], 0, 0, 0);
;           else acc[m][n] = __builtin_amdgcn_mfma_f32_16x16x32_bf16(af[ks][m], bfr[ks][n], acc[m][n], 0, 0, 0);
;         }
;     __builtin_amdgcn_s_setprio(0);
;     __builtin_amdgcn_sched_group_barrier(0x100, 4 + NF, 0);
; #pragma unroll
;     for (int i = 0; i < 4 + NF; ++i) { __builtin_amdgcn_sched_group_barrier(0x008, 2, 0); __builtin_amdgcn_sched_group_barrier(0x100, 1, 0); }
;     __builtin_amdgcn_sched_group_barrier(0x008, 8 * NF - 2 * (4 + NF), 0);
.LBB0_43:
	s_and_b32 s7, s7, 0x8000
	v_or_b32_e32 v0, s7, v67
	v_add_u32_e32 v73, v0, v68
	v_add_u32_e32 v0, v0, v69
	ds_read_b128 v[90:93], v0 offset:16384
	ds_read_b128 v[94:97], v0 offset:18432
	ds_read_b128 v[98:101], v0 offset:20480
	ds_read_b128 v[102:105], v0 offset:22528
	v_or_b32_e32 v0, s7, v70
	ds_read_b128 v[74:77], v73
	ds_read_b128 v[78:81], v73 offset:2048
	ds_read_b128 v[82:85], v73 offset:4096
	ds_read_b128 v[86:89], v73 offset:6144
	s_add_i32 s36, s7, 0x8000
	s_and_b32 s69, s36, 0x8000
	s_add_i32 s69, s69, s68
	v_add_u32_e32 v73, v0, v68
	v_add_u32_e32 v0, v0, v69
	s_mov_b32 m0, s69
	s_nop 0
	global_load_lds_dwordx4 v232, s[64:65]
	ds_read_b128 v[106:109], v73
	s_add_i32 m0, s69, 0x1000
	s_nop 0
	global_load_lds_dwordx4 v233, s[64:65]
	ds_read_b128 v[110:113], v73 offset:2048
	s_add_i32 m0, s69, 0x2000
	s_nop 0
	global_load_lds_dwordx4 v234, s[64:65]
	ds_read_b128 v[114:117], v73 offset:4096
	s_add_i32 m0, s69, 0x3000
	s_nop 0
	global_load_lds_dwordx4 v235, s[64:65]
	ds_read_b128 v[118:121], v73 offset:6144
	s_add_i32 m0, s69, 0x4000
	s_nop 0
	global_load_lds_dwordx4 v236, s[66:67]
	ds_read_b128 v[126:129], v0 offset:16384
	s_add_i32 m0, s69, 0x5000
	s_nop 0
	global_load_lds_dwordx4 v237, s[66:67]
	ds_read_b128 v[130:133], v0 offset:18432
	s_add_i32 m0, s69, 0x6000
	s_nop 0
	global_load_lds_dwordx4 v238, s[66:67]
	ds_read_b128 v[134:137], v0 offset:20480
	s_add_i32 m0, s69, 0x7000
	s_nop 0
	global_load_lds_dwordx4 v239, s[66:67]
	ds_read_b128 v[138:141], v0 offset:22528
	s_add_u32 s64, s64, 0x80
	s_addc_u32 s65, s65, 0
	s_add_u32 s66, s66, 0x80
	s_addc_u32 s67, s67, 0
	s_setprio 1
	s_waitcnt lgkmcnt(11)
	v_mfma_f32_16x16x32_bf16 v[62:65], v[74:77], v[90:93], v[62:65]
	v_mfma_f32_16x16x32_bf16 v[58:61], v[74:77], v[94:97], v[58:61]
	v_mfma_f32_16x16x32_bf16 v[46:49], v[74:77], v[98:101], v[46:49]
	v_mfma_f32_16x16x32_bf16 v[42:45], v[74:77], v[102:105], v[42:45]
	s_waitcnt lgkmcnt(10)
	v_mfma_f32_16x16x32_bf16 v[38:41], v[78:81], v[90:93], v[38:41]
	v_mfma_f32_16x16x32_bf16 v[34:37], v[78:81], v[94:97], v[34:37]
	v_mfma_f32_16x16x32_bf16 v[30:33], v[78:81], v[98:101], v[30:33]
	v_mfma_f32_16x16x32_bf16 v[26:29], v[78:81], v[102:105], v[26:29]
	s_waitcnt lgkmcnt(9)
	v_mfma_f32_16x16x32_bf16 v[22:25], v[82:85], v[90:93], v[22:25]
	v_mfma_f32_16x16x32_bf16 v[18:21], v[82:85], v[94:97], v[18:21]
	v_mfma_f32_16x16x32_bf16 v[14:17], v[82:85], v[98:101], v[14:17]
	v_mfma_f32_16x16x32_bf16 v[10:13], v[82:85], v[102:105], v[10:13]
	s_waitcnt lgkmcnt(8)
	v_mfma_f32_16x16x32_bf16 v[6:9], v[86:89], v[90:93], v[6:9]
	v_mfma_f32_16x16x32_bf16 v[2:5], v[86:89], v[94:97], v[2:5]
	v_mfma_f32_16x16x32_bf16 v[50:53], v[86:89], v[98:101], v[50:53]
	v_mfma_f32_16x16x32_bf16 v[54:57], v[86:89], v[102:105], v[54:57]
	s_waitcnt lgkmcnt(3)
	v_mfma_f32_16x16x32_bf16 v[62:65], v[106:109], v[126:129], v[62:65]
	s_waitcnt lgkmcnt(2)
	v_mfma_f32_16x16x32_bf16 v[58:61], v[106:109], v[130:133], v[58:61]
	s_waitcnt lgkmcnt(1)
	v_mfma_f32_16x16x32_bf16 v[46:49], v[106:109], v[134:137], v[46:49]
	s_waitcnt lgkmcnt(0)
	v_mfma_f32_16x16x32_bf16 v[42:45], v[106:109], v[138:141], v[42:45]
	v_mfma_f32_16x16x32_bf16 v[38:41], v[110:113], v[126:129], v[38:41]
	v_mfma_f32_16x16x32_bf16 v[34:37], v[110:113], v[130:133], v[34:37]
	v_mfma_f32_16x16x32_bf16 v[30:33], v[110:113], v[134:137], v[30:33]
	v_mfma_f32_16x16x32_bf16 v[26:29], v[110:113], v[138:141], v[26:29]
	v_mfma_f32_16x16x32_bf16 v[22:25], v[114:117], v[126:129], v[22:25]
	v_mfma_f32_16x16x32_bf16 v[18:21], v[114:117], v[130:133], v[18:21]
	v_mfma_f32_16x16x32_bf16 v[14:17], v[114:117], v[134:137], v[14:17]
	v_mfma_f32_16x16x32_bf16 v[10:13], v[114:117], v[138:141], v[10:13]
	v_mfma_f32_16x16x32_bf16 v[6:9], v[118:121], v[126:129], v[6:9]
	v_mfma_f32_16x16x32_bf16 v[2:5], v[118:121], v[130:133], v[2:5]
	v_mfma_f32_16x16x32_bf16 v[50:53], v[118:121], v[134:137], v[50:53]
	v_mfma_f32_16x16x32_bf16 v[54:57], v[118:121], v[138:141], v[54:57]
	s_setprio 0
	s_waitcnt vmcnt(0)
	s_add_i32 s6, s6, 64
	s_cmpk_lg_i32 s6, 0x3c0
	s_mov_b32 s7, s36
	s_waitcnt vmcnt(0)
	s_barrier
	s_cbranch_scc1 .LBB0_43
	v_add_u32_e32 v0, v70, v69
	ds_read_b128 v[72:75], v0 offset:55296
	ds_read_b128 v[76:79], v0 offset:53248
	ds_read_b128 v[80:83], v0 offset:51200
	ds_read_b128 v[84:87], v0 offset:49152
	v_add_u32_e32 v0, v70, v68
	ds_read_b128 v[88:91], v0 offset:38912
	ds_read_b128 v[92:95], v0 offset:36864
	ds_read_b128 v[96:99], v0 offset:34816
	ds_read_b128 v[100:103], v0 offset:32768
	v_add_u32_e32 v0, v67, v69
	ds_read_b128 v[104:107], v0 offset:55296
	ds_read_b128 v[108:111], v0 offset:53248
	ds_read_b128 v[112:115], v0 offset:51200
	ds_read_b128 v[116:119], v0 offset:49152
	v_add_u32_e32 v0, v67, v68
	ds_read_b128 v[66:69], v0 offset:38912
	ds_read_b128 v[126:129], v0 offset:36864
	ds_read_b128 v[130:133], v0 offset:34816
	ds_read_b128 v[134:137], v0 offset:32768
	s_setprio 1
	s_waitcnt lgkmcnt(0)
; DEVI int opaque_tid() { int t = __builtin_amdgcn_workitem_id_x(); asm volatile("" : "+v"(t)); return t; }
; DEVI char* opaque_ptr(char* p) { asm volatile("" : "+s"(p)); return p; }
;     ...
;     for (int ks = 0; ks < 2; ++ks)
; #pragma unroll
;       for (int m = 0; m < 4; ++m)
; #pragma unroll
;         for (int n = 0; n < NF; ++n) {
;           if (SWAP) acc[m][n] = __builtin_amdgcn_mfma_f32_16x16x32_bf16(bfr[ks][n], af[ks][m], acc[m][n], 0, 0, 0);
;           else acc[m][n] = __builtin_amdgcn_mfma_f32_16x16x32_bf16(af[ks][m], bfr[ks][n], acc[m][n], 0, 0, 0);
;         }
; DEVI void epi_proj(const Params& p, int L, f32x4 (&acc)[4][4], int m0, int nt) {
;   char* ws = opaque_ptr(p.ws);
;   const int tid = opaque_tid(), lane = tid & 63, wid = tid >> 6, wr = wid >> 1, wc = wid & 1, fr = lane & 15, fq = lane >> 4;
;   const int mbase = m0 + wr * 64;
;   if (nt == 7 || nt == 9 || nt == 18 || nt == 19) {
;     const int b = mbase >> 12, t0 = mbase & 4095;
;     bf16* dstp;
;     if (nt == 7) dstp = (bf16*)(ws + OFF_VST) + (long)(b * 2 + wc) * 64 * 4096;
;     else if (nt == 9) dstp = (bf16*)(ws + OFF_VWT) + (long)(b * 2 + wc) * 64 * 4096;
;     else dstp = (bf16*)(ws + OFF_VFT) + (long)(b * 4 + (nt - 18) * 2 + wc) * 64 * 4096;
;     store_tr_wave(acc, dstp, 4096, t0);
;   } else if (nt == 20) {
;     if (wc == 0) {
;       float* mb = (float*)(ws + OFF_XQ);
; #pragma unroll
;       for (int m = 0; m < 4; ++m)
; #pragma unroll
;         for (int j = 0; j < 4; ++j) {
;           float* rp = mb + (long)(mbase + m * 16 + fq * 4 + j) * 64 + fr;
; #pragma unroll
;           for (int n = 0; n < 4; ++n) rp[n * 16] = acc[m][n][j];
	v_mfma_f32_16x16x32_bf16 v[62:65], v[134:137], v[116:119], v[62:65]
	v_mfma_f32_16x16x32_bf16 v[58:61], v[134:137], v[112:115], v[58:61]
	v_mfma_f32_16x16x32_bf16 v[46:49], v[134:137], v[108:111], v[46:49]
	v_mfma_f32_16x16x32_bf16 v[42:45], v[134:137], v[104:107], v[42:45]
	v_mfma_f32_16x16x32_bf16 v[38:41], v[130:133], v[116:119], v[38:41]
	v_mfma_f32_16x16x32_bf16 v[34:37], v[130:133], v[112:115], v[34:37]
	v_mfma_f32_16x16x32_bf16 v[30:33], v[130:133], v[108:111], v[30:33]
	v_mfma_f32_16x16x32_bf16 v[26:29], v[130:133], v[104:107], v[26:29]
	v_mfma_f32_16x16x32_bf16 v[22:25], v[126:129], v[116:119], v[22:25]
	v_mfma_f32_16x16x32_bf16 v[18:21], v[126:129], v[112:115], v[18:21]
	v_mfma_f32_16x16x32_bf16 v[14:17], v[126:129], v[108:111], v[14:17]
	v_mfma_f32_16x16x32_bf16 v[10:13], v[126:129], v[104:107], v[10:13]
	v_mfma_f32_16x16x32_bf16 v[6:9], v[66:69], v[116:119], v[6:9]
	v_mfma_f32_16x16x32_bf16 v[2:5], v[66:69], v[112:115], v[2:5]
	v_mfma_f32_16x16x32_bf16 v[108:111], v[66:69], v[108:111], v[50:53]
	v_mfma_f32_16x16x32_bf16 v[66:69], v[66:69], v[104:107], v[54:57]
	v_mfma_f32_16x16x32_bf16 v[62:65], v[100:103], v[84:87], v[62:65]
	v_mfma_f32_16x16x32_bf16 v[58:61], v[100:103], v[80:83], v[58:61]
	v_mfma_f32_16x16x32_bf16 v[54:57], v[100:103], v[76:79], v[46:49]
	v_mfma_f32_16x16x32_bf16 v[50:53], v[100:103], v[72:75], v[42:45]
	v_mfma_f32_16x16x32_bf16 v[46:49], v[96:99], v[84:87], v[38:41]
	v_mfma_f32_16x16x32_bf16 v[42:45], v[96:99], v[80:83], v[34:37]
	v_mfma_f32_16x16x32_bf16 v[38:41], v[96:99], v[76:79], v[30:33]
	v_mfma_f32_16x16x32_bf16 v[34:37], v[96:99], v[72:75], v[26:29]
	v_mfma_f32_16x16x32_bf16 v[30:33], v[92:95], v[84:87], v[22:25]
	v_mfma_f32_16x16x32_bf16 v[26:29], v[92:95], v[80:83], v[18:21]
	v_mfma_f32_16x16x32_bf16 v[22:25], v[92:95], v[76:79], v[14:17]
	v_mfma_f32_16x16x32_bf16 v[18:21], v[92:95], v[72:75], v[10:13]
	v_mfma_f32_16x16x32_bf16 v[14:17], v[88:91], v[84:87], v[6:9]
	v_mfma_f32_16x16x32_bf16 v[10:13], v[88:91], v[80:83], v[2:5]
	v_mfma_f32_16x16x32_bf16 v[6:9], v[88:91], v[76:79], v[108:111]
	v_mfma_f32_16x16x32_bf16 v[2:5], v[88:91], v[72:75], v[66:69]
	s_setprio 0
	s_mov_b64 s[36:37], s[90:91]
	s_nop 0
	v_mov_b32_e32 v68, v154
	s_waitcnt vmcnt(0)
	s_barrier
	s_cmp_lt_i32 s93, 18
	v_ashrrev_i32_e32 v0, 1, v68
	v_and_b32_e32 v0, 0xffffffc0, v0
	v_bfe_u32 v101, v68, 6, 1
	v_add_u32_e32 v100, s94, v0
	s_cbranch_scc1 .LBB0_51
	s_mov_b64 s[38:39], 0
	s_mov_b64 s[40:41], -1
	s_cmp_gt_i32 s93, 19
	s_mov_b64 s[50:51], 0
	s_cbranch_scc0 .LBB0_52
	s_cmp_eq_u32 s93, 20
	s_mov_b64 s[50:51], -1
	s_cbranch_scc0 .LBB0_70
	v_cmp_eq_u32_e32 vcc, 0, v101
	s_and_saveexec_b64 s[40:41], vcc
	s_cbranch_execz .LBB0_50
	v_and_b32_e32 v69, 15, v68
	v_lshrrev_b32_e32 v0, 2, v68
	v_and_or_b32 v98, v0, 12, v100
	v_lshlrev_b32_e32 v0, 2, v69
	v_lshl_add_u64 v[66:67], s[36:37], 0, v[0:1]
	s_mov_b64 s[6:7], 0x1b6bc000
	v_ashrrev_i32_e32 v99, 31, v98
	v_lshl_add_u64 v[102:103], v[66:67], 0, s[6:7]
	v_lshlrev_b64 v[66:67], 8, v[98:99]
	v_or_b32_e32 v96, 1, v98
	v_lshl_add_u64 v[66:67], v[102:103], 0, v[66:67]
	v_ashrrev_i32_e32 v97, 31, v96
	flat_store_dword v[66:67], v62
	flat_store_dword v[66:67], v58 offset:64
	flat_store_dword v[66:67], v54 offset:128
	flat_store_dword v[66:67], v50 offset:192
	v_lshlrev_b64 v[66:67], 8, v[96:97]
	v_or_b32_e32 v94, 2, v98
	v_lshl_add_u64 v[66:67], v[102:103], 0, v[66:67]
	v_ashrrev_i32_e32 v95, 31, v94
	flat_store_dword v[66:67], v63
	flat_store_dword v[66:67], v59 offset:64
	flat_store_dword v[66:67], v55 offset:128
	flat_store_dword v[66:67], v51 offset:192
	v_lshlrev_b64 v[66:67], 8, v[94:95]
	v_or_b32_e32 v92, 3, v98
	v_lshl_add_u64 v[66:67], v[102:103], 0, v[66:67]
	v_ashrrev_i32_e32 v93, 31, v92
	flat_store_dword v[66:67], v64
	flat_store_dword v[66:67], v60 offset:64
	flat_store_dword v[66:67], v56 offset:128
	flat_store_dword v[66:67], v52 offset:192
	v_lshlrev_b64 v[66:67], 8, v[92:93]
	v_or_b32_e32 v90, 16, v98
	v_lshl_add_u64 v[66:67], v[102:103], 0, v[66:67]
	v_ashrrev_i32_e32 v91, 31, v90
	flat_store_dword v[66:67], v65
	flat_store_dword v[66:67], v61 offset:64
	flat_store_dword v[66:67], v57 offset:128
	flat_store_dword v[66:67], v53 offset:192
	v_lshlrev_b64 v[66:67], 8, v[90:91]
	v_or_b32_e32 v88, 17, v98
	v_lshl_add_u64 v[66:67], v[102:103], 0, v[66:67]
	v_ashrrev_i32_e32 v89, 31, v88
	flat_store_dword v[66:67], v46
	flat_store_dword v[66:67], v42 offset:64
	flat_store_dword v[66:67], v38 offset:128
	flat_store_dword v[66:67], v34 offset:192
	v_lshlrev_b64 v[66:67], 8, v[88:89]
	v_or_b32_e32 v86, 18, v98
	v_lshl_add_u64 v[66:67], v[102:103], 0, v[66:67]
	v_ashrrev_i32_e32 v87, 31, v86
	flat_store_dword v[66:67], v47
	flat_store_dword v[66:67], v43 offset:64
	flat_store_dword v[66:67], v39 offset:128
	flat_store_dword v[66:67], v35 offset:192
	v_lshlrev_b64 v[66:67], 8, v[86:87]
	v_or_b32_e32 v84, 19, v98
	v_lshl_add_u64 v[66:67], v[102:103], 0, v[66:67]
	v_ashrrev_i32_e32 v85, 31, v84
	flat_store_dword v[66:67], v48
	flat_store_dword v[66:67], v44 offset:64
	flat_store_dword v[66:67], v40 offset:128
	flat_store_dword v[66:67], v36 offset:192
	v_lshlrev_b64 v[66:67], 8, v[84:85]
	v_or_b32_e32 v82, 32, v98
	v_lshl_add_u64 v[66:67], v[102:103], 0, v[66:67]
	v_ashrrev_i32_e32 v83, 31, v82
	flat_store_dword v[66:67], v49
	flat_store_dword v[66:67], v45 offset:64
	flat_store_dword v[66:67], v41 offset:128
	flat_store_dword v[66:67], v37 offset:192
	v_lshlrev_b64 v[66:67], 8, v[82:83]
	v_or_b32_e32 v80, 33, v98
	v_lshl_add_u64 v[66:67], v[102:103], 0, v[66:67]
	v_ashrrev_i32_e32 v81, 31, v80
	flat_store_dword v[66:67], v30
	flat_store_dword v[66:67], v26 offset:64
; DEVI void epi_proj(const Params& p, int L, f32x4 (&acc)[4][4], int m0, int nt) {
;     ...
;           float* rp = mb + (long)(mbase + m * 16 + fq * 4 + j) * 64 + fr;
; #pragma unroll
;           for (int n = 0; n < 4; ++n) rp[n * 16] = acc[m][n][j];
;         }
;       if (fr >= 8 && fr < 12) {
;         float* flog = (float*)(ws + OFF_FLOG);
;         const float bfh = p.in[11][L * 4 + (fr - 8)];
; #pragma unroll
;         for (int m = 0; m < 4; ++m)
; #pragma unroll
;           for (int j = 0; j < 4; ++j) {
;             const float x = acc[m][3][j] + bfh;
;             flog[(long)(mbase + m * 16 + fq * 4 + j) * 4 + (fr - 8)] = fminf(x, 0.f) - log1pf(__expf(-fabsf(x)));
	flat_store_dword v[66:67], v22 offset:128
	flat_store_dword v[66:67], v18 offset:192
	v_lshlrev_b64 v[66:67], 8, v[80:81]
	v_or_b32_e32 v78, 34, v98
	v_lshl_add_u64 v[66:67], v[102:103], 0, v[66:67]
	v_ashrrev_i32_e32 v79, 31, v78
	flat_store_dword v[66:67], v31
	flat_store_dword v[66:67], v27 offset:64
	flat_store_dword v[66:67], v23 offset:128
	flat_store_dword v[66:67], v19 offset:192
	v_lshlrev_b64 v[66:67], 8, v[78:79]
	v_or_b32_e32 v76, 35, v98
	v_lshl_add_u64 v[66:67], v[102:103], 0, v[66:67]
	v_ashrrev_i32_e32 v77, 31, v76
	flat_store_dword v[66:67], v32
	flat_store_dword v[66:67], v28 offset:64
	flat_store_dword v[66:67], v24 offset:128
	flat_store_dword v[66:67], v20 offset:192
	v_lshlrev_b64 v[66:67], 8, v[76:77]
	v_or_b32_e32 v74, 48, v98
	v_lshl_add_u64 v[66:67], v[102:103], 0, v[66:67]
	v_ashrrev_i32_e32 v75, 31, v74
	flat_store_dword v[66:67], v33
	flat_store_dword v[66:67], v29 offset:64
	flat_store_dword v[66:67], v25 offset:128
	flat_store_dword v[66:67], v21 offset:192
	v_lshlrev_b64 v[66:67], 8, v[74:75]
	v_or_b32_e32 v72, 49, v98
	v_lshl_add_u64 v[66:67], v[102:103], 0, v[66:67]
	v_ashrrev_i32_e32 v73, 31, v72
	flat_store_dword v[66:67], v14
	flat_store_dword v[66:67], v10 offset:64
	flat_store_dword v[66:67], v6 offset:128
	flat_store_dword v[66:67], v2 offset:192
	v_lshlrev_b64 v[66:67], 8, v[72:73]
	v_or_b32_e32 v70, 50, v98
	v_lshl_add_u64 v[66:67], v[102:103], 0, v[66:67]
	v_ashrrev_i32_e32 v71, 31, v70
	flat_store_dword v[66:67], v15
	flat_store_dword v[66:67], v11 offset:64
	flat_store_dword v[66:67], v7 offset:128
	flat_store_dword v[66:67], v3 offset:192
	v_lshlrev_b64 v[66:67], 8, v[70:71]
	v_lshl_add_u64 v[66:67], v[102:103], 0, v[66:67]
	flat_store_dword v[66:67], v16
	flat_store_dword v[66:67], v12 offset:64
	flat_store_dword v[66:67], v8 offset:128
	flat_store_dword v[66:67], v4 offset:192
	v_or_b32_e32 v66, 51, v98
	v_ashrrev_i32_e32 v67, 31, v66
	v_lshlrev_b64 v[104:105], 8, v[66:67]
	v_and_b32_e32 v0, 12, v68
	v_lshl_add_u64 v[102:103], v[102:103], 0, v[104:105]
	v_cmp_eq_u32_e32 vcc, 8, v0
	flat_store_dword v[102:103], v17
	flat_store_dword v[102:103], v13 offset:64
	flat_store_dword v[102:103], v9 offset:128
	flat_store_dword v[102:103], v5 offset:192
	s_and_b64 exec, exec, vcc
	s_cbranch_execz .LBB0_50
	v_add_u32_e32 v68, -8, v69
	s_mov_b32 s6, s62
	v_readlane_b32 s60, v251, 0
	v_or_b32_e32 v0, s42, v68
	v_readlane_b32 s66, v251, 6
	v_readlane_b32 s67, v251, 7
	v_readlane_b32 s62, v251, 2
	v_mov_b32_e32 v69, v1
	v_lshl_add_u64 v[102:103], v[0:1], 2, s[66:67]
	global_load_dword v0, v[102:103], off
	s_mov_b32 s62, s6
	v_lshl_add_u64 v[68:69], v[68:69], 2, s[36:37]
	s_mov_b64 s[6:7], 0x1b3bc000
	v_lshl_add_u64 v[68:69], v[68:69], 0, s[6:7]
	s_mov_b32 s6, 0xbfb8aa3b
	s_mov_b32 s7, 0x3f2aaaab
	s_mov_b32 s10, 0x3f317218
	s_mov_b32 s11, 0x7f800000
	s_mov_b32 s50, 0x33800000
	v_lshl_add_u64 v[98:99], v[98:99], 4, v[68:69]
	v_lshl_add_u64 v[96:97], v[96:97], 4, v[68:69]
	v_lshl_add_u64 v[94:95], v[94:95], 4, v[68:69]
	v_lshl_add_u64 v[92:93], v[92:93], 4, v[68:69]
	v_lshl_add_u64 v[90:91], v[90:91], 4, v[68:69]
	v_lshl_add_u64 v[88:89], v[88:89], 4, v[68:69]
	v_lshl_add_u64 v[86:87], v[86:87], 4, v[68:69]
	v_lshl_add_u64 v[84:85], v[84:85], 4, v[68:69]
	v_lshl_add_u64 v[82:83], v[82:83], 4, v[68:69]
	v_lshl_add_u64 v[80:81], v[80:81], 4, v[68:69]
	v_lshl_add_u64 v[78:79], v[78:79], 4, v[68:69]
	v_lshl_add_u64 v[76:77], v[76:77], 4, v[68:69]
	v_lshl_add_u64 v[74:75], v[74:75], 4, v[68:69]
	v_lshl_add_u64 v[72:73], v[72:73], 4, v[68:69]
	v_lshl_add_u64 v[70:71], v[70:71], 4, v[68:69]
	v_lshl_add_u64 v[66:67], v[66:67], 4, v[68:69]
	v_readlane_b32 s61, v251, 1
	v_readlane_b32 s63, v251, 3
	v_readlane_b32 s64, v251, 4
	v_readlane_b32 s65, v251, 5
	v_readlane_b32 s68, v251, 8
	v_readlane_b32 s69, v251, 9
	v_readlane_b32 s70, v251, 10
	v_readlane_b32 s71, v251, 11
	v_readlane_b32 s72, v251, 12
	v_readlane_b32 s73, v251, 13
	v_readlane_b32 s74, v251, 14
	v_readlane_b32 s75, v251, 15
	s_waitcnt vmcnt(0)
	v_add_f32_e32 v102, v50, v0
	v_min_f32_e32 v104, 0, v102
	v_mul_f32_e64 v102, |v102|, s6
	v_exp_f32_e32 v105, v102
	s_nop 0
	v_add_f32_e32 v106, 1.0, v105
	v_add_f32_e32 v102, -1.0, v106
	v_sub_f32_e32 v103, v102, v106
	v_add_f32_e32 v103, 1.0, v103
	v_sub_f32_e32 v102, v105, v102
	v_add_f32_e32 v107, v102, v103
	v_frexp_mant_f32_e32 v102, v106
	v_cmp_gt_f32_e32 vcc, s7, v102
	v_cvt_f64_f32_e32 v[102:103], v106
	v_frexp_exp_i32_f64_e32 v102, v[102:103]
	v_subbrev_co_u32_e32 v102, vcc, 0, v102, vcc
	v_sub_u32_e32 v103, 0, v102
	v_ldexp_f32 v106, v106, v103
	v_ldexp_f32 v103, v107, v103
	v_add_f32_e32 v107, -1.0, v106
	v_add_f32_e32 v108, 1.0, v107
	v_sub_f32_e32 v108, v106, v108
	v_add_f32_e32 v108, v103, v108
	v_add_f32_e32 v109, v107, v108
	v_sub_f32_e32 v107, v109, v107
	v_sub_f32_e32 v107, v108, v107
	v_add_f32_e32 v108, 1.0, v106
	v_add_f32_e32 v110, -1.0, v108
	v_sub_f32_e32 v106, v106, v110
	v_add_f32_e32 v103, v103, v106
	v_add_f32_e32 v106, v108, v103
	v_sub_f32_e32 v108, v106, v108
	v_sub_f32_e32 v103, v103, v108
	v_rcp_f32_e32 v108, v106
	v_cvt_f32_i32_e32 v102, v102
	v_cmp_neq_f32_e32 vcc, s11, v105
	v_mul_f32_e32 v110, v109, v108
	v_mul_f32_e32 v111, v106, v110
	v_fma_f32 v112, v110, v106, -v111
	v_fmac_f32_e32 v112, v110, v103
	v_add_f32_e32 v113, v111, v112
	v_sub_f32_e32 v114, v109, v113
	v_sub_f32_e32 v109, v109, v114
	v_sub_f32_e32 v111, v113, v111
	v_sub_f32_e32 v109, v109, v113
	v_add_f32_e32 v107, v107, v109
	v_sub_f32_e32 v109, v111, v112
	v_add_f32_e32 v107, v109, v107
	v_add_f32_e32 v109, v114, v107
	v_mul_f32_e32 v111, v108, v109
	v_mul_f32_e32 v112, v106, v111
	v_fma_f32 v106, v111, v106, -v112
; DEVI void epi_proj(const Params& p, int L, f32x4 (&acc)[4][4], int m0, int nt) {
;     ...
;       if (fr >= 8 && fr < 12) {
;         float* flog = (float*)(ws + OFF_FLOG);
;         const float bfh = p.in[11][L * 4 + (fr - 8)];
; #pragma unroll
;         for (int m = 0; m < 4; ++m)
; #pragma unroll
;           for (int j = 0; j < 4; ++j) {
;             const float x = acc[m][3][j] + bfh;
;             flog[(long)(mbase + m * 16 + fq * 4 + j) * 4 + (fr - 8)] = fminf(x, 0.f) - log1pf(__expf(-fabsf(x)));
	v_fmac_f32_e32 v106, v111, v103
	v_sub_f32_e32 v103, v114, v109
	v_add_f32_e32 v103, v107, v103
	v_add_f32_e32 v107, v112, v106
	v_sub_f32_e32 v113, v109, v107
	v_sub_f32_e32 v109, v109, v113
	v_sub_f32_e32 v112, v107, v112
	v_sub_f32_e32 v107, v109, v107
	v_add_f32_e32 v103, v103, v107
	v_sub_f32_e32 v106, v112, v106
	v_add_f32_e32 v103, v106, v103
	v_add_f32_e32 v106, v110, v111
	v_add_f32_e32 v103, v113, v103
	v_sub_f32_e32 v107, v106, v110
	v_mul_f32_e32 v103, v108, v103
	v_sub_f32_e32 v107, v111, v107
	v_add_f32_e32 v103, v107, v103
	v_mul_f32_e32 v110, 0x3f317218, v102
	v_add_f32_e32 v107, v106, v103
	v_fma_f32 v111, v102, s10, -v110
	v_mul_f32_e32 v108, v107, v107
	v_fmac_f32_e32 v111, 0xb102e308, v102
	v_sub_f32_e32 v102, v107, v106
	v_fmamk_f32 v109, v108, 0x3e9b6dac, v155
	v_sub_f32_e32 v102, v103, v102
	v_add_f32_e32 v103, v110, v111
	v_fmaak_f32 v109, v108, v109, 0x3f2aaada
	v_sub_f32_e32 v106, v103, v110
	v_ldexp_f32 v110, v107, 1
	v_mul_f32_e32 v107, v107, v108
	v_mul_f32_e32 v107, v107, v109
	v_add_f32_e32 v108, v110, v107
	v_sub_f32_e32 v109, v108, v110
	v_ldexp_f32 v102, v102, 1
	v_sub_f32_e32 v107, v107, v109
	v_add_f32_e32 v102, v102, v107
	v_add_f32_e32 v107, v108, v102
	v_sub_f32_e32 v108, v107, v108
	v_sub_f32_e32 v102, v102, v108
	v_add_f32_e32 v108, v103, v107
	v_sub_f32_e32 v109, v108, v103
	v_sub_f32_e32 v110, v108, v109
	v_sub_f32_e32 v106, v111, v106
	v_sub_f32_e32 v103, v103, v110
	v_sub_f32_e32 v107, v107, v109
	v_add_f32_e32 v103, v107, v103
	v_add_f32_e32 v107, v106, v102
	v_sub_f32_e32 v109, v107, v106
	v_sub_f32_e32 v110, v107, v109
	v_sub_f32_e32 v106, v106, v110
	v_sub_f32_e32 v102, v102, v109
	v_add_f32_e32 v103, v107, v103
	v_add_f32_e32 v102, v102, v106
	v_add_f32_e32 v106, v108, v103
	v_sub_f32_e32 v107, v106, v108
	v_sub_f32_e32 v103, v103, v107
	v_add_f32_e32 v102, v102, v103
	v_add_f32_e32 v102, v106, v102
	v_cndmask_b32_e32 v102, v179, v102, vcc
	v_cmp_ngt_f32_e32 vcc, -1.0, v105
	s_nop 1
	v_cndmask_b32_e32 v102, v180, v102, vcc
	v_cmp_neq_f32_e32 vcc, -1.0, v105
	s_nop 1
	v_cndmask_b32_e32 v102, v181, v102, vcc
	v_cmp_lt_f32_e64 vcc, |v105|, s50
	s_nop 1
	v_cndmask_b32_e32 v102, v102, v105, vcc
	v_sub_f32_e32 v102, v104, v102
	flat_store_dword v[98:99], v102
	v_add_f32_e32 v99, v51, v0
	v_min_f32_e32 v98, 0, v99
	v_mul_f32_e64 v99, |v99|, s6
	v_exp_f32_e32 v99, v99
	s_nop 0
	v_add_f32_e32 v104, 1.0, v99
	v_add_f32_e32 v102, -1.0, v104
	v_sub_f32_e32 v103, v102, v104
	v_add_f32_e32 v103, 1.0, v103
	v_sub_f32_e32 v102, v99, v102
	v_add_f32_e32 v105, v102, v103
	v_frexp_mant_f32_e32 v102, v104
	v_cmp_gt_f32_e32 vcc, s7, v102
	v_cvt_f64_f32_e32 v[102:103], v104
	v_frexp_exp_i32_f64_e32 v102, v[102:103]
	v_subbrev_co_u32_e32 v102, vcc, 0, v102, vcc
	v_sub_u32_e32 v103, 0, v102
	v_ldexp_f32 v104, v104, v103
	v_ldexp_f32 v103, v105, v103
	v_add_f32_e32 v105, -1.0, v104
	v_add_f32_e32 v106, 1.0, v105
	v_sub_f32_e32 v106, v104, v106
	v_add_f32_e32 v106, v103, v106
	v_add_f32_e32 v107, v105, v106
	v_sub_f32_e32 v105, v107, v105
	v_sub_f32_e32 v105, v106, v105
	v_add_f32_e32 v106, 1.0, v104
	v_add_f32_e32 v108, -1.0, v106
	v_sub_f32_e32 v104, v104, v108
	v_add_f32_e32 v103, v103, v104
	v_add_f32_e32 v104, v106, v103
	v_sub_f32_e32 v106, v104, v106
	v_sub_f32_e32 v103, v103, v106
	v_rcp_f32_e32 v106, v104
	v_cvt_f32_i32_e32 v102, v102
	v_cmp_neq_f32_e32 vcc, s11, v99
	v_mul_f32_e32 v108, v107, v106
	v_mul_f32_e32 v109, v104, v108
	v_fma_f32 v110, v108, v104, -v109
	v_fmac_f32_e32 v110, v108, v103
	v_add_f32_e32 v111, v109, v110
	v_sub_f32_e32 v112, v107, v111
	v_sub_f32_e32 v107, v107, v112
	v_sub_f32_e32 v109, v111, v109
	v_sub_f32_e32 v107, v107, v111
	v_add_f32_e32 v105, v105, v107
	v_sub_f32_e32 v107, v109, v110
	v_add_f32_e32 v105, v107, v105
	v_add_f32_e32 v107, v112, v105
	v_mul_f32_e32 v109, v106, v107
	v_mul_f32_e32 v110, v104, v109
	v_fma_f32 v104, v109, v104, -v110
	v_fmac_f32_e32 v104, v109, v103
	v_sub_f32_e32 v103, v112, v107
	v_add_f32_e32 v103, v105, v103
	v_add_f32_e32 v105, v110, v104
	v_sub_f32_e32 v111, v107, v105
	v_sub_f32_e32 v107, v107, v111
	v_sub_f32_e32 v110, v105, v110
	v_sub_f32_e32 v105, v107, v105
	v_add_f32_e32 v103, v103, v105
	v_sub_f32_e32 v104, v110, v104
	v_add_f32_e32 v103, v104, v103
	v_add_f32_e32 v104, v108, v109
	v_add_f32_e32 v103, v111, v103
	v_sub_f32_e32 v105, v104, v108
	v_mul_f32_e32 v103, v106, v103
	v_sub_f32_e32 v105, v109, v105
	v_add_f32_e32 v103, v105, v103
	v_mul_f32_e32 v108, 0x3f317218, v102
	v_add_f32_e32 v105, v104, v103
	v_fma_f32 v109, v102, s10, -v108
	v_mul_f32_e32 v106, v105, v105
	v_fmac_f32_e32 v109, 0xb102e308, v102
	v_sub_f32_e32 v102, v105, v104
	v_fmamk_f32 v107, v106, 0x3e9b6dac, v155
	v_sub_f32_e32 v102, v103, v102
	v_add_f32_e32 v103, v108, v109
	v_fmaak_f32 v107, v106, v107, 0x3f2aaada
	v_sub_f32_e32 v104, v103, v108
	v_ldexp_f32 v108, v105, 1
	v_mul_f32_e32 v105, v105, v106
	v_mul_f32_e32 v105, v105, v107
	v_add_f32_e32 v106, v108, v105
	v_sub_f32_e32 v107, v106, v108
	v_ldexp_f32 v102, v102, 1
	v_sub_f32_e32 v105, v105, v107
	v_add_f32_e32 v102, v102, v105
	v_add_f32_e32 v105, v106, v102
	v_sub_f32_e32 v106, v105, v106
	v_sub_f32_e32 v102, v102, v106
	v_add_f32_e32 v106, v103, v105
	v_sub_f32_e32 v107, v106, v103
	v_sub_f32_e32 v108, v106, v107
	v_sub_f32_e32 v104, v109, v104
	v_sub_f32_e32 v103, v103, v108
	v_sub_f32_e32 v105, v105, v107
	v_add_f32_e32 v103, v105, v103
	v_add_f32_e32 v105, v104, v102
	v_sub_f32_e32 v107, v105, v104
	v_sub_f32_e32 v108, v105, v107
	v_sub_f32_e32 v104, v104, v108
	v_sub_f32_e32 v102, v102, v107
	v_add_f32_e32 v103, v105, v103
	v_add_f32_e32 v102, v102, v104
	v_add_f32_e32 v104, v106, v103
; DEVI void epi_proj(const Params& p, int L, f32x4 (&acc)[4][4], int m0, int nt) {
;     ...
;       if (fr >= 8 && fr < 12) {
;         float* flog = (float*)(ws + OFF_FLOG);
;         const float bfh = p.in[11][L * 4 + (fr - 8)];
; #pragma unroll
;         for (int m = 0; m < 4; ++m)
; #pragma unroll
;           for (int j = 0; j < 4; ++j) {
;             const float x = acc[m][3][j] + bfh;
;             flog[(long)(mbase + m * 16 + fq * 4 + j) * 4 + (fr - 8)] = fminf(x, 0.f) - log1pf(__expf(-fabsf(x)));
	v_sub_f32_e32 v105, v104, v106
	v_sub_f32_e32 v103, v103, v105
	v_add_f32_e32 v102, v102, v103
	v_add_f32_e32 v102, v104, v102
	v_cndmask_b32_e32 v102, v179, v102, vcc
	v_cmp_ngt_f32_e32 vcc, -1.0, v99
	s_nop 1
	v_cndmask_b32_e32 v102, v180, v102, vcc
	v_cmp_neq_f32_e32 vcc, -1.0, v99
	s_nop 1
	v_cndmask_b32_e32 v102, v181, v102, vcc
	v_cmp_lt_f32_e64 vcc, |v99|, s50
	s_nop 1
	v_cndmask_b32_e32 v99, v102, v99, vcc
	v_sub_f32_e32 v98, v98, v99
	flat_store_dword v[96:97], v98
	v_add_f32_e32 v96, v52, v0
	v_min_f32_e32 v98, 0, v96
	v_mul_f32_e64 v96, |v96|, s6
	v_exp_f32_e32 v99, v96
	s_nop 0
	v_add_f32_e32 v102, 1.0, v99
	v_add_f32_e32 v96, -1.0, v102
	v_sub_f32_e32 v97, v96, v102
	v_add_f32_e32 v97, 1.0, v97
	v_sub_f32_e32 v96, v99, v96
	v_add_f32_e32 v103, v96, v97
	v_frexp_mant_f32_e32 v96, v102
	v_cmp_gt_f32_e32 vcc, s7, v96
	v_cvt_f64_f32_e32 v[96:97], v102
	v_frexp_exp_i32_f64_e32 v96, v[96:97]
	v_subbrev_co_u32_e32 v96, vcc, 0, v96, vcc
	v_sub_u32_e32 v97, 0, v96
	v_ldexp_f32 v102, v102, v97
	v_ldexp_f32 v97, v103, v97
	v_add_f32_e32 v103, -1.0, v102
	v_add_f32_e32 v104, 1.0, v103
	v_sub_f32_e32 v104, v102, v104
	v_add_f32_e32 v104, v97, v104
	v_add_f32_e32 v105, v103, v104
	v_sub_f32_e32 v103, v105, v103
	v_sub_f32_e32 v103, v104, v103
	v_add_f32_e32 v104, 1.0, v102
	v_add_f32_e32 v106, -1.0, v104
	v_sub_f32_e32 v102, v102, v106
	v_add_f32_e32 v97, v97, v102
	v_add_f32_e32 v102, v104, v97
	v_sub_f32_e32 v104, v102, v104
	v_sub_f32_e32 v97, v97, v104
	v_rcp_f32_e32 v104, v102
	v_cvt_f32_i32_e32 v96, v96
	v_cmp_neq_f32_e32 vcc, s11, v99
	v_mul_f32_e32 v106, v105, v104
	v_mul_f32_e32 v107, v102, v106
	v_fma_f32 v108, v106, v102, -v107
	v_fmac_f32_e32 v108, v106, v97
	v_add_f32_e32 v109, v107, v108
	v_sub_f32_e32 v110, v105, v109
	v_sub_f32_e32 v105, v105, v110
	v_sub_f32_e32 v107, v109, v107
	v_sub_f32_e32 v105, v105, v109
	v_add_f32_e32 v103, v103, v105
	v_sub_f32_e32 v105, v107, v108
	v_add_f32_e32 v103, v105, v103
	v_add_f32_e32 v105, v110, v103
	v_mul_f32_e32 v107, v104, v105
	v_mul_f32_e32 v108, v102, v107
	v_fma_f32 v102, v107, v102, -v108
	v_fmac_f32_e32 v102, v107, v97
	v_sub_f32_e32 v97, v110, v105
	v_add_f32_e32 v97, v103, v97
	v_add_f32_e32 v103, v108, v102
	v_sub_f32_e32 v109, v105, v103
	v_sub_f32_e32 v105, v105, v109
	v_sub_f32_e32 v108, v103, v108
	v_sub_f32_e32 v103, v105, v103
	v_add_f32_e32 v97, v97, v103
	v_sub_f32_e32 v102, v108, v102
	v_add_f32_e32 v97, v102, v97
	v_add_f32_e32 v102, v106, v107
	v_add_f32_e32 v97, v109, v97
	v_sub_f32_e32 v103, v102, v106
	v_mul_f32_e32 v97, v104, v97
	v_sub_f32_e32 v103, v107, v103
	v_add_f32_e32 v97, v103, v97
	v_mul_f32_e32 v106, 0x3f317218, v96
	v_add_f32_e32 v103, v102, v97
	v_fma_f32 v107, v96, s10, -v106
	v_mul_f32_e32 v104, v103, v103
	v_fmac_f32_e32 v107, 0xb102e308, v96
	v_sub_f32_e32 v96, v103, v102
	v_fmamk_f32 v105, v104, 0x3e9b6dac, v155
	v_sub_f32_e32 v96, v97, v96
	v_add_f32_e32 v97, v106, v107
	v_fmaak_f32 v105, v104, v105, 0x3f2aaada
	v_sub_f32_e32 v102, v97, v106
	v_ldexp_f32 v106, v103, 1
	v_mul_f32_e32 v103, v103, v104
	v_mul_f32_e32 v103, v103, v105
	v_add_f32_e32 v104, v106, v103
	v_sub_f32_e32 v105, v104, v106
	v_ldexp_f32 v96, v96, 1
	v_sub_f32_e32 v103, v103, v105
	v_add_f32_e32 v96, v96, v103
	v_add_f32_e32 v103, v104, v96
	v_sub_f32_e32 v104, v103, v104
	v_sub_f32_e32 v96, v96, v104
	v_add_f32_e32 v104, v97, v103
	v_sub_f32_e32 v105, v104, v97
	v_sub_f32_e32 v106, v104, v105
	v_sub_f32_e32 v102, v107, v102
	v_sub_f32_e32 v97, v97, v106
	v_sub_f32_e32 v103, v103, v105
	v_add_f32_e32 v97, v103, v97
	v_add_f32_e32 v103, v102, v96
	v_sub_f32_e32 v105, v103, v102
	v_sub_f32_e32 v106, v103, v105
	v_sub_f32_e32 v102, v102, v106
	v_sub_f32_e32 v96, v96, v105
	v_add_f32_e32 v97, v103, v97
	v_add_f32_e32 v96, v96, v102
	v_add_f32_e32 v102, v104, v97
	v_sub_f32_e32 v103, v102, v104
	v_sub_f32_e32 v97, v97, v103
	v_add_f32_e32 v96, v96, v97
	v_add_f32_e32 v96, v102, v96
	v_cndmask_b32_e32 v96, v179, v96, vcc
	v_cmp_ngt_f32_e32 vcc, -1.0, v99
	s_nop 1
	v_cndmask_b32_e32 v96, v180, v96, vcc
	v_cmp_neq_f32_e32 vcc, -1.0, v99
	s_nop 1
	v_cndmask_b32_e32 v96, v181, v96, vcc
	v_cmp_lt_f32_e64 vcc, |v99|, s50
	s_nop 1
	v_cndmask_b32_e32 v96, v96, v99, vcc
	v_sub_f32_e32 v96, v98, v96
	flat_store_dword v[94:95], v96
	v_add_f32_e32 v94, v53, v0
	v_min_f32_e32 v96, 0, v94
	v_mul_f32_e64 v94, |v94|, s6
	v_exp_f32_e32 v97, v94
	s_nop 0
	v_add_f32_e32 v98, 1.0, v97
	v_add_f32_e32 v94, -1.0, v98
	v_sub_f32_e32 v95, v94, v98
	v_add_f32_e32 v95, 1.0, v95
	v_sub_f32_e32 v94, v97, v94
	v_add_f32_e32 v99, v94, v95
	v_frexp_mant_f32_e32 v94, v98
	v_cmp_gt_f32_e32 vcc, s7, v94
	v_cvt_f64_f32_e32 v[94:95], v98
	v_frexp_exp_i32_f64_e32 v94, v[94:95]
	v_subbrev_co_u32_e32 v94, vcc, 0, v94, vcc
	v_sub_u32_e32 v95, 0, v94
	v_ldexp_f32 v98, v98, v95
	v_ldexp_f32 v95, v99, v95
	v_add_f32_e32 v99, -1.0, v98
	v_add_f32_e32 v102, 1.0, v99
	v_sub_f32_e32 v102, v98, v102
	v_add_f32_e32 v102, v95, v102
	v_add_f32_e32 v103, v99, v102
	v_sub_f32_e32 v99, v103, v99
	v_sub_f32_e32 v99, v102, v99
	v_add_f32_e32 v102, 1.0, v98
	v_add_f32_e32 v104, -1.0, v102
	v_sub_f32_e32 v98, v98, v104
	v_add_f32_e32 v95, v95, v98
	v_add_f32_e32 v98, v102, v95
	v_sub_f32_e32 v102, v98, v102
	v_sub_f32_e32 v95, v95, v102
	v_rcp_f32_e32 v102, v98
	v_cvt_f32_i32_e32 v94, v94
	v_cmp_neq_f32_e32 vcc, s11, v97
	v_mul_f32_e32 v104, v103, v102
	v_mul_f32_e32 v105, v98, v104
	v_fma_f32 v106, v104, v98, -v105
	v_fmac_f32_e32 v106, v104, v95
	v_add_f32_e32 v107, v105, v106
	v_sub_f32_e32 v108, v103, v107
	v_sub_f32_e32 v103, v103, v108
	v_sub_f32_e32 v105, v107, v105
	v_sub_f32_e32 v103, v103, v107
	v_add_f32_e32 v99, v99, v103
; DEVI void epi_proj(const Params& p, int L, f32x4 (&acc)[4][4], int m0, int nt) {
;     ...
;       if (fr >= 8 && fr < 12) {
;         float* flog = (float*)(ws + OFF_FLOG);
;         const float bfh = p.in[11][L * 4 + (fr - 8)];
; #pragma unroll
;         for (int m = 0; m < 4; ++m)
; #pragma unroll
;           for (int j = 0; j < 4; ++j) {
;             const float x = acc[m][3][j] + bfh;
;             flog[(long)(mbase + m * 16 + fq * 4 + j) * 4 + (fr - 8)] = fminf(x, 0.f) - log1pf(__expf(-fabsf(x)));
	v_sub_f32_e32 v103, v105, v106
	v_add_f32_e32 v99, v103, v99
	v_add_f32_e32 v103, v108, v99
	v_mul_f32_e32 v105, v102, v103
	v_mul_f32_e32 v106, v98, v105
	v_fma_f32 v98, v105, v98, -v106
	v_fmac_f32_e32 v98, v105, v95
	v_sub_f32_e32 v95, v108, v103
	v_add_f32_e32 v95, v99, v95
	v_add_f32_e32 v99, v106, v98
	v_sub_f32_e32 v107, v103, v99
	v_sub_f32_e32 v103, v103, v107
	v_sub_f32_e32 v106, v99, v106
	v_sub_f32_e32 v99, v103, v99
	v_add_f32_e32 v95, v95, v99
	v_sub_f32_e32 v98, v106, v98
	v_add_f32_e32 v95, v98, v95
	v_add_f32_e32 v98, v104, v105
	v_add_f32_e32 v95, v107, v95
	v_sub_f32_e32 v99, v98, v104
	v_mul_f32_e32 v95, v102, v95
	v_sub_f32_e32 v99, v105, v99
	v_add_f32_e32 v95, v99, v95
	v_mul_f32_e32 v104, 0x3f317218, v94
	v_add_f32_e32 v99, v98, v95
	v_fma_f32 v105, v94, s10, -v104
	v_mul_f32_e32 v102, v99, v99
	v_fmac_f32_e32 v105, 0xb102e308, v94
	v_sub_f32_e32 v94, v99, v98
	v_fmamk_f32 v103, v102, 0x3e9b6dac, v155
	v_sub_f32_e32 v94, v95, v94
	v_add_f32_e32 v95, v104, v105
	v_fmaak_f32 v103, v102, v103, 0x3f2aaada
	v_sub_f32_e32 v98, v95, v104
	v_ldexp_f32 v104, v99, 1
	v_mul_f32_e32 v99, v99, v102
	v_mul_f32_e32 v99, v99, v103
	v_add_f32_e32 v102, v104, v99
	v_sub_f32_e32 v103, v102, v104
	v_ldexp_f32 v94, v94, 1
	v_sub_f32_e32 v99, v99, v103
	v_add_f32_e32 v94, v94, v99
	v_add_f32_e32 v99, v102, v94
	v_sub_f32_e32 v102, v99, v102
	v_sub_f32_e32 v94, v94, v102
	v_add_f32_e32 v102, v95, v99
	v_sub_f32_e32 v103, v102, v95
	v_sub_f32_e32 v104, v102, v103
	v_sub_f32_e32 v98, v105, v98
	v_sub_f32_e32 v95, v95, v104
	v_sub_f32_e32 v99, v99, v103
	v_add_f32_e32 v95, v99, v95
	v_add_f32_e32 v99, v98, v94
	v_sub_f32_e32 v103, v99, v98
	v_sub_f32_e32 v104, v99, v103
	v_sub_f32_e32 v98, v98, v104
	v_sub_f32_e32 v94, v94, v103
	v_add_f32_e32 v95, v99, v95
	v_add_f32_e32 v94, v94, v98
	v_add_f32_e32 v98, v102, v95
	v_sub_f32_e32 v99, v98, v102
	v_sub_f32_e32 v95, v95, v99
	v_add_f32_e32 v94, v94, v95
	v_add_f32_e32 v94, v98, v94
	v_cndmask_b32_e32 v94, v179, v94, vcc
	v_cmp_ngt_f32_e32 vcc, -1.0, v97
	s_nop 1
	v_cndmask_b32_e32 v94, v180, v94, vcc
	v_cmp_neq_f32_e32 vcc, -1.0, v97
	s_nop 1
	v_cndmask_b32_e32 v94, v181, v94, vcc
	v_cmp_lt_f32_e64 vcc, |v97|, s50
	s_nop 1
	v_cndmask_b32_e32 v94, v94, v97, vcc
	v_sub_f32_e32 v94, v96, v94
	flat_store_dword v[92:93], v94
	v_add_f32_e32 v92, v34, v0
	v_min_f32_e32 v94, 0, v92
	v_mul_f32_e64 v92, |v92|, s6
	v_exp_f32_e32 v95, v92
	s_nop 0
	v_add_f32_e32 v96, 1.0, v95
	v_add_f32_e32 v92, -1.0, v96
	v_sub_f32_e32 v93, v92, v96
	v_add_f32_e32 v93, 1.0, v93
	v_sub_f32_e32 v92, v95, v92
	v_add_f32_e32 v97, v92, v93
	v_frexp_mant_f32_e32 v92, v96
	v_cmp_gt_f32_e32 vcc, s7, v92
	v_cvt_f64_f32_e32 v[92:93], v96
	v_frexp_exp_i32_f64_e32 v92, v[92:93]
	v_subbrev_co_u32_e32 v92, vcc, 0, v92, vcc
	v_sub_u32_e32 v93, 0, v92
	v_ldexp_f32 v96, v96, v93
	v_ldexp_f32 v93, v97, v93
	v_add_f32_e32 v97, -1.0, v96
	v_add_f32_e32 v98, 1.0, v97
	v_sub_f32_e32 v98, v96, v98
	v_add_f32_e32 v98, v93, v98
	v_add_f32_e32 v99, v97, v98
	v_sub_f32_e32 v97, v99, v97
	v_sub_f32_e32 v97, v98, v97
	v_add_f32_e32 v98, 1.0, v96
	v_add_f32_e32 v102, -1.0, v98
	v_sub_f32_e32 v96, v96, v102
	v_add_f32_e32 v93, v93, v96
	v_add_f32_e32 v96, v98, v93
	v_sub_f32_e32 v98, v96, v98
	v_sub_f32_e32 v93, v93, v98
	v_rcp_f32_e32 v98, v96
	v_cvt_f32_i32_e32 v92, v92
	v_cmp_neq_f32_e32 vcc, s11, v95
	v_mul_f32_e32 v102, v99, v98
	v_mul_f32_e32 v103, v96, v102
	v_fma_f32 v104, v102, v96, -v103
	v_fmac_f32_e32 v104, v102, v93
	v_add_f32_e32 v105, v103, v104
	v_sub_f32_e32 v106, v99, v105
	v_sub_f32_e32 v99, v99, v106
	v_sub_f32_e32 v103, v105, v103
	v_sub_f32_e32 v99, v99, v105
	v_add_f32_e32 v97, v97, v99
	v_sub_f32_e32 v99, v103, v104
	v_add_f32_e32 v97, v99, v97
	v_add_f32_e32 v99, v106, v97
	v_mul_f32_e32 v103, v98, v99
	v_mul_f32_e32 v104, v96, v103
	v_fma_f32 v96, v103, v96, -v104
	v_fmac_f32_e32 v96, v103, v93
	v_sub_f32_e32 v93, v106, v99
	v_add_f32_e32 v93, v97, v93
	v_add_f32_e32 v97, v104, v96
	v_sub_f32_e32 v105, v99, v97
	v_sub_f32_e32 v99, v99, v105
	v_sub_f32_e32 v104, v97, v104
	v_sub_f32_e32 v97, v99, v97
	v_add_f32_e32 v93, v93, v97
	v_sub_f32_e32 v96, v104, v96
	v_add_f32_e32 v93, v96, v93
	v_add_f32_e32 v96, v102, v103
	v_add_f32_e32 v93, v105, v93
	v_sub_f32_e32 v97, v96, v102
	v_mul_f32_e32 v93, v98, v93
	v_sub_f32_e32 v97, v103, v97
	v_add_f32_e32 v93, v97, v93
	v_mul_f32_e32 v102, 0x3f317218, v92
	v_add_f32_e32 v97, v96, v93
	v_fma_f32 v103, v92, s10, -v102
	v_mul_f32_e32 v98, v97, v97
	v_fmac_f32_e32 v103, 0xb102e308, v92
	v_sub_f32_e32 v92, v97, v96
	v_fmamk_f32 v99, v98, 0x3e9b6dac, v155
	v_sub_f32_e32 v92, v93, v92
	v_add_f32_e32 v93, v102, v103
	v_fmaak_f32 v99, v98, v99, 0x3f2aaada
	v_sub_f32_e32 v96, v93, v102
	v_ldexp_f32 v102, v97, 1
	v_mul_f32_e32 v97, v97, v98
	v_mul_f32_e32 v97, v97, v99
	v_add_f32_e32 v98, v102, v97
	v_sub_f32_e32 v99, v98, v102
	v_ldexp_f32 v92, v92, 1
	v_sub_f32_e32 v97, v97, v99
	v_add_f32_e32 v92, v92, v97
	v_add_f32_e32 v97, v98, v92
	v_sub_f32_e32 v98, v97, v98
	v_sub_f32_e32 v92, v92, v98
	v_add_f32_e32 v98, v93, v97
	v_sub_f32_e32 v99, v98, v93
	v_sub_f32_e32 v102, v98, v99
	v_sub_f32_e32 v96, v103, v96
	v_sub_f32_e32 v93, v93, v102
	v_sub_f32_e32 v97, v97, v99
	v_add_f32_e32 v93, v97, v93
	v_add_f32_e32 v97, v96, v92
	v_sub_f32_e32 v99, v97, v96
	v_sub_f32_e32 v102, v97, v99
	v_sub_f32_e32 v96, v96, v102
	v_sub_f32_e32 v92, v92, v99
	v_add_f32_e32 v93, v97, v93
	v_add_f32_e32 v92, v92, v96
	v_add_f32_e32 v96, v98, v93
	v_sub_f32_e32 v97, v96, v98
	v_sub_f32_e32 v93, v93, v97
	v_add_f32_e32 v92, v92, v93
	v_add_f32_e32 v92, v96, v92
	v_cndmask_b32_e32 v92, v179, v92, vcc
; DEVI void epi_proj(const Params& p, int L, f32x4 (&acc)[4][4], int m0, int nt) {
;     ...
;       if (fr >= 8 && fr < 12) {
;         float* flog = (float*)(ws + OFF_FLOG);
;         const float bfh = p.in[11][L * 4 + (fr - 8)];
; #pragma unroll
;         for (int m = 0; m < 4; ++m)
; #pragma unroll
;           for (int j = 0; j < 4; ++j) {
;             const float x = acc[m][3][j] + bfh;
;             flog[(long)(mbase + m * 16 + fq * 4 + j) * 4 + (fr - 8)] = fminf(x, 0.f) - log1pf(__expf(-fabsf(x)));
	v_cmp_ngt_f32_e32 vcc, -1.0, v95
	s_nop 1
	v_cndmask_b32_e32 v92, v180, v92, vcc
	v_cmp_neq_f32_e32 vcc, -1.0, v95
	s_nop 1
	v_cndmask_b32_e32 v92, v181, v92, vcc
	v_cmp_lt_f32_e64 vcc, |v95|, s50
	s_nop 1
	v_cndmask_b32_e32 v92, v92, v95, vcc
	v_sub_f32_e32 v92, v94, v92
	flat_store_dword v[90:91], v92
	v_add_f32_e32 v90, v35, v0
	v_min_f32_e32 v92, 0, v90
	v_mul_f32_e64 v90, |v90|, s6
	v_exp_f32_e32 v93, v90
	s_nop 0
	v_add_f32_e32 v94, 1.0, v93
	v_add_f32_e32 v90, -1.0, v94
	v_sub_f32_e32 v91, v90, v94
	v_add_f32_e32 v91, 1.0, v91
	v_sub_f32_e32 v90, v93, v90
	v_add_f32_e32 v95, v90, v91
	v_frexp_mant_f32_e32 v90, v94
	v_cmp_gt_f32_e32 vcc, s7, v90
	v_cvt_f64_f32_e32 v[90:91], v94
	v_frexp_exp_i32_f64_e32 v90, v[90:91]
	v_subbrev_co_u32_e32 v90, vcc, 0, v90, vcc
	v_sub_u32_e32 v91, 0, v90
	v_ldexp_f32 v94, v94, v91
	v_ldexp_f32 v91, v95, v91
	v_add_f32_e32 v95, -1.0, v94
	v_add_f32_e32 v96, 1.0, v95
	v_sub_f32_e32 v96, v94, v96
	v_add_f32_e32 v96, v91, v96
	v_add_f32_e32 v97, v95, v96
	v_sub_f32_e32 v95, v97, v95
	v_sub_f32_e32 v95, v96, v95
	v_add_f32_e32 v96, 1.0, v94
	v_add_f32_e32 v98, -1.0, v96
	v_sub_f32_e32 v94, v94, v98
	v_add_f32_e32 v91, v91, v94
	v_add_f32_e32 v94, v96, v91
	v_sub_f32_e32 v96, v94, v96
	v_sub_f32_e32 v91, v91, v96
	v_rcp_f32_e32 v96, v94
	v_cvt_f32_i32_e32 v90, v90
	v_cmp_neq_f32_e32 vcc, s11, v93
	v_mul_f32_e32 v98, v97, v96
	v_mul_f32_e32 v99, v94, v98
	v_fma_f32 v102, v98, v94, -v99
	v_fmac_f32_e32 v102, v98, v91
	v_add_f32_e32 v103, v99, v102
	v_sub_f32_e32 v104, v97, v103
	v_sub_f32_e32 v97, v97, v104
	v_sub_f32_e32 v99, v103, v99
	v_sub_f32_e32 v97, v97, v103
	v_add_f32_e32 v95, v95, v97
	v_sub_f32_e32 v97, v99, v102
	v_add_f32_e32 v95, v97, v95
	v_add_f32_e32 v97, v104, v95
	v_mul_f32_e32 v99, v96, v97
	v_mul_f32_e32 v102, v94, v99
	v_fma_f32 v94, v99, v94, -v102
	v_fmac_f32_e32 v94, v99, v91
	v_sub_f32_e32 v91, v104, v97
	v_add_f32_e32 v91, v95, v91
	v_add_f32_e32 v95, v102, v94
	v_sub_f32_e32 v103, v97, v95
	v_sub_f32_e32 v97, v97, v103
	v_sub_f32_e32 v102, v95, v102
	v_sub_f32_e32 v95, v97, v95
	v_add_f32_e32 v91, v91, v95
	v_sub_f32_e32 v94, v102, v94
	v_add_f32_e32 v91, v94, v91
	v_add_f32_e32 v94, v98, v99
	v_add_f32_e32 v91, v103, v91
	v_sub_f32_e32 v95, v94, v98
	v_mul_f32_e32 v91, v96, v91
	v_sub_f32_e32 v95, v99, v95
	v_add_f32_e32 v91, v95, v91
	v_mul_f32_e32 v98, 0x3f317218, v90
	v_add_f32_e32 v95, v94, v91
	v_fma_f32 v99, v90, s10, -v98
	v_mul_f32_e32 v96, v95, v95
	v_fmac_f32_e32 v99, 0xb102e308, v90
	v_sub_f32_e32 v90, v95, v94
	v_fmamk_f32 v97, v96, 0x3e9b6dac, v155
	v_sub_f32_e32 v90, v91, v90
	v_add_f32_e32 v91, v98, v99
	v_fmaak_f32 v97, v96, v97, 0x3f2aaada
	v_sub_f32_e32 v94, v91, v98
	v_ldexp_f32 v98, v95, 1
	v_mul_f32_e32 v95, v95, v96
	v_mul_f32_e32 v95, v95, v97
	v_add_f32_e32 v96, v98, v95
	v_sub_f32_e32 v97, v96, v98
	v_ldexp_f32 v90, v90, 1
	v_sub_f32_e32 v95, v95, v97
	v_add_f32_e32 v90, v90, v95
	v_add_f32_e32 v95, v96, v90
	v_sub_f32_e32 v96, v95, v96
	v_sub_f32_e32 v90, v90, v96
	v_add_f32_e32 v96, v91, v95
	v_sub_f32_e32 v97, v96, v91
	v_sub_f32_e32 v98, v96, v97
	v_sub_f32_e32 v94, v99, v94
	v_sub_f32_e32 v91, v91, v98
	v_sub_f32_e32 v95, v95, v97
	v_add_f32_e32 v91, v95, v91
	v_add_f32_e32 v95, v94, v90
	v_sub_f32_e32 v97, v95, v94
	v_sub_f32_e32 v98, v95, v97
	v_sub_f32_e32 v94, v94, v98
	v_sub_f32_e32 v90, v90, v97
	v_add_f32_e32 v91, v95, v91
	v_add_f32_e32 v90, v90, v94
	v_add_f32_e32 v94, v96, v91
	v_sub_f32_e32 v95, v94, v96
	v_sub_f32_e32 v91, v91, v95
	v_add_f32_e32 v90, v90, v91
	v_add_f32_e32 v90, v94, v90
	v_cndmask_b32_e32 v90, v179, v90, vcc
	v_cmp_ngt_f32_e32 vcc, -1.0, v93
	s_nop 1
	v_cndmask_b32_e32 v90, v180, v90, vcc
	v_cmp_neq_f32_e32 vcc, -1.0, v93
	s_nop 1
	v_cndmask_b32_e32 v90, v181, v90, vcc
	v_cmp_lt_f32_e64 vcc, |v93|, s50
	s_nop 1
	v_cndmask_b32_e32 v90, v90, v93, vcc
	v_sub_f32_e32 v90, v92, v90
	flat_store_dword v[88:89], v90
	v_add_f32_e32 v88, v36, v0
	v_min_f32_e32 v90, 0, v88
	v_mul_f32_e64 v88, |v88|, s6
	v_exp_f32_e32 v91, v88
	s_nop 0
	v_add_f32_e32 v92, 1.0, v91
	v_add_f32_e32 v88, -1.0, v92
	v_sub_f32_e32 v89, v88, v92
	v_add_f32_e32 v89, 1.0, v89
	v_sub_f32_e32 v88, v91, v88
	v_add_f32_e32 v93, v88, v89
	v_frexp_mant_f32_e32 v88, v92
	v_cmp_gt_f32_e32 vcc, s7, v88
	v_cvt_f64_f32_e32 v[88:89], v92
	v_frexp_exp_i32_f64_e32 v88, v[88:89]
	v_subbrev_co_u32_e32 v88, vcc, 0, v88, vcc
	v_sub_u32_e32 v89, 0, v88
	v_ldexp_f32 v92, v92, v89
	v_ldexp_f32 v89, v93, v89
	v_add_f32_e32 v93, -1.0, v92
	v_add_f32_e32 v94, 1.0, v93
	v_sub_f32_e32 v94, v92, v94
	v_add_f32_e32 v94, v89, v94
	v_add_f32_e32 v95, v93, v94
	v_sub_f32_e32 v93, v95, v93
	v_sub_f32_e32 v93, v94, v93
	v_add_f32_e32 v94, 1.0, v92
	v_add_f32_e32 v96, -1.0, v94
	v_sub_f32_e32 v92, v92, v96
	v_add_f32_e32 v89, v89, v92
	v_add_f32_e32 v92, v94, v89
	v_sub_f32_e32 v94, v92, v94
	v_sub_f32_e32 v89, v89, v94
	v_rcp_f32_e32 v94, v92
	v_cvt_f32_i32_e32 v88, v88
	v_cmp_neq_f32_e32 vcc, s11, v91
	v_mul_f32_e32 v96, v95, v94
	v_mul_f32_e32 v97, v92, v96
	v_fma_f32 v98, v96, v92, -v97
	v_fmac_f32_e32 v98, v96, v89
	v_add_f32_e32 v99, v97, v98
	v_sub_f32_e32 v102, v95, v99
	v_sub_f32_e32 v95, v95, v102
	v_sub_f32_e32 v97, v99, v97
	v_sub_f32_e32 v95, v95, v99
	v_add_f32_e32 v93, v93, v95
	v_sub_f32_e32 v95, v97, v98
	v_add_f32_e32 v93, v95, v93
	v_add_f32_e32 v95, v102, v93
	v_mul_f32_e32 v97, v94, v95
	v_mul_f32_e32 v98, v92, v97
	v_fma_f32 v92, v97, v92, -v98
	v_fmac_f32_e32 v92, v97, v89
	v_sub_f32_e32 v89, v102, v95
	v_add_f32_e32 v89, v93, v89
	v_add_f32_e32 v93, v98, v92
	v_sub_f32_e32 v99, v95, v93
	v_sub_f32_e32 v95, v95, v99
	v_sub_f32_e32 v98, v93, v98
	v_sub_f32_e32 v93, v95, v93
; DEVI void epi_proj(const Params& p, int L, f32x4 (&acc)[4][4], int m0, int nt) {
;     ...
;       if (fr >= 8 && fr < 12) {
;         float* flog = (float*)(ws + OFF_FLOG);
;         const float bfh = p.in[11][L * 4 + (fr - 8)];
; #pragma unroll
;         for (int m = 0; m < 4; ++m)
; #pragma unroll
;           for (int j = 0; j < 4; ++j) {
;             const float x = acc[m][3][j] + bfh;
;             flog[(long)(mbase + m * 16 + fq * 4 + j) * 4 + (fr - 8)] = fminf(x, 0.f) - log1pf(__expf(-fabsf(x)));
	v_add_f32_e32 v89, v89, v93
	v_sub_f32_e32 v92, v98, v92
	v_add_f32_e32 v89, v92, v89
	v_add_f32_e32 v92, v96, v97
	v_add_f32_e32 v89, v99, v89
	v_sub_f32_e32 v93, v92, v96
	v_mul_f32_e32 v89, v94, v89
	v_sub_f32_e32 v93, v97, v93
	v_add_f32_e32 v89, v93, v89
	v_mul_f32_e32 v96, 0x3f317218, v88
	v_add_f32_e32 v93, v92, v89
	v_fma_f32 v97, v88, s10, -v96
	v_mul_f32_e32 v94, v93, v93
	v_fmac_f32_e32 v97, 0xb102e308, v88
	v_sub_f32_e32 v88, v93, v92
	v_fmamk_f32 v95, v94, 0x3e9b6dac, v155
	v_sub_f32_e32 v88, v89, v88
	v_add_f32_e32 v89, v96, v97
	v_fmaak_f32 v95, v94, v95, 0x3f2aaada
	v_sub_f32_e32 v92, v89, v96
	v_ldexp_f32 v96, v93, 1
	v_mul_f32_e32 v93, v93, v94
	v_mul_f32_e32 v93, v93, v95
	v_add_f32_e32 v94, v96, v93
	v_sub_f32_e32 v95, v94, v96
	v_ldexp_f32 v88, v88, 1
	v_sub_f32_e32 v93, v93, v95
	v_add_f32_e32 v88, v88, v93
	v_add_f32_e32 v93, v94, v88
	v_sub_f32_e32 v94, v93, v94
	v_sub_f32_e32 v88, v88, v94
	v_add_f32_e32 v94, v89, v93
	v_sub_f32_e32 v95, v94, v89
	v_sub_f32_e32 v96, v94, v95
	v_sub_f32_e32 v92, v97, v92
	v_sub_f32_e32 v89, v89, v96
	v_sub_f32_e32 v93, v93, v95
	v_add_f32_e32 v89, v93, v89
	v_add_f32_e32 v93, v92, v88
	v_sub_f32_e32 v95, v93, v92
	v_sub_f32_e32 v96, v93, v95
	v_sub_f32_e32 v92, v92, v96
	v_sub_f32_e32 v88, v88, v95
	v_add_f32_e32 v89, v93, v89
	v_add_f32_e32 v88, v88, v92
	v_add_f32_e32 v92, v94, v89
	v_sub_f32_e32 v93, v92, v94
	v_sub_f32_e32 v89, v89, v93
	v_add_f32_e32 v88, v88, v89
	v_add_f32_e32 v88, v92, v88
	v_cndmask_b32_e32 v88, v179, v88, vcc
	v_cmp_ngt_f32_e32 vcc, -1.0, v91
	s_nop 1
	v_cndmask_b32_e32 v88, v180, v88, vcc
	v_cmp_neq_f32_e32 vcc, -1.0, v91
	s_nop 1
	v_cndmask_b32_e32 v88, v181, v88, vcc
	v_cmp_lt_f32_e64 vcc, |v91|, s50
	s_nop 1
	v_cndmask_b32_e32 v88, v88, v91, vcc
	v_sub_f32_e32 v88, v90, v88
	flat_store_dword v[86:87], v88
	v_add_f32_e32 v86, v37, v0
	v_min_f32_e32 v88, 0, v86
	v_mul_f32_e64 v86, |v86|, s6
	v_exp_f32_e32 v89, v86
	s_nop 0
	v_add_f32_e32 v90, 1.0, v89
	v_add_f32_e32 v86, -1.0, v90
	v_sub_f32_e32 v87, v86, v90
	v_add_f32_e32 v87, 1.0, v87
	v_sub_f32_e32 v86, v89, v86
	v_add_f32_e32 v91, v86, v87
	v_frexp_mant_f32_e32 v86, v90
	v_cmp_gt_f32_e32 vcc, s7, v86
	v_cvt_f64_f32_e32 v[86:87], v90
	v_frexp_exp_i32_f64_e32 v86, v[86:87]
	v_subbrev_co_u32_e32 v86, vcc, 0, v86, vcc
	v_sub_u32_e32 v87, 0, v86
	v_ldexp_f32 v90, v90, v87
	v_ldexp_f32 v87, v91, v87
	v_add_f32_e32 v91, -1.0, v90
	v_add_f32_e32 v92, 1.0, v91
	v_sub_f32_e32 v92, v90, v92
	v_add_f32_e32 v92, v87, v92
	v_add_f32_e32 v93, v91, v92
	v_sub_f32_e32 v91, v93, v91
	v_sub_f32_e32 v91, v92, v91
	v_add_f32_e32 v92, 1.0, v90
	v_add_f32_e32 v94, -1.0, v92
	v_sub_f32_e32 v90, v90, v94
	v_add_f32_e32 v87, v87, v90
	v_add_f32_e32 v90, v92, v87
	v_sub_f32_e32 v92, v90, v92
	v_sub_f32_e32 v87, v87, v92
	v_rcp_f32_e32 v92, v90
	v_cvt_f32_i32_e32 v86, v86
	v_cmp_neq_f32_e32 vcc, s11, v89
	v_mul_f32_e32 v94, v93, v92
	v_mul_f32_e32 v95, v90, v94
	v_fma_f32 v96, v94, v90, -v95
	v_fmac_f32_e32 v96, v94, v87
	v_add_f32_e32 v97, v95, v96
	v_sub_f32_e32 v98, v93, v97
	v_sub_f32_e32 v93, v93, v98
	v_sub_f32_e32 v95, v97, v95
	v_sub_f32_e32 v93, v93, v97
	v_add_f32_e32 v91, v91, v93
	v_sub_f32_e32 v93, v95, v96
	v_add_f32_e32 v91, v93, v91
	v_add_f32_e32 v93, v98, v91
	v_mul_f32_e32 v95, v92, v93
	v_mul_f32_e32 v96, v90, v95
	v_fma_f32 v90, v95, v90, -v96
	v_fmac_f32_e32 v90, v95, v87
	v_sub_f32_e32 v87, v98, v93
	v_add_f32_e32 v87, v91, v87
	v_add_f32_e32 v91, v96, v90
	v_sub_f32_e32 v97, v93, v91
	v_sub_f32_e32 v93, v93, v97
	v_sub_f32_e32 v96, v91, v96
	v_sub_f32_e32 v91, v93, v91
	v_add_f32_e32 v87, v87, v91
	v_sub_f32_e32 v90, v96, v90
	v_add_f32_e32 v87, v90, v87
	v_add_f32_e32 v90, v94, v95
	v_add_f32_e32 v87, v97, v87
	v_sub_f32_e32 v91, v90, v94
	v_mul_f32_e32 v87, v92, v87
	v_sub_f32_e32 v91, v95, v91
	v_add_f32_e32 v87, v91, v87
	v_mul_f32_e32 v94, 0x3f317218, v86
	v_add_f32_e32 v91, v90, v87
	v_fma_f32 v95, v86, s10, -v94
	v_mul_f32_e32 v92, v91, v91
	v_fmac_f32_e32 v95, 0xb102e308, v86
	v_sub_f32_e32 v86, v91, v90
	v_fmamk_f32 v93, v92, 0x3e9b6dac, v155
	v_sub_f32_e32 v86, v87, v86
	v_add_f32_e32 v87, v94, v95
	v_fmaak_f32 v93, v92, v93, 0x3f2aaada
	v_sub_f32_e32 v90, v87, v94
	v_ldexp_f32 v94, v91, 1
	v_mul_f32_e32 v91, v91, v92
	v_mul_f32_e32 v91, v91, v93
	v_add_f32_e32 v92, v94, v91
	v_sub_f32_e32 v93, v92, v94
	v_ldexp_f32 v86, v86, 1
	v_sub_f32_e32 v91, v91, v93
	v_add_f32_e32 v86, v86, v91
	v_add_f32_e32 v91, v92, v86
	v_sub_f32_e32 v92, v91, v92
	v_sub_f32_e32 v86, v86, v92
	v_add_f32_e32 v92, v87, v91
	v_sub_f32_e32 v93, v92, v87
	v_sub_f32_e32 v94, v92, v93
	v_sub_f32_e32 v90, v95, v90
	v_sub_f32_e32 v87, v87, v94
	v_sub_f32_e32 v91, v91, v93
	v_add_f32_e32 v87, v91, v87
	v_add_f32_e32 v91, v90, v86
	v_sub_f32_e32 v93, v91, v90
	v_sub_f32_e32 v94, v91, v93
	v_sub_f32_e32 v90, v90, v94
	v_sub_f32_e32 v86, v86, v93
	v_add_f32_e32 v87, v91, v87
	v_add_f32_e32 v86, v86, v90
	v_add_f32_e32 v90, v92, v87
	v_sub_f32_e32 v91, v90, v92
	v_sub_f32_e32 v87, v87, v91
	v_add_f32_e32 v86, v86, v87
	v_add_f32_e32 v86, v90, v86
	v_cndmask_b32_e32 v86, v179, v86, vcc
	v_cmp_ngt_f32_e32 vcc, -1.0, v89
	s_nop 1
	v_cndmask_b32_e32 v86, v180, v86, vcc
	v_cmp_neq_f32_e32 vcc, -1.0, v89
	s_nop 1
	v_cndmask_b32_e32 v86, v181, v86, vcc
	v_cmp_lt_f32_e64 vcc, |v89|, s50
	s_nop 1
	v_cndmask_b32_e32 v86, v86, v89, vcc
	v_sub_f32_e32 v86, v88, v86
	flat_store_dword v[84:85], v86
	v_add_f32_e32 v84, v18, v0
	v_min_f32_e32 v86, 0, v84
	v_mul_f32_e64 v84, |v84|, s6
	v_exp_f32_e32 v87, v84
	s_nop 0
	v_add_f32_e32 v88, 1.0, v87
	v_add_f32_e32 v84, -1.0, v88
	v_sub_f32_e32 v85, v84, v88
	v_add_f32_e32 v85, 1.0, v85
; DEVI void epi_proj(const Params& p, int L, f32x4 (&acc)[4][4], int m0, int nt) {
;     ...
;       if (fr >= 8 && fr < 12) {
;         float* flog = (float*)(ws + OFF_FLOG);
;         const float bfh = p.in[11][L * 4 + (fr - 8)];
; #pragma unroll
;         for (int m = 0; m < 4; ++m)
; #pragma unroll
;           for (int j = 0; j < 4; ++j) {
;             const float x = acc[m][3][j] + bfh;
;             flog[(long)(mbase + m * 16 + fq * 4 + j) * 4 + (fr - 8)] = fminf(x, 0.f) - log1pf(__expf(-fabsf(x)));
	v_sub_f32_e32 v84, v87, v84
	v_add_f32_e32 v89, v84, v85
	v_frexp_mant_f32_e32 v84, v88
	v_cmp_gt_f32_e32 vcc, s7, v84
	v_cvt_f64_f32_e32 v[84:85], v88
	v_frexp_exp_i32_f64_e32 v84, v[84:85]
	v_subbrev_co_u32_e32 v84, vcc, 0, v84, vcc
	v_sub_u32_e32 v85, 0, v84
	v_ldexp_f32 v88, v88, v85
	v_ldexp_f32 v85, v89, v85
	v_add_f32_e32 v89, -1.0, v88
	v_add_f32_e32 v90, 1.0, v89
	v_sub_f32_e32 v90, v88, v90
	v_add_f32_e32 v90, v85, v90
	v_add_f32_e32 v91, v89, v90
	v_sub_f32_e32 v89, v91, v89
	v_sub_f32_e32 v89, v90, v89
	v_add_f32_e32 v90, 1.0, v88
	v_add_f32_e32 v92, -1.0, v90
	v_sub_f32_e32 v88, v88, v92
	v_add_f32_e32 v85, v85, v88
	v_add_f32_e32 v88, v90, v85
	v_sub_f32_e32 v90, v88, v90
	v_sub_f32_e32 v85, v85, v90
	v_rcp_f32_e32 v90, v88
	v_cvt_f32_i32_e32 v84, v84
	v_cmp_neq_f32_e32 vcc, s11, v87
	v_mul_f32_e32 v92, v91, v90
	v_mul_f32_e32 v93, v88, v92
	v_fma_f32 v94, v92, v88, -v93
	v_fmac_f32_e32 v94, v92, v85
	v_add_f32_e32 v95, v93, v94
	v_sub_f32_e32 v96, v91, v95
	v_sub_f32_e32 v91, v91, v96
	v_sub_f32_e32 v93, v95, v93
	v_sub_f32_e32 v91, v91, v95
	v_add_f32_e32 v89, v89, v91
	v_sub_f32_e32 v91, v93, v94
	v_add_f32_e32 v89, v91, v89
	v_add_f32_e32 v91, v96, v89
	v_mul_f32_e32 v93, v90, v91
	v_mul_f32_e32 v94, v88, v93
	v_fma_f32 v88, v93, v88, -v94
	v_fmac_f32_e32 v88, v93, v85
	v_sub_f32_e32 v85, v96, v91
	v_add_f32_e32 v85, v89, v85
	v_add_f32_e32 v89, v94, v88
	v_sub_f32_e32 v95, v91, v89
	v_sub_f32_e32 v91, v91, v95
	v_sub_f32_e32 v94, v89, v94
	v_sub_f32_e32 v89, v91, v89
	v_add_f32_e32 v85, v85, v89
	v_sub_f32_e32 v88, v94, v88
	v_add_f32_e32 v85, v88, v85
	v_add_f32_e32 v88, v92, v93
	v_add_f32_e32 v85, v95, v85
	v_sub_f32_e32 v89, v88, v92
	v_mul_f32_e32 v85, v90, v85
	v_sub_f32_e32 v89, v93, v89
	v_add_f32_e32 v85, v89, v85
	v_mul_f32_e32 v92, 0x3f317218, v84
	v_add_f32_e32 v89, v88, v85
	v_fma_f32 v93, v84, s10, -v92
	v_mul_f32_e32 v90, v89, v89
	v_fmac_f32_e32 v93, 0xb102e308, v84
	v_sub_f32_e32 v84, v89, v88
	v_fmamk_f32 v91, v90, 0x3e9b6dac, v155
	v_sub_f32_e32 v84, v85, v84
	v_add_f32_e32 v85, v92, v93
	v_fmaak_f32 v91, v90, v91, 0x3f2aaada
	v_sub_f32_e32 v88, v85, v92
	v_ldexp_f32 v92, v89, 1
	v_mul_f32_e32 v89, v89, v90
	v_mul_f32_e32 v89, v89, v91
	v_add_f32_e32 v90, v92, v89
	v_sub_f32_e32 v91, v90, v92
	v_ldexp_f32 v84, v84, 1
	v_sub_f32_e32 v89, v89, v91
	v_add_f32_e32 v84, v84, v89
	v_add_f32_e32 v89, v90, v84
	v_sub_f32_e32 v90, v89, v90
	v_sub_f32_e32 v84, v84, v90
	v_add_f32_e32 v90, v85, v89
	v_sub_f32_e32 v91, v90, v85
	v_sub_f32_e32 v92, v90, v91
	v_sub_f32_e32 v88, v93, v88
	v_sub_f32_e32 v85, v85, v92
	v_sub_f32_e32 v89, v89, v91
	v_add_f32_e32 v85, v89, v85
	v_add_f32_e32 v89, v88, v84
	v_sub_f32_e32 v91, v89, v88
	v_sub_f32_e32 v92, v89, v91
	v_sub_f32_e32 v88, v88, v92
	v_sub_f32_e32 v84, v84, v91
	v_add_f32_e32 v85, v89, v85
	v_add_f32_e32 v84, v84, v88
	v_add_f32_e32 v88, v90, v85
	v_sub_f32_e32 v89, v88, v90
	v_sub_f32_e32 v85, v85, v89
	v_add_f32_e32 v84, v84, v85
	v_add_f32_e32 v84, v88, v84
	v_cndmask_b32_e32 v84, v179, v84, vcc
	v_cmp_ngt_f32_e32 vcc, -1.0, v87
	s_nop 1
	v_cndmask_b32_e32 v84, v180, v84, vcc
	v_cmp_neq_f32_e32 vcc, -1.0, v87
	s_nop 1
	v_cndmask_b32_e32 v84, v181, v84, vcc
	v_cmp_lt_f32_e64 vcc, |v87|, s50
	s_nop 1
	v_cndmask_b32_e32 v84, v84, v87, vcc
	v_sub_f32_e32 v84, v86, v84
	flat_store_dword v[82:83], v84
	v_add_f32_e32 v82, v19, v0
	v_min_f32_e32 v84, 0, v82
	v_mul_f32_e64 v82, |v82|, s6
	v_exp_f32_e32 v85, v82
	s_nop 0
	v_add_f32_e32 v86, 1.0, v85
	v_add_f32_e32 v82, -1.0, v86
	v_sub_f32_e32 v83, v82, v86
	v_add_f32_e32 v83, 1.0, v83
	v_sub_f32_e32 v82, v85, v82
	v_add_f32_e32 v87, v82, v83
	v_frexp_mant_f32_e32 v82, v86
	v_cmp_gt_f32_e32 vcc, s7, v82
	v_cvt_f64_f32_e32 v[82:83], v86
	v_frexp_exp_i32_f64_e32 v82, v[82:83]
	v_subbrev_co_u32_e32 v82, vcc, 0, v82, vcc
	v_sub_u32_e32 v83, 0, v82
	v_ldexp_f32 v86, v86, v83
	v_ldexp_f32 v83, v87, v83
	v_add_f32_e32 v87, -1.0, v86
	v_add_f32_e32 v88, 1.0, v87
	v_sub_f32_e32 v88, v86, v88
	v_add_f32_e32 v88, v83, v88
	v_add_f32_e32 v89, v87, v88
	v_sub_f32_e32 v87, v89, v87
	v_sub_f32_e32 v87, v88, v87
	v_add_f32_e32 v88, 1.0, v86
	v_add_f32_e32 v90, -1.0, v88
	v_sub_f32_e32 v86, v86, v90
	v_add_f32_e32 v83, v83, v86
	v_add_f32_e32 v86, v88, v83
	v_sub_f32_e32 v88, v86, v88
	v_sub_f32_e32 v83, v83, v88
	v_rcp_f32_e32 v88, v86
	v_cvt_f32_i32_e32 v82, v82
	v_cmp_neq_f32_e32 vcc, s11, v85
	v_mul_f32_e32 v90, v89, v88
	v_mul_f32_e32 v91, v86, v90
	v_fma_f32 v92, v90, v86, -v91
	v_fmac_f32_e32 v92, v90, v83
	v_add_f32_e32 v93, v91, v92
	v_sub_f32_e32 v94, v89, v93
	v_sub_f32_e32 v89, v89, v94
	v_sub_f32_e32 v91, v93, v91
	v_sub_f32_e32 v89, v89, v93
	v_add_f32_e32 v87, v87, v89
	v_sub_f32_e32 v89, v91, v92
	v_add_f32_e32 v87, v89, v87
	v_add_f32_e32 v89, v94, v87
	v_mul_f32_e32 v91, v88, v89
	v_mul_f32_e32 v92, v86, v91
	v_fma_f32 v86, v91, v86, -v92
	v_fmac_f32_e32 v86, v91, v83
	v_sub_f32_e32 v83, v94, v89
	v_add_f32_e32 v83, v87, v83
	v_add_f32_e32 v87, v92, v86
	v_sub_f32_e32 v93, v89, v87
	v_sub_f32_e32 v89, v89, v93
	v_sub_f32_e32 v92, v87, v92
	v_sub_f32_e32 v87, v89, v87
	v_add_f32_e32 v83, v83, v87
	v_sub_f32_e32 v86, v92, v86
	v_add_f32_e32 v83, v86, v83
	v_add_f32_e32 v86, v90, v91
	v_add_f32_e32 v83, v93, v83
	v_sub_f32_e32 v87, v86, v90
	v_mul_f32_e32 v83, v88, v83
	v_sub_f32_e32 v87, v91, v87
	v_add_f32_e32 v83, v87, v83
	v_mul_f32_e32 v90, 0x3f317218, v82
	v_add_f32_e32 v87, v86, v83
	v_fma_f32 v91, v82, s10, -v90
	v_mul_f32_e32 v88, v87, v87
	v_fmac_f32_e32 v91, 0xb102e308, v82
	v_sub_f32_e32 v82, v87, v86
	v_fmamk_f32 v89, v88, 0x3e9b6dac, v155
	v_sub_f32_e32 v82, v83, v82
	v_add_f32_e32 v83, v90, v91
; DEVI void epi_proj(const Params& p, int L, f32x4 (&acc)[4][4], int m0, int nt) {
;     ...
;       if (fr >= 8 && fr < 12) {
;         float* flog = (float*)(ws + OFF_FLOG);
;         const float bfh = p.in[11][L * 4 + (fr - 8)];
; #pragma unroll
;         for (int m = 0; m < 4; ++m)
; #pragma unroll
;           for (int j = 0; j < 4; ++j) {
;             const float x = acc[m][3][j] + bfh;
;             flog[(long)(mbase + m * 16 + fq * 4 + j) * 4 + (fr - 8)] = fminf(x, 0.f) - log1pf(__expf(-fabsf(x)));
	v_fmaak_f32 v89, v88, v89, 0x3f2aaada
	v_sub_f32_e32 v86, v83, v90
	v_ldexp_f32 v90, v87, 1
	v_mul_f32_e32 v87, v87, v88
	v_mul_f32_e32 v87, v87, v89
	v_add_f32_e32 v88, v90, v87
	v_sub_f32_e32 v89, v88, v90
	v_ldexp_f32 v82, v82, 1
	v_sub_f32_e32 v87, v87, v89
	v_add_f32_e32 v82, v82, v87
	v_add_f32_e32 v87, v88, v82
	v_sub_f32_e32 v88, v87, v88
	v_sub_f32_e32 v82, v82, v88
	v_add_f32_e32 v88, v83, v87
	v_sub_f32_e32 v89, v88, v83
	v_sub_f32_e32 v90, v88, v89
	v_sub_f32_e32 v86, v91, v86
	v_sub_f32_e32 v83, v83, v90
	v_sub_f32_e32 v87, v87, v89
	v_add_f32_e32 v83, v87, v83
	v_add_f32_e32 v87, v86, v82
	v_sub_f32_e32 v89, v87, v86
	v_sub_f32_e32 v90, v87, v89
	v_sub_f32_e32 v86, v86, v90
	v_sub_f32_e32 v82, v82, v89
	v_add_f32_e32 v83, v87, v83
	v_add_f32_e32 v82, v82, v86
	v_add_f32_e32 v86, v88, v83
	v_sub_f32_e32 v87, v86, v88
	v_sub_f32_e32 v83, v83, v87
	v_add_f32_e32 v82, v82, v83
	v_add_f32_e32 v82, v86, v82
	v_cndmask_b32_e32 v82, v179, v82, vcc
	v_cmp_ngt_f32_e32 vcc, -1.0, v85
	s_nop 1
	v_cndmask_b32_e32 v82, v180, v82, vcc
	v_cmp_neq_f32_e32 vcc, -1.0, v85
	s_nop 1
	v_cndmask_b32_e32 v82, v181, v82, vcc
	v_cmp_lt_f32_e64 vcc, |v85|, s50
	s_nop 1
	v_cndmask_b32_e32 v82, v82, v85, vcc
	v_sub_f32_e32 v82, v84, v82
	flat_store_dword v[80:81], v82
	v_add_f32_e32 v80, v20, v0
	v_min_f32_e32 v82, 0, v80
	v_mul_f32_e64 v80, |v80|, s6
	v_exp_f32_e32 v83, v80
	s_nop 0
	v_add_f32_e32 v84, 1.0, v83
	v_add_f32_e32 v80, -1.0, v84
	v_sub_f32_e32 v81, v80, v84
	v_add_f32_e32 v81, 1.0, v81
	v_sub_f32_e32 v80, v83, v80
	v_add_f32_e32 v85, v80, v81
	v_frexp_mant_f32_e32 v80, v84
	v_cmp_gt_f32_e32 vcc, s7, v80
	v_cvt_f64_f32_e32 v[80:81], v84
	v_frexp_exp_i32_f64_e32 v80, v[80:81]
	v_subbrev_co_u32_e32 v80, vcc, 0, v80, vcc
	v_sub_u32_e32 v81, 0, v80
	v_ldexp_f32 v84, v84, v81
	v_ldexp_f32 v81, v85, v81
	v_add_f32_e32 v85, -1.0, v84
	v_add_f32_e32 v86, 1.0, v85
	v_sub_f32_e32 v86, v84, v86
	v_add_f32_e32 v86, v81, v86
	v_add_f32_e32 v87, v85, v86
	v_sub_f32_e32 v85, v87, v85
	v_sub_f32_e32 v85, v86, v85
	v_add_f32_e32 v86, 1.0, v84
	v_add_f32_e32 v88, -1.0, v86
	v_sub_f32_e32 v84, v84, v88
	v_add_f32_e32 v81, v81, v84
	v_add_f32_e32 v84, v86, v81
	v_sub_f32_e32 v86, v84, v86
	v_sub_f32_e32 v81, v81, v86
	v_rcp_f32_e32 v86, v84
	v_cvt_f32_i32_e32 v80, v80
	v_cmp_neq_f32_e32 vcc, s11, v83
	v_mul_f32_e32 v88, v87, v86
	v_mul_f32_e32 v89, v84, v88
	v_fma_f32 v90, v88, v84, -v89
	v_fmac_f32_e32 v90, v88, v81
	v_add_f32_e32 v91, v89, v90
	v_sub_f32_e32 v92, v87, v91
	v_sub_f32_e32 v87, v87, v92
	v_sub_f32_e32 v89, v91, v89
	v_sub_f32_e32 v87, v87, v91
	v_add_f32_e32 v85, v85, v87
	v_sub_f32_e32 v87, v89, v90
	v_add_f32_e32 v85, v87, v85
	v_add_f32_e32 v87, v92, v85
	v_mul_f32_e32 v89, v86, v87
	v_mul_f32_e32 v90, v84, v89
	v_fma_f32 v84, v89, v84, -v90
	v_fmac_f32_e32 v84, v89, v81
	v_sub_f32_e32 v81, v92, v87
	v_add_f32_e32 v81, v85, v81
	v_add_f32_e32 v85, v90, v84
	v_sub_f32_e32 v91, v87, v85
	v_sub_f32_e32 v87, v87, v91
	v_sub_f32_e32 v90, v85, v90
	v_sub_f32_e32 v85, v87, v85
	v_add_f32_e32 v81, v81, v85
	v_sub_f32_e32 v84, v90, v84
	v_add_f32_e32 v81, v84, v81
	v_add_f32_e32 v84, v88, v89
	v_add_f32_e32 v81, v91, v81
	v_sub_f32_e32 v85, v84, v88
	v_mul_f32_e32 v81, v86, v81
	v_sub_f32_e32 v85, v89, v85
	v_add_f32_e32 v81, v85, v81
	v_mul_f32_e32 v88, 0x3f317218, v80
	v_add_f32_e32 v85, v84, v81
	v_fma_f32 v89, v80, s10, -v88
	v_mul_f32_e32 v86, v85, v85
	v_fmac_f32_e32 v89, 0xb102e308, v80
	v_sub_f32_e32 v80, v85, v84
	v_fmamk_f32 v87, v86, 0x3e9b6dac, v155
	v_sub_f32_e32 v80, v81, v80
	v_add_f32_e32 v81, v88, v89
	v_fmaak_f32 v87, v86, v87, 0x3f2aaada
	v_sub_f32_e32 v84, v81, v88
	v_ldexp_f32 v88, v85, 1
	v_mul_f32_e32 v85, v85, v86
	v_mul_f32_e32 v85, v85, v87
	v_add_f32_e32 v86, v88, v85
	v_sub_f32_e32 v87, v86, v88
	v_ldexp_f32 v80, v80, 1
	v_sub_f32_e32 v85, v85, v87
	v_add_f32_e32 v80, v80, v85
	v_add_f32_e32 v85, v86, v80
	v_sub_f32_e32 v86, v85, v86
	v_sub_f32_e32 v80, v80, v86
	v_add_f32_e32 v86, v81, v85
	v_sub_f32_e32 v87, v86, v81
	v_sub_f32_e32 v88, v86, v87
	v_sub_f32_e32 v84, v89, v84
	v_sub_f32_e32 v81, v81, v88
	v_sub_f32_e32 v85, v85, v87
	v_add_f32_e32 v81, v85, v81
	v_add_f32_e32 v85, v84, v80
	v_sub_f32_e32 v87, v85, v84
	v_sub_f32_e32 v88, v85, v87
	v_sub_f32_e32 v84, v84, v88
	v_sub_f32_e32 v80, v80, v87
	v_add_f32_e32 v81, v85, v81
	v_add_f32_e32 v80, v80, v84
	v_add_f32_e32 v84, v86, v81
	v_sub_f32_e32 v85, v84, v86
	v_sub_f32_e32 v81, v81, v85
	v_add_f32_e32 v80, v80, v81
	v_add_f32_e32 v80, v84, v80
	v_cndmask_b32_e32 v80, v179, v80, vcc
	v_cmp_ngt_f32_e32 vcc, -1.0, v83
	s_nop 1
	v_cndmask_b32_e32 v80, v180, v80, vcc
	v_cmp_neq_f32_e32 vcc, -1.0, v83
	s_nop 1
	v_cndmask_b32_e32 v80, v181, v80, vcc
	v_cmp_lt_f32_e64 vcc, |v83|, s50
	s_nop 1
	v_cndmask_b32_e32 v80, v80, v83, vcc
	v_sub_f32_e32 v80, v82, v80
	flat_store_dword v[78:79], v80
	v_add_f32_e32 v78, v21, v0
	v_min_f32_e32 v80, 0, v78
	v_mul_f32_e64 v78, |v78|, s6
	v_exp_f32_e32 v81, v78
	s_nop 0
	v_add_f32_e32 v82, 1.0, v81
	v_add_f32_e32 v78, -1.0, v82
	v_sub_f32_e32 v79, v78, v82
	v_add_f32_e32 v79, 1.0, v79
	v_sub_f32_e32 v78, v81, v78
	v_add_f32_e32 v83, v78, v79
	v_frexp_mant_f32_e32 v78, v82
	v_cmp_gt_f32_e32 vcc, s7, v78
	v_cvt_f64_f32_e32 v[78:79], v82
	v_frexp_exp_i32_f64_e32 v78, v[78:79]
	v_subbrev_co_u32_e32 v78, vcc, 0, v78, vcc
	v_sub_u32_e32 v79, 0, v78
	v_ldexp_f32 v82, v82, v79
	v_ldexp_f32 v79, v83, v79
	v_add_f32_e32 v83, -1.0, v82
	v_add_f32_e32 v84, 1.0, v83
	v_sub_f32_e32 v84, v82, v84
	v_add_f32_e32 v84, v79, v84
	v_add_f32_e32 v85, v83, v84
	v_sub_f32_e32 v83, v85, v83
	v_sub_f32_e32 v83, v84, v83
	v_add_f32_e32 v84, 1.0, v82
; DEVI void epi_proj(const Params& p, int L, f32x4 (&acc)[4][4], int m0, int nt) {
;     ...
;       if (fr >= 8 && fr < 12) {
;         float* flog = (float*)(ws + OFF_FLOG);
;         const float bfh = p.in[11][L * 4 + (fr - 8)];
; #pragma unroll
;         for (int m = 0; m < 4; ++m)
; #pragma unroll
;           for (int j = 0; j < 4; ++j) {
;             const float x = acc[m][3][j] + bfh;
;             flog[(long)(mbase + m * 16 + fq * 4 + j) * 4 + (fr - 8)] = fminf(x, 0.f) - log1pf(__expf(-fabsf(x)));
	v_add_f32_e32 v86, -1.0, v84
	v_sub_f32_e32 v82, v82, v86
	v_add_f32_e32 v79, v79, v82
	v_add_f32_e32 v82, v84, v79
	v_sub_f32_e32 v84, v82, v84
	v_sub_f32_e32 v79, v79, v84
	v_rcp_f32_e32 v84, v82
	v_cvt_f32_i32_e32 v78, v78
	v_cmp_neq_f32_e32 vcc, s11, v81
	v_mul_f32_e32 v86, v85, v84
	v_mul_f32_e32 v87, v82, v86
	v_fma_f32 v88, v86, v82, -v87
	v_fmac_f32_e32 v88, v86, v79
	v_add_f32_e32 v89, v87, v88
	v_sub_f32_e32 v90, v85, v89
	v_sub_f32_e32 v85, v85, v90
	v_sub_f32_e32 v87, v89, v87
	v_sub_f32_e32 v85, v85, v89
	v_add_f32_e32 v83, v83, v85
	v_sub_f32_e32 v85, v87, v88
	v_add_f32_e32 v83, v85, v83
	v_add_f32_e32 v85, v90, v83
	v_mul_f32_e32 v87, v84, v85
	v_mul_f32_e32 v88, v82, v87
	v_fma_f32 v82, v87, v82, -v88
	v_fmac_f32_e32 v82, v87, v79
	v_sub_f32_e32 v79, v90, v85
	v_add_f32_e32 v79, v83, v79
	v_add_f32_e32 v83, v88, v82
	v_sub_f32_e32 v89, v85, v83
	v_sub_f32_e32 v85, v85, v89
	v_sub_f32_e32 v88, v83, v88
	v_sub_f32_e32 v83, v85, v83
	v_add_f32_e32 v79, v79, v83
	v_sub_f32_e32 v82, v88, v82
	v_add_f32_e32 v79, v82, v79
	v_add_f32_e32 v82, v86, v87
	v_add_f32_e32 v79, v89, v79
	v_sub_f32_e32 v83, v82, v86
	v_mul_f32_e32 v79, v84, v79
	v_sub_f32_e32 v83, v87, v83
	v_add_f32_e32 v79, v83, v79
	v_mul_f32_e32 v86, 0x3f317218, v78
	v_add_f32_e32 v83, v82, v79
	v_fma_f32 v87, v78, s10, -v86
	v_mul_f32_e32 v84, v83, v83
	v_fmac_f32_e32 v87, 0xb102e308, v78
	v_sub_f32_e32 v78, v83, v82
	v_fmamk_f32 v85, v84, 0x3e9b6dac, v155
	v_sub_f32_e32 v78, v79, v78
	v_add_f32_e32 v79, v86, v87
	v_fmaak_f32 v85, v84, v85, 0x3f2aaada
	v_sub_f32_e32 v82, v79, v86
	v_ldexp_f32 v86, v83, 1
	v_mul_f32_e32 v83, v83, v84
	v_mul_f32_e32 v83, v83, v85
	v_add_f32_e32 v84, v86, v83
	v_sub_f32_e32 v85, v84, v86
	v_ldexp_f32 v78, v78, 1
	v_sub_f32_e32 v83, v83, v85
	v_add_f32_e32 v78, v78, v83
	v_add_f32_e32 v83, v84, v78
	v_sub_f32_e32 v84, v83, v84
	v_sub_f32_e32 v78, v78, v84
	v_add_f32_e32 v84, v79, v83
	v_sub_f32_e32 v85, v84, v79
	v_sub_f32_e32 v86, v84, v85
	v_sub_f32_e32 v82, v87, v82
	v_sub_f32_e32 v79, v79, v86
	v_sub_f32_e32 v83, v83, v85
	v_add_f32_e32 v79, v83, v79
	v_add_f32_e32 v83, v82, v78
	v_sub_f32_e32 v85, v83, v82
	v_sub_f32_e32 v86, v83, v85
	v_sub_f32_e32 v82, v82, v86
	v_sub_f32_e32 v78, v78, v85
	v_add_f32_e32 v79, v83, v79
	v_add_f32_e32 v78, v78, v82
	v_add_f32_e32 v82, v84, v79
	v_sub_f32_e32 v83, v82, v84
	v_sub_f32_e32 v79, v79, v83
	v_add_f32_e32 v78, v78, v79
	v_add_f32_e32 v78, v82, v78
	v_cndmask_b32_e32 v78, v179, v78, vcc
	v_cmp_ngt_f32_e32 vcc, -1.0, v81
	s_nop 1
	v_cndmask_b32_e32 v78, v180, v78, vcc
	v_cmp_neq_f32_e32 vcc, -1.0, v81
	s_nop 1
	v_cndmask_b32_e32 v78, v181, v78, vcc
	v_cmp_lt_f32_e64 vcc, |v81|, s50
	s_nop 1
	v_cndmask_b32_e32 v78, v78, v81, vcc
	v_sub_f32_e32 v78, v80, v78
	flat_store_dword v[76:77], v78
	v_add_f32_e32 v76, v2, v0
	v_min_f32_e32 v78, 0, v76
	v_mul_f32_e64 v76, |v76|, s6
	v_exp_f32_e32 v79, v76
	s_nop 0
	v_add_f32_e32 v80, 1.0, v79
	v_add_f32_e32 v76, -1.0, v80
	v_sub_f32_e32 v77, v76, v80
	v_add_f32_e32 v77, 1.0, v77
	v_sub_f32_e32 v76, v79, v76
	v_add_f32_e32 v81, v76, v77
	v_frexp_mant_f32_e32 v76, v80
	v_cmp_gt_f32_e32 vcc, s7, v76
	v_cvt_f64_f32_e32 v[76:77], v80
	v_frexp_exp_i32_f64_e32 v76, v[76:77]
	v_subbrev_co_u32_e32 v76, vcc, 0, v76, vcc
	v_sub_u32_e32 v77, 0, v76
	v_ldexp_f32 v80, v80, v77
	v_ldexp_f32 v77, v81, v77
	v_add_f32_e32 v81, -1.0, v80
	v_add_f32_e32 v82, 1.0, v81
	v_sub_f32_e32 v82, v80, v82
	v_add_f32_e32 v82, v77, v82
	v_add_f32_e32 v83, v81, v82
	v_sub_f32_e32 v81, v83, v81
	v_sub_f32_e32 v81, v82, v81
	v_add_f32_e32 v82, 1.0, v80
	v_add_f32_e32 v84, -1.0, v82
	v_sub_f32_e32 v80, v80, v84
	v_add_f32_e32 v77, v77, v80
	v_add_f32_e32 v80, v82, v77
	v_sub_f32_e32 v82, v80, v82
	v_sub_f32_e32 v77, v77, v82
	v_rcp_f32_e32 v82, v80
	v_cvt_f32_i32_e32 v76, v76
	v_cmp_neq_f32_e32 vcc, s11, v79
	v_mul_f32_e32 v84, v83, v82
	v_mul_f32_e32 v85, v80, v84
	v_fma_f32 v86, v84, v80, -v85
	v_fmac_f32_e32 v86, v84, v77
	v_add_f32_e32 v87, v85, v86
	v_sub_f32_e32 v88, v83, v87
	v_sub_f32_e32 v83, v83, v88
	v_sub_f32_e32 v85, v87, v85
	v_sub_f32_e32 v83, v83, v87
	v_add_f32_e32 v81, v81, v83
	v_sub_f32_e32 v83, v85, v86
	v_add_f32_e32 v81, v83, v81
	v_add_f32_e32 v83, v88, v81
	v_mul_f32_e32 v85, v82, v83
	v_mul_f32_e32 v86, v80, v85
	v_fma_f32 v80, v85, v80, -v86
	v_fmac_f32_e32 v80, v85, v77
	v_sub_f32_e32 v77, v88, v83
	v_add_f32_e32 v77, v81, v77
	v_add_f32_e32 v81, v86, v80
	v_sub_f32_e32 v87, v83, v81
	v_sub_f32_e32 v83, v83, v87
	v_sub_f32_e32 v86, v81, v86
	v_sub_f32_e32 v81, v83, v81
	v_add_f32_e32 v77, v77, v81
	v_sub_f32_e32 v80, v86, v80
	v_add_f32_e32 v77, v80, v77
	v_add_f32_e32 v80, v84, v85
	v_add_f32_e32 v77, v87, v77
	v_sub_f32_e32 v81, v80, v84
	v_mul_f32_e32 v77, v82, v77
	v_sub_f32_e32 v81, v85, v81
	v_add_f32_e32 v77, v81, v77
	v_mul_f32_e32 v84, 0x3f317218, v76
	v_add_f32_e32 v81, v80, v77
	v_fma_f32 v85, v76, s10, -v84
	v_mul_f32_e32 v82, v81, v81
	v_fmac_f32_e32 v85, 0xb102e308, v76
	v_sub_f32_e32 v76, v81, v80
	v_fmamk_f32 v83, v82, 0x3e9b6dac, v155
	v_sub_f32_e32 v76, v77, v76
	v_add_f32_e32 v77, v84, v85
	v_fmaak_f32 v83, v82, v83, 0x3f2aaada
	v_sub_f32_e32 v80, v77, v84
	v_ldexp_f32 v84, v81, 1
	v_mul_f32_e32 v81, v81, v82
	v_mul_f32_e32 v81, v81, v83
	v_add_f32_e32 v82, v84, v81
	v_sub_f32_e32 v83, v82, v84
	v_ldexp_f32 v76, v76, 1
	v_sub_f32_e32 v81, v81, v83
	v_add_f32_e32 v76, v76, v81
	v_add_f32_e32 v81, v82, v76
	v_sub_f32_e32 v82, v81, v82
	v_sub_f32_e32 v76, v76, v82
	v_add_f32_e32 v82, v77, v81
	v_sub_f32_e32 v83, v82, v77
	v_sub_f32_e32 v84, v82, v83
	v_sub_f32_e32 v80, v85, v80
	v_sub_f32_e32 v77, v77, v84
	v_sub_f32_e32 v81, v81, v83
; DEVI void epi_proj(const Params& p, int L, f32x4 (&acc)[4][4], int m0, int nt) {
;     ...
;       if (fr >= 8 && fr < 12) {
;         float* flog = (float*)(ws + OFF_FLOG);
;         const float bfh = p.in[11][L * 4 + (fr - 8)];
; #pragma unroll
;         for (int m = 0; m < 4; ++m)
; #pragma unroll
;           for (int j = 0; j < 4; ++j) {
;             const float x = acc[m][3][j] + bfh;
;             flog[(long)(mbase + m * 16 + fq * 4 + j) * 4 + (fr - 8)] = fminf(x, 0.f) - log1pf(__expf(-fabsf(x)));
	v_add_f32_e32 v77, v81, v77
	v_add_f32_e32 v81, v80, v76
	v_sub_f32_e32 v83, v81, v80
	v_sub_f32_e32 v84, v81, v83
	v_sub_f32_e32 v80, v80, v84
	v_sub_f32_e32 v76, v76, v83
	v_add_f32_e32 v77, v81, v77
	v_add_f32_e32 v76, v76, v80
	v_add_f32_e32 v80, v82, v77
	v_sub_f32_e32 v81, v80, v82
	v_sub_f32_e32 v77, v77, v81
	v_add_f32_e32 v76, v76, v77
	v_add_f32_e32 v76, v80, v76
	v_cndmask_b32_e32 v76, v179, v76, vcc
	v_cmp_ngt_f32_e32 vcc, -1.0, v79
	s_nop 1
	v_cndmask_b32_e32 v76, v180, v76, vcc
	v_cmp_neq_f32_e32 vcc, -1.0, v79
	s_nop 1
	v_cndmask_b32_e32 v76, v181, v76, vcc
	v_cmp_lt_f32_e64 vcc, |v79|, s50
	s_nop 1
	v_cndmask_b32_e32 v76, v76, v79, vcc
	v_sub_f32_e32 v76, v78, v76
	flat_store_dword v[74:75], v76
	v_add_f32_e32 v74, v3, v0
	v_min_f32_e32 v76, 0, v74
	v_mul_f32_e64 v74, |v74|, s6
	v_exp_f32_e32 v77, v74
	s_nop 0
	v_add_f32_e32 v78, 1.0, v77
	v_add_f32_e32 v74, -1.0, v78
	v_sub_f32_e32 v75, v74, v78
	v_add_f32_e32 v75, 1.0, v75
	v_sub_f32_e32 v74, v77, v74
	v_add_f32_e32 v79, v74, v75
	v_frexp_mant_f32_e32 v74, v78
	v_cmp_gt_f32_e32 vcc, s7, v74
	v_cvt_f64_f32_e32 v[74:75], v78
	v_frexp_exp_i32_f64_e32 v74, v[74:75]
	v_subbrev_co_u32_e32 v74, vcc, 0, v74, vcc
	v_sub_u32_e32 v75, 0, v74
	v_ldexp_f32 v78, v78, v75
	v_ldexp_f32 v75, v79, v75
	v_add_f32_e32 v79, -1.0, v78
	v_add_f32_e32 v80, 1.0, v79
	v_sub_f32_e32 v80, v78, v80
	v_add_f32_e32 v80, v75, v80
	v_add_f32_e32 v81, v79, v80
	v_sub_f32_e32 v79, v81, v79
	v_sub_f32_e32 v79, v80, v79
	v_add_f32_e32 v80, 1.0, v78
	v_add_f32_e32 v82, -1.0, v80
	v_sub_f32_e32 v78, v78, v82
	v_add_f32_e32 v75, v75, v78
	v_add_f32_e32 v78, v80, v75
	v_sub_f32_e32 v80, v78, v80
	v_sub_f32_e32 v75, v75, v80
	v_rcp_f32_e32 v80, v78
	v_cvt_f32_i32_e32 v74, v74
	v_cmp_neq_f32_e32 vcc, s11, v77
	v_mul_f32_e32 v82, v81, v80
	v_mul_f32_e32 v83, v78, v82
	v_fma_f32 v84, v82, v78, -v83
	v_fmac_f32_e32 v84, v82, v75
	v_add_f32_e32 v85, v83, v84
	v_sub_f32_e32 v86, v81, v85
	v_sub_f32_e32 v81, v81, v86
	v_sub_f32_e32 v83, v85, v83
	v_sub_f32_e32 v81, v81, v85
	v_add_f32_e32 v79, v79, v81
	v_sub_f32_e32 v81, v83, v84
	v_add_f32_e32 v79, v81, v79
	v_add_f32_e32 v81, v86, v79
	v_mul_f32_e32 v83, v80, v81
	v_mul_f32_e32 v84, v78, v83
	v_fma_f32 v78, v83, v78, -v84
	v_fmac_f32_e32 v78, v83, v75
	v_sub_f32_e32 v75, v86, v81
	v_add_f32_e32 v75, v79, v75
	v_add_f32_e32 v79, v84, v78
	v_sub_f32_e32 v85, v81, v79
	v_sub_f32_e32 v81, v81, v85
	v_sub_f32_e32 v84, v79, v84
	v_sub_f32_e32 v79, v81, v79
	v_add_f32_e32 v75, v75, v79
	v_sub_f32_e32 v78, v84, v78
	v_add_f32_e32 v75, v78, v75
	v_add_f32_e32 v78, v82, v83
	v_add_f32_e32 v75, v85, v75
	v_sub_f32_e32 v79, v78, v82
	v_mul_f32_e32 v75, v80, v75
	v_sub_f32_e32 v79, v83, v79
	v_add_f32_e32 v75, v79, v75
	v_mul_f32_e32 v82, 0x3f317218, v74
	v_add_f32_e32 v79, v78, v75
	v_fma_f32 v83, v74, s10, -v82
	v_mul_f32_e32 v80, v79, v79
	v_fmac_f32_e32 v83, 0xb102e308, v74
	v_sub_f32_e32 v74, v79, v78
	v_fmamk_f32 v81, v80, 0x3e9b6dac, v155
	v_sub_f32_e32 v74, v75, v74
	v_add_f32_e32 v75, v82, v83
	v_fmaak_f32 v81, v80, v81, 0x3f2aaada
	v_sub_f32_e32 v78, v75, v82
	v_ldexp_f32 v82, v79, 1
	v_mul_f32_e32 v79, v79, v80
	v_mul_f32_e32 v79, v79, v81
	v_add_f32_e32 v80, v82, v79
	v_sub_f32_e32 v81, v80, v82
	v_ldexp_f32 v74, v74, 1
	v_sub_f32_e32 v79, v79, v81
	v_add_f32_e32 v74, v74, v79
	v_add_f32_e32 v79, v80, v74
	v_sub_f32_e32 v80, v79, v80
	v_sub_f32_e32 v74, v74, v80
	v_add_f32_e32 v80, v75, v79
	v_sub_f32_e32 v81, v80, v75
	v_sub_f32_e32 v82, v80, v81
	v_sub_f32_e32 v78, v83, v78
	v_sub_f32_e32 v75, v75, v82
	v_sub_f32_e32 v79, v79, v81
	v_add_f32_e32 v75, v79, v75
	v_add_f32_e32 v79, v78, v74
	v_sub_f32_e32 v81, v79, v78
	v_sub_f32_e32 v82, v79, v81
	v_sub_f32_e32 v78, v78, v82
	v_sub_f32_e32 v74, v74, v81
	v_add_f32_e32 v75, v79, v75
	v_add_f32_e32 v74, v74, v78
	v_add_f32_e32 v78, v80, v75
	v_sub_f32_e32 v79, v78, v80
	v_sub_f32_e32 v75, v75, v79
	v_add_f32_e32 v74, v74, v75
	v_add_f32_e32 v74, v78, v74
	v_cndmask_b32_e32 v74, v179, v74, vcc
	v_cmp_ngt_f32_e32 vcc, -1.0, v77
	s_nop 1
	v_cndmask_b32_e32 v74, v180, v74, vcc
	v_cmp_neq_f32_e32 vcc, -1.0, v77
	s_nop 1
	v_cndmask_b32_e32 v74, v181, v74, vcc
	v_cmp_lt_f32_e64 vcc, |v77|, s50
	s_nop 1
	v_cndmask_b32_e32 v74, v74, v77, vcc
	v_sub_f32_e32 v74, v76, v74
	flat_store_dword v[72:73], v74
	v_add_f32_e32 v72, v4, v0
	v_min_f32_e32 v74, 0, v72
	v_mul_f32_e64 v72, |v72|, s6
	v_exp_f32_e32 v75, v72
	v_add_f32_e32 v0, v5, v0
	v_add_f32_e32 v76, 1.0, v75
	v_add_f32_e32 v72, -1.0, v76
	v_sub_f32_e32 v73, v72, v76
	v_add_f32_e32 v73, 1.0, v73
	v_sub_f32_e32 v72, v75, v72
	v_add_f32_e32 v77, v72, v73
	v_frexp_mant_f32_e32 v72, v76
	v_cmp_gt_f32_e32 vcc, s7, v72
	v_cvt_f64_f32_e32 v[72:73], v76
	v_frexp_exp_i32_f64_e32 v72, v[72:73]
	v_subbrev_co_u32_e32 v72, vcc, 0, v72, vcc
	v_sub_u32_e32 v73, 0, v72
	v_ldexp_f32 v76, v76, v73
	v_ldexp_f32 v73, v77, v73
	v_add_f32_e32 v77, -1.0, v76
	v_add_f32_e32 v78, 1.0, v77
	v_sub_f32_e32 v78, v76, v78
	v_add_f32_e32 v78, v73, v78
	v_add_f32_e32 v79, v77, v78
	v_sub_f32_e32 v77, v79, v77
	v_sub_f32_e32 v77, v78, v77
	v_add_f32_e32 v78, 1.0, v76
	v_add_f32_e32 v80, -1.0, v78
	v_sub_f32_e32 v76, v76, v80
	v_add_f32_e32 v73, v73, v76
	v_add_f32_e32 v76, v78, v73
	v_sub_f32_e32 v78, v76, v78
	v_sub_f32_e32 v73, v73, v78
	v_rcp_f32_e32 v78, v76
	v_cvt_f32_i32_e32 v72, v72
	v_cmp_neq_f32_e32 vcc, s11, v75
	v_mul_f32_e32 v80, v79, v78
	v_mul_f32_e32 v81, v76, v80
	v_fma_f32 v82, v80, v76, -v81
	v_fmac_f32_e32 v82, v80, v73
	v_add_f32_e32 v83, v81, v82
	v_sub_f32_e32 v84, v79, v83
	v_sub_f32_e32 v79, v79, v84
	v_sub_f32_e32 v81, v83, v81
	v_sub_f32_e32 v79, v79, v83
	v_add_f32_e32 v77, v77, v79
; DEVI void epi_proj(const Params& p, int L, f32x4 (&acc)[4][4], int m0, int nt) {
;     ...
;       if (fr >= 8 && fr < 12) {
;         float* flog = (float*)(ws + OFF_FLOG);
;         const float bfh = p.in[11][L * 4 + (fr - 8)];
; #pragma unroll
;         for (int m = 0; m < 4; ++m)
; #pragma unroll
;           for (int j = 0; j < 4; ++j) {
;             const float x = acc[m][3][j] + bfh;
;             flog[(long)(mbase + m * 16 + fq * 4 + j) * 4 + (fr - 8)] = fminf(x, 0.f) - log1pf(__expf(-fabsf(x)));
	v_sub_f32_e32 v79, v81, v82
	v_add_f32_e32 v77, v79, v77
	v_add_f32_e32 v79, v84, v77
	v_mul_f32_e32 v81, v78, v79
	v_mul_f32_e32 v82, v76, v81
	v_fma_f32 v76, v81, v76, -v82
	v_fmac_f32_e32 v76, v81, v73
	v_sub_f32_e32 v73, v84, v79
	v_add_f32_e32 v73, v77, v73
	v_add_f32_e32 v77, v82, v76
	v_sub_f32_e32 v83, v79, v77
	v_sub_f32_e32 v79, v79, v83
	v_sub_f32_e32 v82, v77, v82
	v_sub_f32_e32 v77, v79, v77
	v_add_f32_e32 v73, v73, v77
	v_sub_f32_e32 v76, v82, v76
	v_add_f32_e32 v73, v76, v73
	v_add_f32_e32 v76, v80, v81
	v_add_f32_e32 v73, v83, v73
	v_sub_f32_e32 v77, v76, v80
	v_mul_f32_e32 v73, v78, v73
	v_sub_f32_e32 v77, v81, v77
	v_add_f32_e32 v73, v77, v73
	v_mul_f32_e32 v80, 0x3f317218, v72
	v_add_f32_e32 v77, v76, v73
	v_fma_f32 v81, v72, s10, -v80
	v_mul_f32_e32 v78, v77, v77
	v_fmac_f32_e32 v81, 0xb102e308, v72
	v_sub_f32_e32 v72, v77, v76
	v_fmamk_f32 v79, v78, 0x3e9b6dac, v155
	v_sub_f32_e32 v72, v73, v72
	v_add_f32_e32 v73, v80, v81
	v_fmaak_f32 v79, v78, v79, 0x3f2aaada
	v_sub_f32_e32 v76, v73, v80
	v_ldexp_f32 v80, v77, 1
	v_mul_f32_e32 v77, v77, v78
	v_mul_f32_e32 v77, v77, v79
	v_add_f32_e32 v78, v80, v77
	v_sub_f32_e32 v79, v78, v80
	v_ldexp_f32 v72, v72, 1
	v_sub_f32_e32 v77, v77, v79
	v_add_f32_e32 v72, v72, v77
	v_add_f32_e32 v77, v78, v72
	v_sub_f32_e32 v78, v77, v78
	v_sub_f32_e32 v72, v72, v78
	v_add_f32_e32 v78, v73, v77
	v_sub_f32_e32 v79, v78, v73
	v_sub_f32_e32 v80, v78, v79
	v_sub_f32_e32 v76, v81, v76
	v_sub_f32_e32 v73, v73, v80
	v_sub_f32_e32 v77, v77, v79
	v_add_f32_e32 v73, v77, v73
	v_add_f32_e32 v77, v76, v72
	v_sub_f32_e32 v79, v77, v76
	v_sub_f32_e32 v80, v77, v79
	v_sub_f32_e32 v76, v76, v80
	v_sub_f32_e32 v72, v72, v79
	v_add_f32_e32 v73, v77, v73
	v_add_f32_e32 v72, v72, v76
	v_add_f32_e32 v76, v78, v73
	v_sub_f32_e32 v77, v76, v78
	v_sub_f32_e32 v73, v73, v77
	v_add_f32_e32 v72, v72, v73
	v_add_f32_e32 v72, v76, v72
	v_cndmask_b32_e32 v72, v179, v72, vcc
	v_cmp_ngt_f32_e32 vcc, -1.0, v75
	s_nop 1
	v_cndmask_b32_e32 v72, v180, v72, vcc
	v_cmp_neq_f32_e32 vcc, -1.0, v75
	s_nop 1
	v_cndmask_b32_e32 v72, v181, v72, vcc
	v_cmp_lt_f32_e64 vcc, |v75|, s50
	s_nop 1
	v_cndmask_b32_e32 v72, v72, v75, vcc
	v_sub_f32_e32 v72, v74, v72
	flat_store_dword v[70:71], v72
	v_min_f32_e32 v72, 0, v0
	v_mul_f32_e64 v0, |v0|, s6
	v_exp_f32_e32 v0, v0
	s_nop 0
	v_add_f32_e32 v73, 1.0, v0
	v_add_f32_e32 v70, -1.0, v73
	v_sub_f32_e32 v71, v70, v73
	v_add_f32_e32 v71, 1.0, v71
	v_sub_f32_e32 v70, v0, v70
	v_add_f32_e32 v74, v70, v71
	v_frexp_mant_f32_e32 v70, v73
	v_cmp_gt_f32_e32 vcc, s7, v70
	v_cvt_f64_f32_e32 v[70:71], v73
	v_frexp_exp_i32_f64_e32 v70, v[70:71]
	v_subbrev_co_u32_e32 v70, vcc, 0, v70, vcc
	v_sub_u32_e32 v71, 0, v70
	v_ldexp_f32 v73, v73, v71
	v_ldexp_f32 v71, v74, v71
	v_add_f32_e32 v74, -1.0, v73
	v_add_f32_e32 v75, 1.0, v74
	v_sub_f32_e32 v75, v73, v75
	v_add_f32_e32 v75, v71, v75
	v_add_f32_e32 v76, v74, v75
	v_sub_f32_e32 v74, v76, v74
	v_sub_f32_e32 v74, v75, v74
	v_add_f32_e32 v75, 1.0, v73
	v_add_f32_e32 v77, -1.0, v75
	v_sub_f32_e32 v73, v73, v77
	v_add_f32_e32 v71, v71, v73
	v_add_f32_e32 v73, v75, v71
	v_sub_f32_e32 v75, v73, v75
	v_sub_f32_e32 v71, v71, v75
	v_rcp_f32_e32 v75, v73
	v_cvt_f32_i32_e32 v70, v70
	v_cmp_neq_f32_e32 vcc, s11, v0
	v_mul_f32_e32 v77, v76, v75
	v_mul_f32_e32 v78, v73, v77
	v_fma_f32 v79, v77, v73, -v78
	v_fmac_f32_e32 v79, v77, v71
	v_add_f32_e32 v80, v78, v79
	v_sub_f32_e32 v81, v76, v80
	v_sub_f32_e32 v76, v76, v81
	v_sub_f32_e32 v78, v80, v78
	v_sub_f32_e32 v76, v76, v80
	v_add_f32_e32 v74, v74, v76
	v_sub_f32_e32 v76, v78, v79
	v_add_f32_e32 v74, v76, v74
	v_add_f32_e32 v76, v81, v74
	v_mul_f32_e32 v78, v75, v76
	v_mul_f32_e32 v79, v73, v78
	v_fma_f32 v73, v78, v73, -v79
	v_fmac_f32_e32 v73, v78, v71
	v_sub_f32_e32 v71, v81, v76
	v_add_f32_e32 v71, v74, v71
	v_add_f32_e32 v74, v79, v73
	v_sub_f32_e32 v80, v76, v74
	v_sub_f32_e32 v76, v76, v80
	v_sub_f32_e32 v79, v74, v79
	v_sub_f32_e32 v74, v76, v74
	v_add_f32_e32 v71, v71, v74
	v_sub_f32_e32 v73, v79, v73
	v_add_f32_e32 v71, v73, v71
	v_add_f32_e32 v73, v77, v78
	v_add_f32_e32 v71, v80, v71
	v_sub_f32_e32 v74, v73, v77
	v_mul_f32_e32 v71, v75, v71
	v_sub_f32_e32 v74, v78, v74
	v_add_f32_e32 v71, v74, v71
	v_mul_f32_e32 v77, 0x3f317218, v70
	v_add_f32_e32 v74, v73, v71
	v_fma_f32 v78, v70, s10, -v77
	v_mul_f32_e32 v75, v74, v74
	v_fmac_f32_e32 v78, 0xb102e308, v70
	v_sub_f32_e32 v70, v74, v73
	v_fmamk_f32 v76, v75, 0x3e9b6dac, v155
	v_sub_f32_e32 v70, v71, v70
	v_add_f32_e32 v71, v77, v78
	v_fmaak_f32 v76, v75, v76, 0x3f2aaada
	v_sub_f32_e32 v73, v71, v77
	v_ldexp_f32 v77, v74, 1
	v_mul_f32_e32 v74, v74, v75
	v_mul_f32_e32 v74, v74, v76
	v_add_f32_e32 v75, v77, v74
	v_sub_f32_e32 v76, v75, v77
	v_ldexp_f32 v70, v70, 1
	v_sub_f32_e32 v74, v74, v76
	v_add_f32_e32 v70, v70, v74
	v_add_f32_e32 v74, v75, v70
	v_sub_f32_e32 v75, v74, v75
	v_sub_f32_e32 v70, v70, v75
	v_add_f32_e32 v75, v71, v74
	v_sub_f32_e32 v76, v75, v71
	v_sub_f32_e32 v77, v75, v76
	v_sub_f32_e32 v73, v78, v73
	v_sub_f32_e32 v71, v71, v77
	v_sub_f32_e32 v74, v74, v76
	v_add_f32_e32 v71, v74, v71
	v_add_f32_e32 v74, v73, v70
	v_sub_f32_e32 v76, v74, v73
	v_sub_f32_e32 v77, v74, v76
	v_sub_f32_e32 v73, v73, v77
	v_sub_f32_e32 v70, v70, v76
	v_add_f32_e32 v71, v74, v71
	v_add_f32_e32 v70, v70, v73
	v_add_f32_e32 v73, v75, v71
	v_sub_f32_e32 v74, v73, v75
	v_sub_f32_e32 v71, v71, v74
	v_add_f32_e32 v70, v70, v71
	v_add_f32_e32 v70, v73, v70
	v_cndmask_b32_e32 v70, v179, v70, vcc
	v_cmp_ngt_f32_e32 vcc, -1.0, v0
	s_nop 1
	v_cndmask_b32_e32 v70, v180, v70, vcc
	v_cmp_neq_f32_e32 vcc, -1.0, v0
	s_nop 1
	v_cndmask_b32_e32 v70, v181, v70, vcc
	v_cmp_lt_f32_e64 vcc, |v0|, s50
	s_nop 1
	v_cndmask_b32_e32 v0, v70, v0, vcc
	v_sub_f32_e32 v0, v72, v0
	flat_store_dword v[66:67], v0

; DEVI void nsa_item(const Params& p, int b, int g, int t0, char* smem) {
;     ...
;   bf16* ocat = (bf16*)(ws + OFF_OCAT);
; #pragma unroll
;   for (int rb = 0; rb < 2; ++rb)
; #pragma unroll
;     for (int db = 0; db < 4; ++db) {
;       const f32x4 tv = totl[(rb * 4 + db) * 256];
;       u32x2 v; v[0] = pack2(tv[0], tv[1]); v[1] = pack2(tv[2], tv[3]);
;       *(u32x2*)(ocat + ((long)b * 4096 + t[rb]) * 1024 + h * 64 + db * 16 + fq * 4) = v;
;     }
.LBB0_510:
	s_or_b64 exec, exec, s[6:7]
	s_mov_b64 s[6:7], 0x10ebc000
	v_mov_b32_e32 v3, 0
	v_lshlrev_b32_e32 v2, 1, v97
	v_lshl_add_u64 v[6:7], s[50:51], 0, v[2:3]
	v_lshlrev_b32_e32 v2, 1, v137
	v_lshl_add_u64 v[6:7], v[6:7], 0, v[2:3]
	v_lshl_add_u64 v[6:7], v[6:7], 0, s[6:7]
	v_lshlrev_b64 v[8:9], 11, v[94:95]
	v_lshl_add_u64 v[8:9], v[6:7], 0, v[8:9]
	v_cvt_pk_bf16_f32 v236, v236, v237
	v_cvt_pk_bf16_f32 v237, v238, v239
	flat_store_dwordx2 v[8:9], v[236:237]
	v_cvt_pk_bf16_f32 v232, v232, v233
	v_cvt_pk_bf16_f32 v233, v234, v235
	flat_store_dwordx2 v[8:9], v[232:233] offset:32
	v_cvt_pk_bf16_f32 v240, v240, v241
	v_cvt_pk_bf16_f32 v241, v242, v243
	flat_store_dwordx2 v[8:9], v[240:241] offset:64
	v_cvt_pk_bf16_f32 v244, v244, v245
	v_cvt_pk_bf16_f32 v245, v246, v247
	flat_store_dwordx2 v[8:9], v[244:245] offset:96
	s_nop 1
	flat_load_dwordx4 v[232:235], v[106:107]
	flat_load_dwordx4 v[236:239], v[108:109]
	flat_load_dwordx4 v[240:243], v[110:111]
	flat_load_dwordx4 v[244:247], v[112:113]
	v_lshlrev_b64 v[2:3], 11, v[92:93]
	v_lshl_add_u64 v[6:7], v[6:7], 0, v[2:3]
	s_waitcnt vmcnt(0) lgkmcnt(0)
	v_pk_fma_f32 v[234:235], v[34:35], v[0:1], v[234:235] op_sel_hi:[1,0,1]
	v_pk_fma_f32 v[232:233], v[32:33], v[0:1], v[232:233] op_sel_hi:[1,0,1]
	v_pk_fma_f32 v[238:239], v[42:43], v[0:1], v[238:239] op_sel_hi:[1,0,1]
	v_pk_fma_f32 v[236:237], v[40:41], v[0:1], v[236:237] op_sel_hi:[1,0,1]
	v_pk_fma_f32 v[242:243], v[38:39], v[0:1], v[242:243] op_sel_hi:[1,0,1]
	v_pk_fma_f32 v[240:241], v[36:37], v[0:1], v[240:241] op_sel_hi:[1,0,1]
	v_pk_fma_f32 v[246:247], v[30:31], v[0:1], v[246:247] op_sel_hi:[1,0,1]
	v_pk_fma_f32 v[244:245], v[28:29], v[0:1], v[244:245] op_sel_hi:[1,0,1]
	v_cvt_pk_bf16_f32 v232, v232, v233
	v_cvt_pk_bf16_f32 v233, v234, v235
	flat_store_dwordx2 v[6:7], v[232:233]
	v_cvt_pk_bf16_f32 v236, v236, v237
	v_cvt_pk_bf16_f32 v237, v238, v239
	flat_store_dwordx2 v[6:7], v[236:237] offset:32
	v_cvt_pk_bf16_f32 v240, v240, v241
	v_cvt_pk_bf16_f32 v241, v242, v243
	flat_store_dwordx2 v[6:7], v[240:241] offset:64
	v_cvt_pk_bf16_f32 v2, v244, v245
	v_mov_b32_e32 v4, v246
	v_mov_b32_e32 v5, v247

.LBB0_1192:
	flat_load_dwordx4 v[232:235], v[114:115]
	flat_load_dwordx4 v[236:239], v[100:101]
	flat_load_dwordx4 v[240:243], v[102:103]
	flat_load_dwordx4 v[244:247], v[104:105]
	v_mov_b32_e32 v0, 0
	v_cmp_lt_f32_e32 vcc, 0, v36
	v_mov_b32_e32 v2, 0
	s_and_saveexec_b64 s[6:7], vcc
	s_cbranch_execz .LBB0_1194
	flat_load_dword v2, v[116:117] offset:4
	s_waitcnt vmcnt(0) lgkmcnt(0)
	v_div_scale_f32 v3, s[8:9], v36, v36, v2
	v_rcp_f32_e32 v21, v3
	v_div_scale_f32 v22, vcc, v2, v36, v2
	v_fma_f32 v23, -v3, v21, 1.0
	v_fmac_f32_e32 v21, v23, v21
	v_mul_f32_e32 v23, v22, v21
	v_fma_f32 v37, -v3, v23, v22
	v_fmac_f32_e32 v23, v37, v21
	v_fma_f32 v3, -v3, v23, v22
	v_div_fmas_f32 v3, v3, v21, v23
	v_div_fixup_f32 v2, v3, v36, v2
.LBB0_1194:
	s_or_b64 exec, exec, s[6:7]
	v_cmp_lt_f32_e32 vcc, 0, v20
	s_waitcnt vmcnt(0) lgkmcnt(0)
	v_pk_fma_f32 v[234:235], v[58:59], v[2:3], v[234:235] op_sel_hi:[1,0,1]
	v_pk_fma_f32 v[232:233], v[56:57], v[2:3], v[232:233] op_sel_hi:[1,0,1]
	flat_store_dwordx4 v[114:115], v[232:235]
	v_pk_fma_f32 v[238:239], v[54:55], v[2:3], v[238:239] op_sel_hi:[1,0,1]
	v_pk_fma_f32 v[236:237], v[52:53], v[2:3], v[236:237] op_sel_hi:[1,0,1]
	flat_store_dwordx4 v[100:101], v[236:239]
	v_pk_fma_f32 v[242:243], v[50:51], v[2:3], v[242:243] op_sel_hi:[1,0,1]
	v_pk_fma_f32 v[240:241], v[48:49], v[2:3], v[240:241] op_sel_hi:[1,0,1]
	flat_store_dwordx4 v[102:103], v[240:243]
	v_pk_fma_f32 v[246:247], v[46:47], v[2:3], v[246:247] op_sel_hi:[1,0,1]
	v_pk_fma_f32 v[244:245], v[44:45], v[2:3], v[244:245] op_sel_hi:[1,0,1]
	flat_store_dwordx4 v[104:105], v[244:247]
	s_nop 1
	flat_load_dwordx4 v[232:235], v[106:107]
	flat_load_dwordx4 v[236:239], v[108:109]
	flat_load_dwordx4 v[240:243], v[110:111]
	flat_load_dwordx4 v[244:247], v[112:113]
	s_and_saveexec_b64 s[6:7], vcc
	s_cbranch_execz .LBB0_1196
	flat_load_dword v0, v[118:119] offset:4
	s_waitcnt vmcnt(0) lgkmcnt(0)
	v_div_scale_f32 v2, s[8:9], v20, v20, v0
	v_rcp_f32_e32 v3, v2
	v_div_scale_f32 v21, vcc, v0, v20, v0
	v_fma_f32 v22, -v2, v3, 1.0
	v_fmac_f32_e32 v3, v22, v3
	v_mul_f32_e32 v22, v21, v3
	v_fma_f32 v23, -v2, v22, v21
	v_fmac_f32_e32 v22, v23, v3
	v_fma_f32 v2, -v2, v22, v21
	v_div_fmas_f32 v2, v2, v3, v22
	v_div_fixup_f32 v0, v2, v20, v0
; DEVI void nsa_item(const Params& p, int b, int g, int t0, char* smem) {
;     ...
;   {
;     const int lo = (t0 >= 511 ? t0 - 511 : 0) >> 6, hi = (t0 + 31) >> 6;
;     const u64 wt = ((hi == 63) ? ~0ull : ((1ull << (hi + 1)) - 1)) & ~((1ull << lo) - 1);
;     const bf16* kb_ = proj + (long)b * 4096 * PROJ_LD + 1024 + g * 64;
;     const bf16* vwt = (const bf16*)(ws + OFF_VWT) + (long)(b * 2 + g) * 64 * 4096;
;     auto kpw = [&](int tile, int row) { return kb_ + (long)(tile * 64 + row) * PROJ_LD; };
;     auto vpw = [&](int tile, int d) { return vwt + (long)d * 4096 + tile * 64; };
;     auto sfw = [&](int rb, int kb, int j, int tile, float s) {
;       int dist = t[rb] - (tile * 64 + kb * 16 + fq * 4 + j);
;       int di = min(max(dist, 0), 127);
;       bool ok = dist >= 0 && dist < 512;
;       return ok ? fmaf(s, sc, lutr[di]) : -INFINITY;
;     };
;     const float cbf = lutr[127];
;     auto ffw = make_fast(sc, [=](int rb, int tile) { return cbf; });
;     auto clw = [&](int rb, int tile) {
;       const int tm = rb ? tmin1 : tmin0;
;       return (tm - (tile * 64 + 63) >= 113 && tm + 3 - tile * 64 < 512) ? 2 : 1;
;     };
;     RESET_STATE
;     attn_run<64, 0, false, false>(wt, wt, qf, kpw, vpw, NoCum{}, sfw, ffw, clw, NoPost{}, m, l, o, smem, curslot);
.LBB0_1196:
	s_or_b64 exec, exec, s[6:7]
	v_mov_b32_e32 v60, v154
	s_waitcnt vmcnt(0) lgkmcnt(0)
	v_pk_fma_f32 v[234:235], v[42:43], v[0:1], v[234:235] op_sel_hi:[1,0,1]
	v_pk_fma_f32 v[232:233], v[40:41], v[0:1], v[232:233] op_sel_hi:[1,0,1]
	flat_store_dwordx4 v[106:107], v[232:235]
	v_pk_fma_f32 v[238:239], v[34:35], v[0:1], v[238:239] op_sel_hi:[1,0,1]
	v_pk_fma_f32 v[236:237], v[32:33], v[0:1], v[236:237] op_sel_hi:[1,0,1]
	flat_store_dwordx4 v[108:109], v[236:239]
	v_pk_fma_f32 v[242:243], v[30:31], v[0:1], v[242:243] op_sel_hi:[1,0,1]
	v_pk_fma_f32 v[240:241], v[28:29], v[0:1], v[240:241] op_sel_hi:[1,0,1]
	flat_store_dwordx4 v[110:111], v[240:243]
	v_pk_fma_f32 v[246:247], v[26:27], v[0:1], v[246:247] op_sel_hi:[1,0,1]
	v_pk_fma_f32 v[244:245], v[24:25], v[0:1], v[244:245] op_sel_hi:[1,0,1]
	flat_store_dwordx4 v[112:113], v[244:247]
	v_sub_u32_e64 v0, v136, s78 clamp
	v_lshrrev_b32_e32 v0, 6, v0
	v_lshrrev_b32_e32 v20, 6, v136
	v_add_u32_e32 v2, 1, v20
	v_lshlrev_b64 v[2:3], v2, -1
	v_not_b32_e32 v21, v3
	v_not_b32_e32 v22, v2
	ds_read_b32 v136, v99 offset:508
	v_cmp_ne_u32_e32 vcc, 63, v20
	v_lshlrev_b64 v[2:3], v0, -1
	s_nop 0
	v_cndmask_b32_e32 v0, -1, v21, vcc
	v_cndmask_b32_e32 v20, -1, v22, vcc
	v_and_b32_e32 v121, v0, v3
	v_and_b32_e32 v120, v20, v2
	v_mov_b32_e32 v2, v1
	v_mov_b32_e32 v3, v1
	v_mov_b32_e32 v0, v1
	v_mov_b64_e32 v[22:23], v[2:3]
	v_mov_b64_e32 v[26:27], v[2:3]
	v_mov_b64_e32 v[54:55], v[2:3]
	v_mov_b64_e32 v[34:35], v[2:3]
	v_mov_b64_e32 v[50:51], v[2:3]
	v_mov_b64_e32 v[42:43], v[2:3]
	v_mov_b64_e32 v[58:59], v[2:3]
	v_mov_b64_e32 v[38:39], v[2:3]
	v_mov_b64_e32 v[46:47], v[2:3]
	v_mov_b64_e32 v[30:31], v[2:3]
	v_cmp_ne_u64_e32 vcc, 0, v[120:121]
	v_mov_b64_e32 v[20:21], v[0:1]
	v_mov_b64_e32 v[24:25], v[0:1]
	v_mov_b64_e32 v[52:53], v[0:1]
	v_mov_b64_e32 v[32:33], v[0:1]
	v_mov_b64_e32 v[48:49], v[0:1]
	v_mov_b64_e32 v[40:41], v[0:1]
	v_mov_b64_e32 v[56:57], v[0:1]
	v_mov_b64_e32 v[36:37], v[0:1]
	v_mov_b64_e32 v[44:45], v[0:1]
	v_mov_b64_e32 v[28:29], v[0:1]
	s_and_saveexec_b64 s[8:9], vcc
	s_cbranch_execz .LBB0_1372
	v_mov_b32_e32 v79, v1
	v_lshl_add_u64 v[2:3], s[50:51], 0, v[78:79]
	s_mov_b64 s[6:7], 0x196bc000
	v_ffbl_b32_e32 v0, v121
	v_lshl_add_u64 v[24:25], v[2:3], 0, s[6:7]
	v_add_u32_e32 v0, 32, v0
	v_ffbl_b32_e32 v2, v120
	v_min_u32_e32 v213, v2, v0
	v_ashrrev_i32_e32 v2, 31, v60
	v_lshrrev_b32_e32 v2, 29, v2
	v_add_u32_e32 v2, v60, v2
	v_ashrrev_i32_e32 v138, 3, v2
	v_and_b32_e32 v2, 0x1ffffff8, v2
	v_sub_u32_e32 v2, v60, v2
	v_lshlrev_b32_e32 v0, 6, v213
	v_bitop3_b32 v2, v2, v138, 7 bitop3:0x78
	v_add_u32_e32 v3, v138, v0
	v_lshlrev_b32_e32 v2, 3, v2
	v_mad_i64_i32 v[20:21], s[6:7], v3, s48, v[76:77]
	v_ashrrev_i32_e32 v3, 31, v2
	v_lshlrev_b32_e32 v139, 4, v60
	v_lshl_add_u64 v[20:21], v[2:3], 1, v[20:21]
	v_readfirstlane_b32 s6, v139
	v_lshl_add_u64 v[20:21], v[20:21], 0, s[44:45]
	s_mov_b32 m0, s6
	v_add_u32_e32 v32, 0x100, v60
	s_waitcnt lgkmcnt(0)
	s_barrier
	global_load_lds_dwordx4 v[20:21], off
	v_ashrrev_i32_e32 v20, 31, v32
	v_lshrrev_b32_e32 v20, 29, v20
	v_add_u32_e32 v20, v32, v20
	v_ashrrev_i32_e32 v140, 3, v20
	v_and_b32_e32 v20, 0x1ffffff8, v20
	v_sub_u32_e32 v20, v32, v20
	v_bitop3_b32 v20, v20, v140, 7 bitop3:0x78
	v_add_u32_e32 v0, v140, v0
	v_lshlrev_b32_e32 v20, 3, v20
	v_mad_i64_i32 v[22:23], s[6:7], v0, s48, v[76:77]
	v_ashrrev_i32_e32 v21, 31, v20
	v_lshlrev_b32_e32 v141, 4, v32
	v_lshl_add_u64 v[22:23], v[20:21], 1, v[22:23]
	v_readfirstlane_b32 s6, v141
	v_ashrrev_i32_e32 v28, 3, v60
	v_lshl_add_u64 v[22:23], v[22:23], 0, s[44:45]
	s_mov_b32 m0, s6
	v_ashrrev_i32_e32 v29, 31, v28
	v_xor_b32_e32 v0, v28, v60
	global_load_lds_dwordx4 v[22:23], off
	v_lshlrev_b64 v[22:23], 13, v[28:29]
	v_lshlrev_b32_e32 v0, 3, v0
	v_lshlrev_b32_e32 v26, 7, v213
	v_mov_b32_e32 v27, v1
	v_lshl_add_u64 v[22:23], v[24:25], 0, v[22:23]
	v_and_b32_e32 v0, 56, v0
	v_lshl_add_u64 v[30:31], v[22:23], 0, v[26:27]
	v_lshlrev_b32_e32 v0, 1, v0
	v_lshl_add_u64 v[28:29], v[30:31], 0, v[0:1]
	v_add_u32_e32 v30, 0x2000, v139
	s_nop 0
	v_readfirstlane_b32 s6, v30
	s_mov_b32 m0, s6
	s_nop 0
	global_load_lds_dwordx4 v[28:29], off
	v_ashrrev_i32_e32 v28, 3, v32
	v_ashrrev_i32_e32 v29, 31, v28
	v_lshlrev_b64 v[30:31], 13, v[28:29]
	v_lshl_add_u64 v[24:25], v[24:25], 0, v[30:31]
	v_lshl_add_u64 v[30:31], v[24:25], 0, v[26:27]
	v_xor_b32_e32 v26, v28, v60
	v_lshlrev_b32_e32 v26, 3, v26
	v_and_b32_e32 v26, 56, v26
	v_lshlrev_b32_e32 v26, 1, v26
	v_lshl_add_u64 v[28:29], v[30:31], 0, v[26:27]
	v_add_u32_e32 v30, 0x2000, v141
	s_nop 0
	v_readfirstlane_b32 s6, v30
	s_mov_b32 m0, s6
	s_nop 0
	global_load_lds_dwordx4 v[28:29], off
	v_lshl_add_u64 v[28:29], v[120:121], 0, -1
	v_and_b32_e32 v29, v29, v121
	v_and_b32_e32 v28, v28, v120
	v_ffbl_b32_e32 v30, v29
	v_add_u32_e32 v30, 32, v30
	v_ffbl_b32_e32 v31, v28
	v_min_u32_e32 v30, v31, v30
	v_cmp_ne_u64_e32 vcc, 0, v[28:29]
	s_nop 1
	v_cndmask_b32_e32 v212, -1, v30, vcc
	v_cmp_lt_i32_e32 vcc, -1, v212
	s_and_saveexec_b64 s[36:37], vcc
	s_cbranch_execz .LBB0_1199
	v_lshlrev_b32_e32 v32, 6, v212
	v_add_u32_e32 v30, v138, v32
	v_mad_i64_i32 v[30:31], s[6:7], v30, s48, v[76:77]
	v_add_u32_e32 v33, 0x4100, v139
	v_lshl_add_u64 v[30:31], v[2:3], 1, v[30:31]
	v_readfirstlane_b32 s6, v33
	v_lshl_add_u64 v[30:31], v[30:31], 0, s[44:45]
	s_mov_b32 m0, s6
	v_add_u32_e32 v34, 0x6100, v139
	global_load_lds_dwordx4 v[30:31], off
	v_add_u32_e32 v30, v140, v32
	v_mad_i64_i32 v[30:31], s[6:7], v30, s48, v[76:77]
	v_add_u32_e32 v32, 0x4100, v141
	v_lshl_add_u64 v[30:31], v[20:21], 1, v[30:31]
	v_readfirstlane_b32 s6, v32
	v_lshl_add_u64 v[30:31], v[30:31], 0, s[44:45]
	s_mov_b32 m0, s6
	v_readfirstlane_b32 s6, v34
	global_load_lds_dwordx4 v[30:31], off
	v_lshlrev_b32_e32 v30, 7, v212
	v_mov_b32_e32 v31, v1
	v_lshl_add_u64 v[32:33], v[22:23], 0, v[30:31]
	v_lshl_add_u64 v[32:33], v[32:33], 0, v[0:1]
	s_mov_b32 m0, s6
	v_lshl_add_u64 v[30:31], v[24:25], 0, v[30:31]
	global_load_lds_dwordx4 v[32:33], off
	v_add_u32_e32 v32, 0x6100, v141
	v_lshl_add_u64 v[30:31], v[30:31], 0, v[26:27]
	v_readfirstlane_b32 s6, v32
	s_mov_b32 m0, s6
	s_nop 0
	global_load_lds_dwordx4 v[30:31], off

.LBB0_1372:
	s_or_b64 exec, exec, s[8:9]
	flat_load_dwordx4 v[232:235], v[100:101]
	flat_load_dwordx4 v[236:239], v[114:115]
	flat_load_dwordx4 v[240:243], v[102:103]
	flat_load_dwordx4 v[244:247], v[104:105]
	v_mov_b32_e32 v0, 0
	v_cmp_lt_f32_e32 vcc, 0, v24
	v_mov_b32_e32 v6, 0
	s_and_saveexec_b64 s[6:7], vcc
	s_cbranch_execz .LBB0_1374
	flat_load_dword v2, v[116:117] offset:8
	s_waitcnt vmcnt(0) lgkmcnt(0)
	v_div_scale_f32 v3, s[8:9], v24, v24, v2
	v_rcp_f32_e32 v4, v3
	v_div_scale_f32 v5, vcc, v2, v24, v2
	v_fma_f32 v6, -v3, v4, 1.0
	v_fmac_f32_e32 v4, v6, v4
	v_mul_f32_e32 v6, v5, v4
	v_fma_f32 v7, -v3, v6, v5
	v_fmac_f32_e32 v6, v7, v4
	v_fma_f32 v3, -v3, v6, v5
	v_div_fmas_f32 v3, v3, v4, v6
	v_div_fixup_f32 v6, v3, v24, v2
.LBB0_1374:
	s_or_b64 exec, exec, s[6:7]
	v_cmp_lt_f32_e32 vcc, 0, v20
	s_waitcnt vmcnt(0) lgkmcnt(0)
	v_pk_fma_f32 v[234:235], v[50:51], v[6:7], v[234:235] op_sel_hi:[1,0,1]
	v_pk_fma_f32 v[232:233], v[48:49], v[6:7], v[232:233] op_sel_hi:[1,0,1]
	v_pk_fma_f32 v[238:239], v[54:55], v[6:7], v[238:239] op_sel_hi:[1,0,1]
	v_pk_fma_f32 v[236:237], v[52:53], v[6:7], v[236:237] op_sel_hi:[1,0,1]
	v_pk_fma_f32 v[242:243], v[58:59], v[6:7], v[242:243] op_sel_hi:[1,0,1]
	v_pk_fma_f32 v[240:241], v[56:57], v[6:7], v[240:241] op_sel_hi:[1,0,1]
	v_pk_fma_f32 v[246:247], v[46:47], v[6:7], v[246:247] op_sel_hi:[1,0,1]
	v_pk_fma_f32 v[244:245], v[44:45], v[6:7], v[244:245] op_sel_hi:[1,0,1]
	s_and_saveexec_b64 s[6:7], vcc
	s_cbranch_execz .LBB0_510
	flat_load_dword v0, v[118:119] offset:8
	s_waitcnt vmcnt(0) lgkmcnt(0)
	v_div_scale_f32 v6, s[8:9], v20, v20, v0
	v_rcp_f32_e32 v7, v6
	v_div_scale_f32 v8, vcc, v0, v20, v0
	v_fma_f32 v9, -v6, v7, 1.0
	v_fmac_f32_e32 v7, v9, v7
	v_mul_f32_e32 v9, v8, v7
	v_fma_f32 v10, -v6, v9, v8
	v_fmac_f32_e32 v9, v10, v7
	v_fma_f32 v6, -v6, v9, v8
	v_div_fmas_f32 v6, v6, v7, v9
	v_div_fixup_f32 v0, v6, v20, v0
	s_branch .LBB0_510

;     ...
;   for (int kt = 0; kt < nk; ++kt) {
;     if (kt + 1 < nk) GL_ISSUE(kt + 1, (kt + 1) & 1)
;     const char* As = smem + (kt & 1) * 32768;
;     const char* Bs = As + 16384;
;     if (DEEP) {
;     bf16x8 af[2][4], bfr[2][NF];
; #pragma unroll
;     for (int ks = 0; ks < 2; ++ks) {
;       const int co = ((ks * 4 + fq) ^ swz) * 16;
; #pragma unroll
;       for (int m = 0; m < 4; ++m) af[ks][m] = *(const bf16x8*)(As + (wr * 64 + m * 16 + fr) * 128 + co);
; #pragma unroll
;       for (int n = 0; n < NF; ++n) bfr[ks][n] = *(const bf16x8*)(Bs + (wc * 16 * NF + n * 16 + fr) * 128 + co);
;     }
;     __builtin_amdgcn_s_setprio(1);
; #pragma unroll
;     for (int ks = 0; ks < 2; ++ks)
; #pragma unroll
;       for (int m = 0; m < 4; ++m)
; #pragma unroll
;         for (int n = 0; n < NF; ++n) {
;           if (SWAP) acc[m][n] = __builtin_amdgcn_mfma_f32_16x16x32_bf16(bfr[ks][n], af[ks][m], acc[m][n], 0, 0, 0);
;           else acc[m][n] = __builtin_amdgcn_mfma_f32_16x16x32_bf16(af[ks][m], bfr[ks][n], acc[m][n], 0, 0, 0);
;         }
;     __builtin_amdgcn_s_setprio(0);
;     __builtin_amdgcn_sched_group_barrier(0x100, 4 + NF, 0);
; #pragma unroll
;     for (int i = 0; i < 4 + NF; ++i) { __builtin_amdgcn_sched_group_barrier(0x008, 2, 0); __builtin_amdgcn_sched_group_barrier(0x100, 1, 0); }
;     __builtin_amdgcn_sched_group_barrier(0x008, 8 * NF - 2 * (4 + NF), 0);
;     } else {
; #pragma unroll
;     for (int ks = 0; ks < 2; ++ks) {
;       const int co = ((ks * 4 + fq) ^ swz) * 16;
;       bf16x8 af[4], bfr[NF];
; #pragma unroll
;       for (int m = 0; m < 4; ++m) af[m] = *(const bf16x8*)(As + (wr * 64 + m * 16 + fr) * 128 + co);
; #pragma unroll
;       for (int n = 0; n < NF; ++n) bfr[n] = *(const bf16x8*)(Bs + (wc * 16 * NF + n * 16 + fr) * 128 + co);
;       __builtin_amdgcn_s_setprio(1);
; #pragma unroll
;       for (int m = 0; m < 4; ++m)
; #pragma unroll
;         for (int n = 0; n < NF; ++n) {
;           if (SWAP) acc[m][n] = __builtin_amdgcn_mfma_f32_16x16x32_bf16(bfr[n], af[m], acc[m][n], 0, 0, 0);
;           else acc[m][n] = __builtin_amdgcn_mfma_f32_16x16x32_bf16(af[m], bfr[n], acc[m][n], 0, 0, 0);
;         }
;       __builtin_amdgcn_s_setprio(0);
;     }
;     }
;     asm volatile("s_waitcnt vmcnt(0)" ::: "memory");
;     __syncthreads();
;   }
.LBB0_1426:
	s_add_i32 s94, s83, 0x8000
	s_and_b32 s93, s94, 0x8000
	s_and_b32 s95, s6, s80
	v_add_u32_e32 v199, s93, v197
	s_lshl_b32 s95, s95, 6
	v_add_u32_e32 v0, s95, v69
	v_readfirstlane_b32 s10, v199
	v_lshl_add_u64 v[200:201], v[0:1], 1, s[50:51]
	s_mov_b32 m0, s10
	v_add_u32_e32 v0, s95, v124
	global_load_lds_dwordx4 v[200:201], off
	v_lshl_add_u64 v[200:201], v[0:1], 1, s[50:51]
	v_add_u32_e32 v0, 0x1000, v199
	v_add_u32_e32 v202, 0x4000, v199
	v_readfirstlane_b32 s10, v0
	s_mov_b32 m0, s10
	v_add_u32_e32 v0, s95, v191
	global_load_lds_dwordx4 v[200:201], off
	v_lshl_add_u64 v[200:201], v[0:1], 1, s[50:51]
	v_add_u32_e32 v0, 0x2000, v199
	s_nop 0
	v_readfirstlane_b32 s10, v0
	s_mov_b32 m0, s10
	v_add_u32_e32 v0, s95, v192
	global_load_lds_dwordx4 v[200:201], off
	v_lshl_add_u64 v[200:201], v[0:1], 1, s[50:51]
	v_add_u32_e32 v0, 0x3000, v199
	s_nop 0
	v_readfirstlane_b32 s10, v0
	s_mov_b32 m0, s10
	v_add_u32_e32 v0, s95, v193
	v_readfirstlane_b32 s10, v202
	global_load_lds_dwordx4 v[200:201], off
	v_lshl_add_u64 v[200:201], v[0:1], 1, s[40:41]
	s_mov_b32 m0, s10
	v_add_u32_e32 v0, s95, v194
	global_load_lds_dwordx4 v[200:201], off
	v_lshl_add_u64 v[200:201], v[0:1], 1, s[40:41]
	v_add_u32_e32 v0, 0x5000, v199
	s_nop 0
	v_readfirstlane_b32 s10, v0
	s_mov_b32 m0, s10
	v_add_u32_e32 v0, s95, v195
	global_load_lds_dwordx4 v[200:201], off
	v_lshl_add_u64 v[200:201], v[0:1], 1, s[40:41]
	v_add_u32_e32 v0, 0x6000, v199
	s_nop 0
	v_readfirstlane_b32 s10, v0
	s_mov_b32 m0, s10
	v_add_u32_e32 v0, s95, v196
	global_load_lds_dwordx4 v[200:201], off
	v_lshl_add_u64 v[200:201], v[0:1], 1, s[40:41]
	v_add_u32_e32 v0, 0x7000, v199
	s_nop 0
	v_readfirstlane_b32 s10, v0
	s_mov_b32 m0, s10
	s_and_b32 s10, s83, 0x8000
	global_load_lds_dwordx4 v[200:201], off
	v_or_b32_e32 v0, s10, v198
	v_add_u32_e32 v199, v0, v67
	v_add_u32_e32 v0, v0, v66
	ds_read_b128 v[200:203], v199
	ds_read_b128 v[204:207], v199 offset:2048
	ds_read_b128 v[208:211], v199 offset:4096
	ds_read_b128 v[212:215], v199 offset:6144
	ds_read_b128 v[216:219], v0 offset:16384
	ds_read_b128 v[220:223], v0 offset:18432
	ds_read_b128 v[224:227], v0 offset:20480
	ds_read_b128 v[228:231], v0 offset:22528
	s_setprio 1
	s_waitcnt lgkmcnt(0)
	v_mfma_f32_16x16x32_bf16 v[62:65], v[216:219], v[200:203], v[62:65]
	v_mfma_f32_16x16x32_bf16 v[58:61], v[220:223], v[200:203], v[58:61]
	v_mfma_f32_16x16x32_bf16 v[54:57], v[224:227], v[200:203], v[54:57]
	v_mfma_f32_16x16x32_bf16 v[50:53], v[228:231], v[200:203], v[50:53]
	v_mfma_f32_16x16x32_bf16 v[46:49], v[216:219], v[204:207], v[46:49]
	v_mfma_f32_16x16x32_bf16 v[42:45], v[220:223], v[204:207], v[42:45]
	v_mfma_f32_16x16x32_bf16 v[38:41], v[224:227], v[204:207], v[38:41]
	v_mfma_f32_16x16x32_bf16 v[34:37], v[228:231], v[204:207], v[34:37]
	v_mfma_f32_16x16x32_bf16 v[30:33], v[216:219], v[208:211], v[30:33]
	v_mfma_f32_16x16x32_bf16 v[26:29], v[220:223], v[208:211], v[26:29]
	v_mfma_f32_16x16x32_bf16 v[22:25], v[224:227], v[208:211], v[22:25]
	v_mfma_f32_16x16x32_bf16 v[18:21], v[228:231], v[208:211], v[18:21]
	v_mfma_f32_16x16x32_bf16 v[14:17], v[216:219], v[212:215], v[14:17]
	v_mfma_f32_16x16x32_bf16 v[10:13], v[220:223], v[212:215], v[10:13]
	v_mfma_f32_16x16x32_bf16 v[6:9], v[224:227], v[212:215], v[6:9]
	v_mfma_f32_16x16x32_bf16 v[2:5], v[228:231], v[212:215], v[2:5]
	s_setprio 0
	v_or_b32_e32 v0, s10, v68
	v_add_u32_e32 v199, v0, v67
	v_add_u32_e32 v0, v0, v66
	ds_read_b128 v[200:203], v199
	ds_read_b128 v[204:207], v199 offset:2048
	ds_read_b128 v[208:211], v199 offset:4096
	ds_read_b128 v[212:215], v199 offset:6144
	ds_read_b128 v[216:219], v0 offset:16384
	ds_read_b128 v[220:223], v0 offset:18432
	ds_read_b128 v[224:227], v0 offset:20480
	ds_read_b128 v[228:231], v0 offset:22528
	s_setprio 1
	s_waitcnt lgkmcnt(0)
	v_mfma_f32_16x16x32_bf16 v[62:65], v[216:219], v[200:203], v[62:65]
	v_mfma_f32_16x16x32_bf16 v[58:61], v[220:223], v[200:203], v[58:61]
	v_mfma_f32_16x16x32_bf16 v[54:57], v[224:227], v[200:203], v[54:57]
	v_mfma_f32_16x16x32_bf16 v[50:53], v[228:231], v[200:203], v[50:53]
	v_mfma_f32_16x16x32_bf16 v[46:49], v[216:219], v[204:207], v[46:49]
	v_mfma_f32_16x16x32_bf16 v[42:45], v[220:223], v[204:207], v[42:45]
	v_mfma_f32_16x16x32_bf16 v[38:41], v[224:227], v[204:207], v[38:41]
	v_mfma_f32_16x16x32_bf16 v[34:37], v[228:231], v[204:207], v[34:37]
	v_mfma_f32_16x16x32_bf16 v[30:33], v[216:219], v[208:211], v[30:33]
	v_mfma_f32_16x16x32_bf16 v[26:29], v[220:223], v[208:211], v[26:29]
	v_mfma_f32_16x16x32_bf16 v[22:25], v[224:227], v[208:211], v[22:25]
	v_mfma_f32_16x16x32_bf16 v[18:21], v[228:231], v[208:211], v[18:21]
	v_mfma_f32_16x16x32_bf16 v[14:17], v[216:219], v[212:215], v[14:17]
	v_mfma_f32_16x16x32_bf16 v[10:13], v[220:223], v[212:215], v[10:13]
	v_mfma_f32_16x16x32_bf16 v[6:9], v[224:227], v[212:215], v[6:9]
	v_mfma_f32_16x16x32_bf16 v[2:5], v[228:231], v[212:215], v[2:5]
	s_setprio 0
	s_waitcnt vmcnt(0)
	s_add_i32 s6, s6, 1
	s_cmp_eq_u32 s7, s6
	s_mov_b32 s83, s94
	s_waitcnt vmcnt(0)
	s_barrier
	s_cbranch_scc0 .LBB0_1426
; DEVI int opaque_tid() { int t = __builtin_amdgcn_workitem_id_x(); asm volatile("" : "+v"(t)); return t; }
;   const int tid = opaque_tid();
;   const int lrow = tid >> 3, lpos = tid & 7;
;   const int gch = (lpos ^ (lrow & 7)) * 8 + koff * 64;
;   char* ab = smem + tid * 16;
; #pragma unroll
;   for (int i = 0; i < 4; ++i)
;     __builtin_amdgcn_global_load_lds((const unsigned*)(A + (unsigned)(arow(m0 + lrow + 32 * i) + gch)), (unsigned*)(ab + i * 4096), 16, 0, 0);
; #pragma unroll
;   for (int i = 0; i < NF; ++i)
;     __builtin_amdgcn_global_load_lds((const unsigned*)(Bt + (unsigned)((n0 + lrow + 32 * i) * ldb + gch)), (unsigned*)(ab + 16384 + i * 4096), 16, 0, 0);
; }
; DEVI void phase_merge(const Params& p, char* smem) {
;     ...
;       gemm_mainloop_g<4, true, RowLinear, true>(acc, ocat + ko, RowLinear{1024}, 64, wb, kk, kk, mt * 128, nt * 128, smem);
;       gemm_prefetch0<4>(xb, RowLinear{1024}, wg + (long)i * 1024 * 1024, 1024, mt * 128, nt * 128, smem);
; #pragma unroll
;       for (int m = 0; m < 4; ++m)
; #pragma unroll
;         for (int n = 0; n < 4; n += 2)
;           brg[(m * 2 + (n >> 1)) * 256] = u32x4{pack2(acc[m][n][0], acc[m][n][1]), pack2(acc[m][n][2], acc[m][n][3]),
;                                                 pack2(acc[m][n + 1][0], acc[m][n + 1][1]), pack2(acc[m][n + 1][2], acc[m][n + 1][3])};
	v_add_u32_e32 v0, s93, v198
	v_add_u32_e32 v69, v0, v67
	v_add_u32_e32 v0, v0, v66
	ds_read_b128 v[192:195], v69
	ds_read_b128 v[196:199], v69 offset:2048
	ds_read_b128 v[200:203], v69 offset:4096
	ds_read_b128 v[204:207], v69 offset:6144
	ds_read_b128 v[208:211], v0 offset:16384
	ds_read_b128 v[212:215], v0 offset:18432
	ds_read_b128 v[216:219], v0 offset:20480
	ds_read_b128 v[220:223], v0 offset:22528
	s_setprio 1
	s_waitcnt lgkmcnt(3)
	v_mfma_f32_16x16x32_bf16 v[62:65], v[208:211], v[192:195], v[62:65]
	s_waitcnt lgkmcnt(2)
	v_mfma_f32_16x16x32_bf16 v[58:61], v[212:215], v[192:195], v[58:61]
	s_waitcnt lgkmcnt(1)
	v_mfma_f32_16x16x32_bf16 v[54:57], v[216:219], v[192:195], v[54:57]
	s_waitcnt lgkmcnt(0)
	v_mfma_f32_16x16x32_bf16 v[50:53], v[220:223], v[192:195], v[50:53]
	v_mfma_f32_16x16x32_bf16 v[46:49], v[208:211], v[196:199], v[46:49]
	v_mfma_f32_16x16x32_bf16 v[42:45], v[212:215], v[196:199], v[42:45]
	v_mfma_f32_16x16x32_bf16 v[38:41], v[216:219], v[196:199], v[38:41]
	v_mfma_f32_16x16x32_bf16 v[34:37], v[220:223], v[196:199], v[34:37]
	v_mfma_f32_16x16x32_bf16 v[30:33], v[208:211], v[200:203], v[30:33]
	v_mfma_f32_16x16x32_bf16 v[26:29], v[212:215], v[200:203], v[26:29]
	v_mfma_f32_16x16x32_bf16 v[22:25], v[216:219], v[200:203], v[22:25]
	v_mfma_f32_16x16x32_bf16 v[18:21], v[220:223], v[200:203], v[18:21]
	v_mfma_f32_16x16x32_bf16 v[14:17], v[208:211], v[204:207], v[14:17]
	v_mfma_f32_16x16x32_bf16 v[10:13], v[212:215], v[204:207], v[10:13]
	v_mfma_f32_16x16x32_bf16 v[6:9], v[216:219], v[204:207], v[6:9]
	v_mfma_f32_16x16x32_bf16 v[2:5], v[220:223], v[204:207], v[2:5]
	s_setprio 0
	v_add_u32_e32 v0, s93, v68
	v_add_u32_e32 v67, v0, v67
	v_add_u32_e32 v0, v0, v66
	ds_read_b128 v[192:195], v67
	ds_read_b128 v[196:199], v67 offset:2048
	ds_read_b128 v[200:203], v67 offset:4096
	ds_read_b128 v[204:207], v67 offset:6144
	ds_read_b128 v[66:69], v0 offset:16384
	ds_read_b128 v[208:211], v0 offset:18432
	ds_read_b128 v[212:215], v0 offset:20480
	ds_read_b128 v[216:219], v0 offset:22528
	s_setprio 1
	s_waitcnt lgkmcnt(3)
	v_mfma_f32_16x16x32_bf16 v[62:65], v[66:69], v[192:195], v[62:65]
	s_waitcnt lgkmcnt(2)
	v_mfma_f32_16x16x32_bf16 v[58:61], v[208:211], v[192:195], v[58:61]
	s_waitcnt lgkmcnt(1)
	v_mfma_f32_16x16x32_bf16 v[54:57], v[212:215], v[192:195], v[54:57]
	s_waitcnt lgkmcnt(0)
	v_mfma_f32_16x16x32_bf16 v[50:53], v[216:219], v[192:195], v[50:53]
	v_mfma_f32_16x16x32_bf16 v[46:49], v[66:69], v[196:199], v[46:49]
	v_mfma_f32_16x16x32_bf16 v[42:45], v[208:211], v[196:199], v[42:45]
	v_mfma_f32_16x16x32_bf16 v[38:41], v[212:215], v[196:199], v[38:41]
	v_mfma_f32_16x16x32_bf16 v[34:37], v[216:219], v[196:199], v[34:37]
	v_mfma_f32_16x16x32_bf16 v[30:33], v[66:69], v[200:203], v[30:33]
	v_mfma_f32_16x16x32_bf16 v[26:29], v[208:211], v[200:203], v[26:29]
	v_mfma_f32_16x16x32_bf16 v[22:25], v[212:215], v[200:203], v[22:25]
	v_mfma_f32_16x16x32_bf16 v[18:21], v[216:219], v[200:203], v[18:21]
	v_mfma_f32_16x16x32_bf16 v[14:17], v[66:69], v[204:207], v[14:17]
	v_mfma_f32_16x16x32_bf16 v[10:13], v[208:211], v[204:207], v[10:13]
	v_mfma_f32_16x16x32_bf16 v[6:9], v[212:215], v[204:207], v[6:9]
	v_mfma_f32_16x16x32_bf16 v[2:5], v[216:219], v[204:207], v[2:5]
	s_setprio 0
	v_mov_b32_e32 v0, v154
	s_waitcnt vmcnt(0)
	s_barrier
	s_lshl_b32 s6, s82, 21
	v_ashrrev_i32_e32 v68, 3, v0
	v_xor_b32_e32 v66, v68, v0
	v_lshlrev_b32_e32 v66, 3, v66
	v_and_b32_e32 v69, 56, v66
	v_lshlrev_b32_e32 v124, 4, v0
	v_add_u32_e32 v0, s19, v68
	s_add_u32 s40, s42, s6
	v_lshl_or_b32 v0, v0, 10, v69
	v_readfirstlane_b32 s6, v124
	v_lshl_add_u64 v[66:67], v[0:1], 1, s[12:13]
	s_mov_b32 m0, s6
	v_add_u32_e32 v191, 0x1000, v124
	global_load_lds_dwordx4 v[66:67], off
	v_add_u32_e32 v66, 0x8000, v0
	v_mov_b32_e32 v67, v1
	v_readfirstlane_b32 s6, v191
	v_lshl_add_u64 v[66:67], v[66:67], 1, s[12:13]
	s_mov_b32 m0, s6
	v_add_u32_e32 v191, 0x2000, v124
	global_load_lds_dwordx4 v[66:67], off
	v_add_u32_e32 v66, 0x10000, v0
	v_mov_b32_e32 v67, v1
	v_readfirstlane_b32 s6, v191
	v_lshl_add_u64 v[66:67], v[66:67], 1, s[12:13]
	s_mov_b32 m0, s6
	v_add_u32_e32 v0, 0x18000, v0
	global_load_lds_dwordx4 v[66:67], off
	v_lshl_add_u64 v[66:67], v[0:1], 1, s[12:13]
	v_add_u32_e32 v0, 0x3000, v124
	s_addc_u32 s41, s43, 0
	v_readfirstlane_b32 s6, v0
	v_add_u32_e32 v0, s18, v68
	v_add_u32_e32 v68, 0x4000, v124
	s_mov_b32 m0, s6
	v_lshl_or_b32 v0, v0, 10, v69
	v_readfirstlane_b32 s6, v68
	global_load_lds_dwordx4 v[66:67], off
	v_lshl_add_u64 v[66:67], v[0:1], 1, s[40:41]
	s_mov_b32 m0, s6
	v_add_u32_e32 v68, 0x5000, v124
	global_load_lds_dwordx4 v[66:67], off
	v_add_u32_e32 v66, 0x8000, v0
	v_mov_b32_e32 v67, v1
	v_readfirstlane_b32 s6, v68
	v_lshl_add_u64 v[66:67], v[66:67], 1, s[40:41]
	s_mov_b32 m0, s6
	v_add_u32_e32 v68, 0x6000, v124
	global_load_lds_dwordx4 v[66:67], off
	v_add_u32_e32 v66, 0x10000, v0
	v_mov_b32_e32 v67, v1
	v_readfirstlane_b32 s6, v68
	v_lshl_add_u64 v[66:67], v[66:67], 1, s[40:41]
	s_mov_b32 m0, s6
	v_add_u32_e32 v0, 0x18000, v0
	global_load_lds_dwordx4 v[66:67], off
	v_lshl_add_u64 v[66:67], v[0:1], 1, s[40:41]
	v_add_u32_e32 v0, 0x7000, v124
	v_cvt_pk_bf16_f32 v62, v62, v63
	v_readfirstlane_b32 s6, v0
	s_mov_b32 m0, s6
	v_cvt_pk_bf16_f32 v63, v64, v65
	global_load_lds_dwordx4 v[66:67], off
	v_cvt_pk_bf16_f32 v64, v58, v59
	v_cvt_pk_bf16_f32 v65, v60, v61
	v_cvt_pk_bf16_f32 v54, v54, v55
	v_cvt_pk_bf16_f32 v55, v56, v57
	v_cvt_pk_bf16_f32 v56, v50, v51
	v_cvt_pk_bf16_f32 v57, v52, v53
	v_cvt_pk_bf16_f32 v46, v46, v47
	v_cvt_pk_bf16_f32 v47, v48, v49
	v_cvt_pk_bf16_f32 v48, v42, v43
	v_cvt_pk_bf16_f32 v49, v44, v45
	v_cvt_pk_bf16_f32 v38, v38, v39
	v_cvt_pk_bf16_f32 v39, v40, v41
	v_cvt_pk_bf16_f32 v40, v34, v35
	v_cvt_pk_bf16_f32 v41, v36, v37
	v_cvt_pk_bf16_f32 v30, v30, v31
	v_cvt_pk_bf16_f32 v31, v32, v33
	v_cvt_pk_bf16_f32 v32, v26, v27
	v_cvt_pk_bf16_f32 v33, v28, v29
	v_cvt_pk_bf16_f32 v22, v22, v23
	v_cvt_pk_bf16_f32 v23, v24, v25
	v_cvt_pk_bf16_f32 v24, v18, v19
	v_cvt_pk_bf16_f32 v25, v20, v21
	v_cvt_pk_bf16_f32 v14, v14, v15
	v_cvt_pk_bf16_f32 v15, v16, v17
	v_cvt_pk_bf16_f32 v16, v10, v11
	v_cvt_pk_bf16_f32 v17, v12, v13
	v_cvt_pk_bf16_f32 v6, v6, v7
	v_cvt_pk_bf16_f32 v7, v8, v9
	v_cvt_pk_bf16_f32 v8, v2, v3
	v_cvt_pk_bf16_f32 v9, v4, v5
	v_mov_b32_e32 v0, v154
	flat_store_dwordx4 v[70:71], v[62:65]
	flat_store_dwordx4 v[74:75], v[54:57]
	flat_store_dwordx4 v[76:77], v[46:49]
	flat_store_dwordx4 v[78:79], v[38:41]
	flat_store_dwordx4 v[80:81], v[30:33]
	flat_store_dwordx4 v[82:83], v[22:25]
	flat_store_dwordx4 v[72:73], v[14:17]
	flat_store_dwordx4 v[84:85], v[6:9]
	s_waitcnt vmcnt(0)
; DEVI int opaque_tid() { int t = __builtin_amdgcn_workitem_id_x(); asm volatile("" : "+v"(t)); return t; }
;   const int tid = opaque_tid(), lane = tid & 63, wid = tid >> 6, wr = wid >> 1, wc = wid & 1, fr = lane & 15, fq = lane >> 4;
;   const int lrow = tid >> 3, lpos = tid & 7;
;   const int gch = (lpos ^ (lrow & 7)) * 8;
;   unsigned aoff[4], boff[NF];
; #pragma unroll
;   for (int i = 0; i < 4; ++i) aoff[i] = (unsigned)(arow(m0 + lrow + 32 * i) + gch);
; #pragma unroll
;   for (int i = 0; i < NF; ++i) boff[i] = (unsigned)((n0 + lrow + 32 * i) * ldb + gch);
;   const int nk = K >> 6;
;   if (!PRE) __syncthreads();
;     ...
;   if (!PRE) GL_ISSUE(0, 0)
;   asm volatile("s_waitcnt vmcnt(0)" ::: "memory");
;   __syncthreads();
;   const int swz = fr & 7;
;   for (int kt = 0; kt < nk; ++kt) {
;     if (kt + 1 < nk) GL_ISSUE(kt + 1, (kt + 1) & 1)
;     ...
; #pragma unroll
;     for (int ks = 0; ks < 2; ++ks) {
;       const int co = ((ks * 4 + fq) ^ swz) * 16;
;       bf16x8 af[4], bfr[NF];
; #pragma unroll
;       for (int m = 0; m < 4; ++m) af[m] = *(const bf16x8*)(As + (wr * 64 + m * 16 + fr) * 128 + co);
; #pragma unroll
;       for (int n = 0; n < NF; ++n) bfr[n] = *(const bf16x8*)(Bs + (wc * 16 * NF + n * 16 + fr) * 128 + co);
;       __builtin_amdgcn_s_setprio(1);
; #pragma unroll
;       for (int m = 0; m < 4; ++m)
; #pragma unroll
;         for (int n = 0; n < NF; ++n) {
;           if (SWAP) acc[m][n] = __builtin_amdgcn_mfma_f32_16x16x32_bf16(bfr[n], af[m], acc[m][n], 0, 0, 0);
;           else acc[m][n] = __builtin_amdgcn_mfma_f32_16x16x32_bf16(af[m], bfr[n], acc[m][n], 0, 0, 0);
;         }
;       __builtin_amdgcn_s_setprio(0);
;     }
	s_mov_b32 s7, 0
	v_ashrrev_i32_e32 v3, 3, v0
	v_lshrrev_b32_e32 v2, 4, v0
	v_xor_b32_e32 v4, v3, v0
	v_bfe_u32 v5, v0, 4, 2
	v_and_b32_e32 v6, 7, v0
	v_and_b32_e32 v7, 15, v0
	v_lshlrev_b32_e32 v124, 4, v0
	v_lshrrev_b32_e32 v8, 1, v0
	v_lshlrev_b32_e32 v0, 7, v0
	v_lshlrev_b32_e32 v4, 3, v4
	v_and_b32_e32 v66, 0x2780, v0
	v_bitop3_b32 v0, v5, v6, 4 bitop3:0x36
	v_and_b32_e32 v4, 56, v4
	v_bitop3_b32 v2, v2, v6, 3 bitop3:0x6c
	v_lshlrev_b32_e32 v67, 4, v0
	v_lshlrev_b32_e32 v0, 10, v3
	v_and_or_b32 v7, v8, s79, v7
	v_lshlrev_b32_e32 v69, 4, v2
	v_add3_u32 v191, s55, v0, v4
	v_add_u32_e32 v0, s19, v3
	v_mov_b32_e32 v2, 0
	v_lshlrev_b32_e32 v68, 7, v7
	v_lshl_or_b32 v192, v0, 10, v4
	s_mov_b32 s6, 0
	v_mov_b32_e32 v3, v2
	v_mov_b32_e32 v4, v2
	v_mov_b32_e32 v5, v2
	v_mov_b32_e32 v6, v2
	v_mov_b32_e32 v7, v2
	v_mov_b32_e32 v8, v2
	v_mov_b32_e32 v9, v2
	v_mov_b32_e32 v10, v2
	v_mov_b32_e32 v11, v2
	v_mov_b32_e32 v12, v2
	v_mov_b32_e32 v13, v2
	v_mov_b32_e32 v14, v2
	v_mov_b32_e32 v15, v2
	v_mov_b32_e32 v16, v2
	v_mov_b32_e32 v17, v2
	v_mov_b32_e32 v18, v2
	v_mov_b32_e32 v19, v2
	v_mov_b32_e32 v20, v2
	v_mov_b32_e32 v21, v2
	v_mov_b32_e32 v22, v2
	v_mov_b32_e32 v23, v2
	v_mov_b32_e32 v24, v2
	v_mov_b32_e32 v25, v2
	v_mov_b32_e32 v26, v2
	v_mov_b32_e32 v27, v2
	v_mov_b32_e32 v28, v2
	v_mov_b32_e32 v29, v2
	v_mov_b32_e32 v30, v2
	v_mov_b32_e32 v31, v2
	v_mov_b32_e32 v32, v2
	v_mov_b32_e32 v33, v2
	v_mov_b32_e32 v34, v2
	v_mov_b32_e32 v35, v2
	v_mov_b32_e32 v36, v2
	v_mov_b32_e32 v37, v2
	v_mov_b32_e32 v38, v2
	v_mov_b32_e32 v39, v2
	v_mov_b32_e32 v40, v2
	v_mov_b32_e32 v41, v2
	v_mov_b32_e32 v42, v2
	v_mov_b32_e32 v43, v2
	v_mov_b32_e32 v44, v2
	v_mov_b32_e32 v45, v2
	v_mov_b32_e32 v46, v2
	v_mov_b32_e32 v47, v2
	v_mov_b32_e32 v48, v2
	v_mov_b32_e32 v49, v2
	v_mov_b32_e32 v50, v2
	v_mov_b32_e32 v51, v2
	v_mov_b32_e32 v52, v2
	v_mov_b32_e32 v53, v2
	v_mov_b32_e32 v54, v2
	v_mov_b32_e32 v55, v2
	v_mov_b32_e32 v56, v2
	v_mov_b32_e32 v57, v2
	v_mov_b32_e32 v58, v2
	v_mov_b32_e32 v59, v2
	v_mov_b32_e32 v60, v2
	v_mov_b32_e32 v61, v2
	v_mov_b32_e32 v62, v2
	v_mov_b32_e32 v63, v2
	v_mov_b32_e32 v64, v2
	v_mov_b32_e32 v65, v2
	v_lshlrev_b32_e32 v232, 1, v192
	v_add_u32_e32 v233, 0x10000, v232
	v_add_u32_e32 v234, 0x20000, v232
	v_add_u32_e32 v235, 0x30000, v232
	v_lshlrev_b32_e32 v236, 1, v191
	v_add_u32_e32 v237, 0x10000, v236
	v_add_u32_e32 v238, 0x20000, v236
	v_add_u32_e32 v239, 0x30000, v236
	v_readfirstlane_b32 s68, v124
	s_add_u32 s64, s12, 0x80
	s_addc_u32 s65, s13, 0
	s_add_u32 s66, s40, 0x80
	s_addc_u32 s67, s41, 0
	s_waitcnt vmcnt(0) lgkmcnt(0)
	s_barrier
.LBB0_1428:
	s_and_b32 s7, s7, 0x8000
	v_or_b32_e32 v0, s7, v69
	v_add_u32_e32 v193, v0, v68
	v_add_u32_e32 v0, v0, v66
	ds_read_b128 v[194:197], v193
	ds_read_b128 v[198:201], v193 offset:2048
	ds_read_b128 v[202:205], v193 offset:4096
	ds_read_b128 v[206:209], v193 offset:6144
	ds_read_b128 v[210:213], v0 offset:16384
	ds_read_b128 v[214:217], v0 offset:18432
	ds_read_b128 v[218:221], v0 offset:20480
	ds_read_b128 v[222:225], v0 offset:22528
	s_add_i32 s10, s7, 0x8000
	s_and_b32 s69, s10, 0x8000
	s_add_i32 s69, s69, s68
	s_mov_b32 m0, s69
	s_nop 0
	global_load_lds_dwordx4 v232, s[64:65]
	s_add_i32 m0, s69, 0x1000
	s_nop 0
	global_load_lds_dwordx4 v233, s[64:65]
	s_add_i32 m0, s69, 0x2000
	s_nop 0
	global_load_lds_dwordx4 v234, s[64:65]
	s_add_i32 m0, s69, 0x3000
	s_nop 0
	global_load_lds_dwordx4 v235, s[64:65]
	s_add_i32 m0, s69, 0x4000
	s_nop 0
	global_load_lds_dwordx4 v236, s[66:67]
	s_add_i32 m0, s69, 0x5000
	s_nop 0
	global_load_lds_dwordx4 v237, s[66:67]
	s_add_i32 m0, s69, 0x6000
	s_nop 0
	global_load_lds_dwordx4 v238, s[66:67]
	s_add_i32 m0, s69, 0x7000
	s_nop 0
	global_load_lds_dwordx4 v239, s[66:67]
	s_add_u32 s64, s64, 0x80
	s_addc_u32 s65, s65, 0
	s_add_u32 s66, s66, 0x80
	s_addc_u32 s67, s67, 0
	s_setprio 1
	s_waitcnt lgkmcnt(3)
	v_mfma_f32_16x16x32_bf16 v[62:65], v[210:213], v[194:197], v[62:65]
	s_waitcnt lgkmcnt(2)
	v_mfma_f32_16x16x32_bf16 v[58:61], v[214:217], v[194:197], v[58:61]
	s_waitcnt lgkmcnt(1)
	v_mfma_f32_16x16x32_bf16 v[54:57], v[218:221], v[194:197], v[54:57]
	s_waitcnt lgkmcnt(0)
	v_mfma_f32_16x16x32_bf16 v[50:53], v[222:225], v[194:197], v[50:53]
	v_mfma_f32_16x16x32_bf16 v[46:49], v[210:213], v[198:201], v[46:49]
	v_mfma_f32_16x16x32_bf16 v[42:45], v[214:217], v[198:201], v[42:45]
	v_mfma_f32_16x16x32_bf16 v[38:41], v[218:221], v[198:201], v[38:41]
	v_mfma_f32_16x16x32_bf16 v[34:37], v[222:225], v[198:201], v[34:37]
	v_mfma_f32_16x16x32_bf16 v[30:33], v[210:213], v[202:205], v[30:33]
	v_mfma_f32_16x16x32_bf16 v[26:29], v[214:217], v[202:205], v[26:29]
	v_mfma_f32_16x16x32_bf16 v[22:25], v[218:221], v[202:205], v[22:25]
	v_mfma_f32_16x16x32_bf16 v[18:21], v[222:225], v[202:205], v[18:21]
	v_mfma_f32_16x16x32_bf16 v[14:17], v[210:213], v[206:209], v[14:17]
	v_mfma_f32_16x16x32_bf16 v[10:13], v[214:217], v[206:209], v[10:13]
	v_mfma_f32_16x16x32_bf16 v[6:9], v[218:221], v[206:209], v[6:9]
	v_mfma_f32_16x16x32_bf16 v[2:5], v[222:225], v[206:209], v[2:5]
	s_setprio 0
	v_or_b32_e32 v0, s7, v67
	v_add_u32_e32 v193, v0, v68
	v_add_u32_e32 v0, v0, v66
	ds_read_b128 v[194:197], v193
	ds_read_b128 v[198:201], v193 offset:2048
	ds_read_b128 v[202:205], v193 offset:4096
	ds_read_b128 v[206:209], v193 offset:6144
	ds_read_b128 v[210:213], v0 offset:16384
	ds_read_b128 v[214:217], v0 offset:18432
	ds_read_b128 v[218:221], v0 offset:20480
	ds_read_b128 v[222:225], v0 offset:22528
	s_setprio 1
	s_waitcnt lgkmcnt(3)
	v_mfma_f32_16x16x32_bf16 v[62:65], v[210:213], v[194:197], v[62:65]
	s_waitcnt lgkmcnt(2)
	v_mfma_f32_16x16x32_bf16 v[58:61], v[214:217], v[194:197], v[58:61]
	s_waitcnt lgkmcnt(1)
	v_mfma_f32_16x16x32_bf16 v[54:57], v[218:221], v[194:197], v[54:57]
	s_waitcnt lgkmcnt(0)
	v_mfma_f32_16x16x32_bf16 v[50:53], v[222:225], v[194:197], v[50:53]
	v_mfma_f32_16x16x32_bf16 v[46:49], v[210:213], v[198:201], v[46:49]
	v_mfma_f32_16x16x32_bf16 v[42:45], v[214:217], v[198:201], v[42:45]
	v_mfma_f32_16x16x32_bf16 v[38:41], v[218:221], v[198:201], v[38:41]
	v_mfma_f32_16x16x32_bf16 v[34:37], v[222:225], v[198:201], v[34:37]
	v_mfma_f32_16x16x32_bf16 v[30:33], v[210:213], v[202:205], v[30:33]
	v_mfma_f32_16x16x32_bf16 v[26:29], v[214:217], v[202:205], v[26:29]
	v_mfma_f32_16x16x32_bf16 v[22:25], v[218:221], v[202:205], v[22:25]
	v_mfma_f32_16x16x32_bf16 v[18:21], v[222:225], v[202:205], v[18:21]
	v_mfma_f32_16x16x32_bf16 v[14:17], v[210:213], v[206:209], v[14:17]
	v_mfma_f32_16x16x32_bf16 v[10:13], v[214:217], v[206:209], v[10:13]
	v_mfma_f32_16x16x32_bf16 v[6:9], v[218:221], v[206:209], v[6:9]
	v_mfma_f32_16x16x32_bf16 v[2:5], v[222:225], v[206:209], v[2:5]
	s_setprio 0
	s_waitcnt vmcnt(0)
	s_add_i32 s6, s6, 64
	s_cmpk_eq_i32 s6, 0x3c0
	s_mov_b32 s7, s10
	s_waitcnt vmcnt(0)
	s_barrier
;     ...
; #pragma unroll
;     for (int ks = 0; ks < 2; ++ks) {
;       const int co = ((ks * 4 + fq) ^ swz) * 16;
;       bf16x8 af[4], bfr[NF];
; #pragma unroll
;       for (int m = 0; m < 4; ++m) af[m] = *(const bf16x8*)(As + (wr * 64 + m * 16 + fr) * 128 + co);
; #pragma unroll
;       for (int n = 0; n < NF; ++n) bfr[n] = *(const bf16x8*)(Bs + (wc * 16 * NF + n * 16 + fr) * 128 + co);
;       __builtin_amdgcn_s_setprio(1);
; #pragma unroll
;       for (int m = 0; m < 4; ++m)
; #pragma unroll
;         for (int n = 0; n < NF; ++n) {
;           if (SWAP) acc[m][n] = __builtin_amdgcn_mfma_f32_16x16x32_bf16(bfr[n], af[m], acc[m][n], 0, 0, 0);
;           else acc[m][n] = __builtin_amdgcn_mfma_f32_16x16x32_bf16(af[m], bfr[n], acc[m][n], 0, 0, 0);
;         }
;       __builtin_amdgcn_s_setprio(0);
;     }
; DEVI void phase_merge(const Params& p, char* smem) {
;     ...
;       gemm_mainloop_g<4, true, RowLinear, true>(acc, xb, RowLinear{1024}, 64, wg + (long)i * 1024 * 1024, 1024, 1024, mt * 128, nt * 128, smem);
;       if (i < 2) {
;         const bf16* wb2 = (const bf16*)(ws + (i == 0 ? OFF_WBM : OFF_WBF));
;         gemm_prefetch0<4>(ocat + (i == 0 ? 512 : 768), RowLinear{1024}, wb2, 256, mt * 128, nt * 128, smem);
;       } else if (t + (int)gridDim.x < 256 * 8) {
;         int mt2, nt2; tile_swz(t + gridDim.x, 256, 8, mt2, nt2);
;         gemm_prefetch0<4>(ocat, RowLinear{1024}, (const bf16*)(ws + OFF_WBN), 512, mt2 * 128, nt2 * 128, smem);
;       }
	s_cbranch_scc0 .LBB0_1428
	v_add_u32_e32 v0, v69, v68
	ds_read_b128 v[192:195], v0 offset:32768
	ds_read_b128 v[196:199], v0 offset:34816
	ds_read_b128 v[200:203], v0 offset:36864
	ds_read_b128 v[204:207], v0 offset:38912
	v_add_u32_e32 v0, v69, v66
	ds_read_b128 v[208:211], v0 offset:49152
	ds_read_b128 v[212:215], v0 offset:51200
	ds_read_b128 v[216:219], v0 offset:53248
	ds_read_b128 v[220:223], v0 offset:55296
	s_setprio 1
	s_waitcnt lgkmcnt(3)
	v_mfma_f32_16x16x32_bf16 v[62:65], v[208:211], v[192:195], v[62:65]
	s_waitcnt lgkmcnt(2)
	v_mfma_f32_16x16x32_bf16 v[58:61], v[212:215], v[192:195], v[58:61]
	s_waitcnt lgkmcnt(1)
	v_mfma_f32_16x16x32_bf16 v[54:57], v[216:219], v[192:195], v[54:57]
	s_waitcnt lgkmcnt(0)
	v_mfma_f32_16x16x32_bf16 v[50:53], v[220:223], v[192:195], v[50:53]
	v_mfma_f32_16x16x32_bf16 v[46:49], v[208:211], v[196:199], v[46:49]
	v_mfma_f32_16x16x32_bf16 v[42:45], v[212:215], v[196:199], v[42:45]
	v_mfma_f32_16x16x32_bf16 v[38:41], v[216:219], v[196:199], v[38:41]
	v_mfma_f32_16x16x32_bf16 v[34:37], v[220:223], v[196:199], v[34:37]
	v_mfma_f32_16x16x32_bf16 v[30:33], v[208:211], v[200:203], v[30:33]
	v_mfma_f32_16x16x32_bf16 v[26:29], v[212:215], v[200:203], v[26:29]
	v_mfma_f32_16x16x32_bf16 v[22:25], v[216:219], v[200:203], v[22:25]
	v_mfma_f32_16x16x32_bf16 v[18:21], v[220:223], v[200:203], v[18:21]
	v_mfma_f32_16x16x32_bf16 v[14:17], v[208:211], v[204:207], v[14:17]
	v_mfma_f32_16x16x32_bf16 v[10:13], v[212:215], v[204:207], v[10:13]
	v_mfma_f32_16x16x32_bf16 v[6:9], v[216:219], v[204:207], v[6:9]
	v_mfma_f32_16x16x32_bf16 v[2:5], v[220:223], v[204:207], v[2:5]
	s_setprio 0
	v_add_u32_e32 v0, v67, v68
	ds_read_b128 v[192:195], v0 offset:32768
	ds_read_b128 v[196:199], v0 offset:34816
	ds_read_b128 v[200:203], v0 offset:36864
	ds_read_b128 v[204:207], v0 offset:38912
	v_add_u32_e32 v0, v67, v66
	ds_read_b128 v[66:69], v0 offset:49152
	ds_read_b128 v[208:211], v0 offset:51200
	ds_read_b128 v[212:215], v0 offset:53248
	ds_read_b128 v[216:219], v0 offset:55296
	s_setprio 1
	s_waitcnt lgkmcnt(3)
	v_mfma_f32_16x16x32_bf16 v[62:65], v[66:69], v[192:195], v[62:65]
	s_waitcnt lgkmcnt(2)
	v_mfma_f32_16x16x32_bf16 v[58:61], v[208:211], v[192:195], v[58:61]
	s_waitcnt lgkmcnt(1)
	v_mfma_f32_16x16x32_bf16 v[54:57], v[212:215], v[192:195], v[54:57]
	s_waitcnt lgkmcnt(0)
	v_mfma_f32_16x16x32_bf16 v[50:53], v[216:219], v[192:195], v[50:53]
	v_mfma_f32_16x16x32_bf16 v[46:49], v[66:69], v[196:199], v[46:49]
	v_mfma_f32_16x16x32_bf16 v[42:45], v[208:211], v[196:199], v[42:45]
	v_mfma_f32_16x16x32_bf16 v[38:41], v[212:215], v[196:199], v[38:41]
	v_mfma_f32_16x16x32_bf16 v[34:37], v[216:219], v[196:199], v[34:37]
	v_mfma_f32_16x16x32_bf16 v[30:33], v[66:69], v[200:203], v[30:33]
	v_mfma_f32_16x16x32_bf16 v[26:29], v[208:211], v[200:203], v[26:29]
	v_mfma_f32_16x16x32_bf16 v[22:25], v[212:215], v[200:203], v[22:25]
	v_mfma_f32_16x16x32_bf16 v[18:21], v[216:219], v[200:203], v[18:21]
	v_mfma_f32_16x16x32_bf16 v[14:17], v[66:69], v[204:207], v[14:17]
	v_mfma_f32_16x16x32_bf16 v[10:13], v[208:211], v[204:207], v[10:13]
	v_mfma_f32_16x16x32_bf16 v[6:9], v[212:215], v[204:207], v[6:9]
	v_mfma_f32_16x16x32_bf16 v[2:5], v[216:219], v[204:207], v[2:5]
	s_setprio 0
	s_waitcnt vmcnt(0)
	s_cmp_lg_u32 s82, 2
	s_barrier
	s_cbranch_scc0 .LBB0_1431
	s_and_b64 s[6:7], s[38:39], exec
	s_cselect_b32 s80, s33, 0xcc4000
	s_add_u32 s6, s8, s80
	v_mov_b32_e32 v0, v154
	s_addc_u32 s7, s9, 0
	s_and_b64 s[38:39], s[38:39], exec
	v_ashrrev_i32_e32 v67, 3, v0
	v_xor_b32_e32 v66, v67, v0
	s_cselect_b32 s10, 0x400, s76
	v_lshlrev_b32_e32 v66, 3, v66
	s_add_u32 s38, s14, s10
	v_and_b32_e32 v124, 56, v66
	v_lshlrev_b32_e32 v66, 4, v0
	v_add_u32_e32 v0, s19, v67
	s_addc_u32 s39, s15, 0
	v_lshl_or_b32 v0, v0, 10, v124
	v_readfirstlane_b32 s10, v66
	v_lshl_add_u64 v[68:69], v[0:1], 1, s[38:39]
	s_mov_b32 m0, s10
	v_add_u32_e32 v191, 0x1000, v66
	global_load_lds_dwordx4 v[68:69], off
	v_add_u32_e32 v68, 0x8000, v0
	v_mov_b32_e32 v69, v1
	v_readfirstlane_b32 s10, v191
	v_lshl_add_u64 v[68:69], v[68:69], 1, s[38:39]
	s_mov_b32 m0, s10
	v_add_u32_e32 v191, 0x2000, v66
	global_load_lds_dwordx4 v[68:69], off
	v_add_u32_e32 v68, 0x10000, v0
	v_mov_b32_e32 v69, v1
	v_readfirstlane_b32 s10, v191
	v_lshl_add_u64 v[68:69], v[68:69], 1, s[38:39]
	s_mov_b32 m0, s10
	v_add_u32_e32 v0, 0x18000, v0
	global_load_lds_dwordx4 v[68:69], off
	v_lshl_add_u64 v[68:69], v[0:1], 1, s[38:39]
	v_add_u32_e32 v0, 0x3000, v66
	s_mov_b64 s[38:39], -1
	v_readfirstlane_b32 s10, v0
	v_add_u32_e32 v0, s18, v67
	v_add_u32_e32 v67, 0x4000, v66
	s_mov_b32 m0, s10
	v_lshl_or_b32 v0, v0, 8, v124
	v_readfirstlane_b32 s10, v67
	global_load_lds_dwordx4 v[68:69], off
	v_lshl_add_u64 v[68:69], v[0:1], 1, s[6:7]
	s_mov_b32 m0, s10
	v_add_u32_e32 v67, 0x5000, v66
	global_load_lds_dwordx4 v[68:69], off
	v_add_u32_e32 v68, 0x2000, v0
	v_mov_b32_e32 v69, v1
	v_readfirstlane_b32 s10, v67
	v_lshl_add_u64 v[68:69], v[68:69], 1, s[6:7]
	s_mov_b32 m0, s10
	v_add_u32_e32 v67, 0x6000, v66
	global_load_lds_dwordx4 v[68:69], off
	v_add_u32_e32 v68, 0x4000, v0
	v_mov_b32_e32 v69, v1
	v_lshl_add_u64 v[68:69], v[68:69], 1, s[6:7]
	v_readfirstlane_b32 s6, v67
	s_mov_b32 m0, s6
	v_add_u32_e32 v0, 0x6000, v0
	global_load_lds_dwordx4 v[68:69], off
	s_mov_b64 s[40:41], s[80:81]
	s_cbranch_execz .LBB0_1432
	s_branch .LBB0_1435

; DEVI int k_rot(int mt, int nt, int nk) { return (((mt & 7) + (nt & 7)) & 7) * nk >> 3; }
;     ...
;   if (!PRE) GL_ISSUE(0, 0)
;   asm volatile("s_waitcnt vmcnt(0)" ::: "memory");
;   __syncthreads();
;   const int swz = fr & 7;
;   for (int kt = 0; kt < nk; ++kt) {
;     if (kt + 1 < nk) GL_ISSUE(kt + 1, (kt + 1) & 1)
;     const char* As = smem + (kt & 1) * 32768;
;     const char* Bs = As + 16384;
;     if (DEEP) {
;     bf16x8 af[2][4], bfr[2][NF];
; #pragma unroll
;     for (int ks = 0; ks < 2; ++ks) {
;       const int co = ((ks * 4 + fq) ^ swz) * 16;
; #pragma unroll
;       for (int m = 0; m < 4; ++m) af[ks][m] = *(const bf16x8*)(As + (wr * 64 + m * 16 + fr) * 128 + co);
; #pragma unroll
;       for (int n = 0; n < NF; ++n) bfr[ks][n] = *(const bf16x8*)(Bs + (wc * 16 * NF + n * 16 + fr) * 128 + co);
;     }
;     __builtin_amdgcn_s_setprio(1);
; #pragma unroll
;     for (int ks = 0; ks < 2; ++ks)
; #pragma unroll
;       for (int m = 0; m < 4; ++m)
; #pragma unroll
;         for (int n = 0; n < NF; ++n) {
;           if (SWAP) acc[m][n] = __builtin_amdgcn_mfma_f32_16x16x32_bf16(bfr[ks][n], af[ks][m], acc[m][n], 0, 0, 0);
;           else acc[m][n] = __builtin_amdgcn_mfma_f32_16x16x32_bf16(af[ks][m], bfr[ks][n], acc[m][n], 0, 0, 0);
;         }
;     __builtin_amdgcn_s_setprio(0);
;     __builtin_amdgcn_sched_group_barrier(0x100, 4 + NF, 0);
; #pragma unroll
;     for (int i = 0; i < 4 + NF; ++i) { __builtin_amdgcn_sched_group_barrier(0x008, 2, 0); __builtin_amdgcn_sched_group_barrier(0x100, 1, 0); }
;     __builtin_amdgcn_sched_group_barrier(0x008, 8 * NF - 2 * (4 + NF), 0);
; template <int EPI>
; DEVI void phase_gemm(const Params& p, const bf16* A, int lda, const bf16* Bt, int K, int NT, bf16* dst, int ldd, char* smem, bool nostore = false,
;                      const float* lng = nullptr, const float* lnb = nullptr) {
;     ...
;   for (; t < 256 * NT; t += gridDim.x) {
;     int mt, nt; tile_swz(t, 256, NT, mt, nt);
;     f32x4 acc[4][4]; zero_acc(acc);
;     gemm_mainloop_g<4, true, RowLinear, true, DEEP_FRAG != 0>(acc, A, RowLinear{lda}, 64, Bt, K, K, mt * 128, nt * 128, smem, KROT ? k_rot(mt, nt, K >> 6) : 0);
.LBB0_1484:
	s_lshl_b32 s6, s13, 4
	s_and_b32 s10, s6, 0x7000
	s_lshl_b32 s6, s42, 8
	s_and_b32 s7, s6, 0x700
	s_ashr_i32 s11, s42, 3
	s_add_i32 s7, s7, s11
	s_ashr_i32 s6, s7, 31
	s_lshr_b32 s6, s6, 26
	s_add_i32 s6, s7, s6
	s_lshl_b32 s6, s6, 4
	v_mov_b32_e32 v0, v154
	s_and_b32 s36, s6, 0xfffffc00
	s_lshl_b32 s6, s11, 7
	s_lshl_b32 s11, s11, 4
	v_ashrrev_i32_e32 v35, 3, v0
	v_lshrrev_b32_e32 v34, 4, v0
	v_xor_b32_e32 v36, v35, v0
	v_bfe_u32 v37, v0, 4, 2
	v_and_b32_e32 v38, 7, v0
	v_and_b32_e32 v39, 15, v0
	v_lshlrev_b32_e32 v102, 4, v0
	v_lshrrev_b32_e32 v40, 1, v0
	v_lshlrev_b32_e32 v0, 7, v0
	s_add_i32 s10, s10, s11
	s_and_b32 s6, s6, 0x380
	v_and_b32_e32 v98, 0x2780, v0
	v_bitop3_b32 v0, v34, v38, 3 bitop3:0x6c
	s_sub_i32 s10, s10, s36
	v_lshlrev_b32_e32 v36, 3, v36
	v_lshlrev_b32_e32 v101, 4, v0
	v_bitop3_b32 v0, v37, v38, 4 bitop3:0x36
	s_or_b32 s6, s6, s36
	s_lshl_b32 s10, s10, 10
	v_and_b32_e32 v36, 56, v36
	s_waitcnt vmcnt(0)
	v_lshlrev_b32_e32 v99, 4, v0
	v_add_u32_e32 v0, s6, v35
	s_and_b32 s10, s10, 0xfffe0000
	v_and_or_b32 v39, v40, s79, v39
	v_lshl_or_b32 v103, v0, 10, v36
	v_lshl_add_u32 v0, v35, 10, s10
	v_mov_b32_e32 v34, 0
	v_lshlrev_b32_e32 v100, 7, v39
	v_or_b32_e32 v104, v0, v36
	s_mov_b32 s40, 0
	s_mov_b32 s37, 0
	v_mov_b32_e32 v35, v34
	v_mov_b32_e32 v36, v34
	v_mov_b32_e32 v37, v34
	v_mov_b32_e32 v38, v34
	v_mov_b32_e32 v39, v34
	v_mov_b32_e32 v40, v34
	v_mov_b32_e32 v41, v34
	v_mov_b32_e32 v42, v34
	v_mov_b32_e32 v43, v34
	v_mov_b32_e32 v44, v34
	v_mov_b32_e32 v45, v34
	v_mov_b32_e32 v46, v34
	v_mov_b32_e32 v47, v34
	v_mov_b32_e32 v48, v34
	v_mov_b32_e32 v49, v34
	v_mov_b32_e32 v50, v34
	v_mov_b32_e32 v51, v34
	v_mov_b32_e32 v52, v34
	v_mov_b32_e32 v53, v34
	v_mov_b32_e32 v54, v34
	v_mov_b32_e32 v55, v34
	v_mov_b32_e32 v56, v34
	v_mov_b32_e32 v57, v34
	v_mov_b32_e32 v58, v34
	v_mov_b32_e32 v59, v34
	v_mov_b32_e32 v60, v34
	v_mov_b32_e32 v61, v34
	v_mov_b32_e32 v62, v34
	v_mov_b32_e32 v63, v34
	v_mov_b32_e32 v64, v34
	v_mov_b32_e32 v65, v34
	v_mov_b32_e32 v66, v34
	v_mov_b32_e32 v67, v34
	v_mov_b32_e32 v68, v34
	v_mov_b32_e32 v69, v34
	v_mov_b32_e32 v70, v34
	v_mov_b32_e32 v71, v34
	v_mov_b32_e32 v72, v34
	v_mov_b32_e32 v73, v34
	v_mov_b32_e32 v74, v34
	v_mov_b32_e32 v75, v34
	v_mov_b32_e32 v76, v34
	v_mov_b32_e32 v77, v34
	v_mov_b32_e32 v78, v34
	v_mov_b32_e32 v79, v34
	v_mov_b32_e32 v80, v34
	v_mov_b32_e32 v81, v34
	v_mov_b32_e32 v82, v34
	v_mov_b32_e32 v83, v34
	v_mov_b32_e32 v84, v34
	v_mov_b32_e32 v85, v34
	v_mov_b32_e32 v86, v34
	v_mov_b32_e32 v87, v34
	v_mov_b32_e32 v88, v34
	v_mov_b32_e32 v89, v34
	v_mov_b32_e32 v90, v34
	v_mov_b32_e32 v91, v34
	v_mov_b32_e32 v92, v34
	v_mov_b32_e32 v93, v34
	v_mov_b32_e32 v94, v34
	v_mov_b32_e32 v95, v34
	v_mov_b32_e32 v96, v34
	v_mov_b32_e32 v97, v34
	v_lshlrev_b32_e32 v232, 1, v103
	v_add_u32_e32 v233, 0x10000, v232
	v_add_u32_e32 v234, 0x20000, v232
	v_add_u32_e32 v235, 0x30000, v232
	v_lshlrev_b32_e32 v236, 1, v104
	v_add_u32_e32 v237, 0x10000, v236
	v_add_u32_e32 v238, 0x20000, v236
	v_add_u32_e32 v239, 0x30000, v236
	v_readfirstlane_b32 s68, v102
	s_add_u32 s64, s14, 0x80
	s_addc_u32 s65, s15, 0
	s_add_u32 s66, s8, 0x80
	s_addc_u32 s67, s9, 0
	s_waitcnt vmcnt(0) lgkmcnt(0)
	s_barrier
.LBB0_1485:
	s_and_b32 s10, s40, 0x8000
	v_or_b32_e32 v0, s10, v101
	v_add_u32_e32 v105, v0, v100
	v_add_u32_e32 v0, v0, v98
	ds_read_b128 v[126:129], v0 offset:16384
	ds_read_b128 v[130:133], v0 offset:18432
	ds_read_b128 v[134:137], v0 offset:20480
	ds_read_b128 v[138:141], v0 offset:22528
	v_or_b32_e32 v0, s10, v99
	ds_read_b128 v[106:109], v105
	ds_read_b128 v[110:113], v105 offset:2048
	ds_read_b128 v[114:117], v105 offset:4096
	ds_read_b128 v[118:121], v105 offset:6144
	s_add_i32 s41, s40, 0x8000
	s_and_b32 s69, s41, 0x8000
	s_add_i32 s69, s69, s68
	v_add_u32_e32 v105, v0, v100
	v_add_u32_e32 v0, v0, v98
	s_mov_b32 m0, s69
	s_nop 0
	global_load_lds_dwordx4 v232, s[64:65]
	ds_read_b128 v[142:145], v105
	s_add_i32 m0, s69, 0x1000
	s_nop 0
	global_load_lds_dwordx4 v233, s[64:65]
	ds_read_b128 v[146:149], v105 offset:2048
	s_add_i32 m0, s69, 0x2000
	s_nop 0
	global_load_lds_dwordx4 v234, s[64:65]
	ds_read_b128 v[150:153], v105 offset:4096
	s_add_i32 m0, s69, 0x3000
	s_nop 0
	global_load_lds_dwordx4 v235, s[64:65]
	ds_read_b128 v[192:195], v105 offset:6144
	s_add_i32 m0, s69, 0x4000
	s_nop 0
	global_load_lds_dwordx4 v236, s[66:67]
	ds_read_b128 v[196:199], v0 offset:16384
	s_add_i32 m0, s69, 0x5000
	s_nop 0
	global_load_lds_dwordx4 v237, s[66:67]
	ds_read_b128 v[200:203], v0 offset:18432
	s_add_i32 m0, s69, 0x6000
	s_nop 0
	global_load_lds_dwordx4 v238, s[66:67]
	ds_read_b128 v[204:207], v0 offset:20480
	s_add_i32 m0, s69, 0x7000
	s_nop 0
	global_load_lds_dwordx4 v239, s[66:67]
	ds_read_b128 v[208:211], v0 offset:22528
	s_add_u32 s64, s64, 0x80
	s_addc_u32 s65, s65, 0
	s_add_u32 s66, s66, 0x80
	s_addc_u32 s67, s67, 0
	s_setprio 1
	s_waitcnt lgkmcnt(11)
	v_mfma_f32_16x16x32_bf16 v[94:97], v[126:129], v[106:109], v[94:97]
	v_mfma_f32_16x16x32_bf16 v[90:93], v[130:133], v[106:109], v[90:93]
	v_mfma_f32_16x16x32_bf16 v[86:89], v[134:137], v[106:109], v[86:89]
	v_mfma_f32_16x16x32_bf16 v[82:85], v[138:141], v[106:109], v[82:85]
	s_waitcnt lgkmcnt(10)
	v_mfma_f32_16x16x32_bf16 v[78:81], v[126:129], v[110:113], v[78:81]
	v_mfma_f32_16x16x32_bf16 v[74:77], v[130:133], v[110:113], v[74:77]
	v_mfma_f32_16x16x32_bf16 v[70:73], v[134:137], v[110:113], v[70:73]
	v_mfma_f32_16x16x32_bf16 v[66:69], v[138:141], v[110:113], v[66:69]
	s_waitcnt lgkmcnt(9)
; DEVI int k_rot(int mt, int nt, int nk) { return (((mt & 7) + (nt & 7)) & 7) * nk >> 3; }
;     ...
;     if (DEEP) {
;     bf16x8 af[2][4], bfr[2][NF];
; #pragma unroll
;     for (int ks = 0; ks < 2; ++ks) {
;       const int co = ((ks * 4 + fq) ^ swz) * 16;
; #pragma unroll
;       for (int m = 0; m < 4; ++m) af[ks][m] = *(const bf16x8*)(As + (wr * 64 + m * 16 + fr) * 128 + co);
; #pragma unroll
;       for (int n = 0; n < NF; ++n) bfr[ks][n] = *(const bf16x8*)(Bs + (wc * 16 * NF + n * 16 + fr) * 128 + co);
;     }
;     __builtin_amdgcn_s_setprio(1);
; #pragma unroll
;     for (int ks = 0; ks < 2; ++ks)
; #pragma unroll
;       for (int m = 0; m < 4; ++m)
; #pragma unroll
;         for (int n = 0; n < NF; ++n) {
;           if (SWAP) acc[m][n] = __builtin_amdgcn_mfma_f32_16x16x32_bf16(bfr[ks][n], af[ks][m], acc[m][n], 0, 0, 0);
;           else acc[m][n] = __builtin_amdgcn_mfma_f32_16x16x32_bf16(af[ks][m], bfr[ks][n], acc[m][n], 0, 0, 0);
;         }
;     __builtin_amdgcn_s_setprio(0);
;     __builtin_amdgcn_sched_group_barrier(0x100, 4 + NF, 0);
; #pragma unroll
;     for (int i = 0; i < 4 + NF; ++i) { __builtin_amdgcn_sched_group_barrier(0x008, 2, 0); __builtin_amdgcn_sched_group_barrier(0x100, 1, 0); }
;     __builtin_amdgcn_sched_group_barrier(0x008, 8 * NF - 2 * (4 + NF), 0);
; template <int EPI>
; DEVI void phase_gemm(const Params& p, const bf16* A, int lda, const bf16* Bt, int K, int NT, bf16* dst, int ldd, char* smem, bool nostore = false,
;                      const float* lng = nullptr, const float* lnb = nullptr) {
;     ...
;   for (; t < 256 * NT; t += gridDim.x) {
;     int mt, nt; tile_swz(t, 256, NT, mt, nt);
;     f32x4 acc[4][4]; zero_acc(acc);
;     gemm_mainloop_g<4, true, RowLinear, true, DEEP_FRAG != 0>(acc, A, RowLinear{lda}, 64, Bt, K, K, mt * 128, nt * 128, smem, KROT ? k_rot(mt, nt, K >> 6) : 0);
;     if (t + (int)gridDim.x < 256 * NT) {
	v_mfma_f32_16x16x32_bf16 v[62:65], v[126:129], v[114:117], v[62:65]
	v_mfma_f32_16x16x32_bf16 v[58:61], v[130:133], v[114:117], v[58:61]
	v_mfma_f32_16x16x32_bf16 v[54:57], v[134:137], v[114:117], v[54:57]
	v_mfma_f32_16x16x32_bf16 v[50:53], v[138:141], v[114:117], v[50:53]
	s_waitcnt lgkmcnt(8)
	v_mfma_f32_16x16x32_bf16 v[46:49], v[126:129], v[118:121], v[46:49]
	v_mfma_f32_16x16x32_bf16 v[42:45], v[130:133], v[118:121], v[42:45]
	v_mfma_f32_16x16x32_bf16 v[38:41], v[134:137], v[118:121], v[38:41]
	v_mfma_f32_16x16x32_bf16 v[34:37], v[138:141], v[118:121], v[34:37]
	s_waitcnt lgkmcnt(3)
	v_mfma_f32_16x16x32_bf16 v[94:97], v[196:199], v[142:145], v[94:97]
	s_waitcnt lgkmcnt(2)
	v_mfma_f32_16x16x32_bf16 v[90:93], v[200:203], v[142:145], v[90:93]
	s_waitcnt lgkmcnt(1)
	v_mfma_f32_16x16x32_bf16 v[86:89], v[204:207], v[142:145], v[86:89]
	s_waitcnt lgkmcnt(0)
	v_mfma_f32_16x16x32_bf16 v[82:85], v[208:211], v[142:145], v[82:85]
	v_mfma_f32_16x16x32_bf16 v[78:81], v[196:199], v[146:149], v[78:81]
	v_mfma_f32_16x16x32_bf16 v[74:77], v[200:203], v[146:149], v[74:77]
	v_mfma_f32_16x16x32_bf16 v[70:73], v[204:207], v[146:149], v[70:73]
	v_mfma_f32_16x16x32_bf16 v[66:69], v[208:211], v[146:149], v[66:69]
	v_mfma_f32_16x16x32_bf16 v[62:65], v[196:199], v[150:153], v[62:65]
	v_mfma_f32_16x16x32_bf16 v[58:61], v[200:203], v[150:153], v[58:61]
	v_mfma_f32_16x16x32_bf16 v[54:57], v[204:207], v[150:153], v[54:57]
	v_mfma_f32_16x16x32_bf16 v[50:53], v[208:211], v[150:153], v[50:53]
	v_mfma_f32_16x16x32_bf16 v[46:49], v[196:199], v[192:195], v[46:49]
	v_mfma_f32_16x16x32_bf16 v[42:45], v[200:203], v[192:195], v[42:45]
	v_mfma_f32_16x16x32_bf16 v[38:41], v[204:207], v[192:195], v[38:41]
	v_mfma_f32_16x16x32_bf16 v[34:37], v[208:211], v[192:195], v[34:37]
	s_setprio 0
	s_waitcnt vmcnt(0)
	s_add_i32 s37, s37, 64
	s_cmpk_eq_i32 s37, 0x3c0
	s_mov_b32 s40, s41
	s_waitcnt vmcnt(0)
	s_barrier
	s_cbranch_scc0 .LBB0_1485
	v_add_u32_e32 v0, v101, v100
	ds_read_b128 v[102:105], v0 offset:32768
	ds_read_b128 v[106:109], v0 offset:34816
	ds_read_b128 v[110:113], v0 offset:36864
	ds_read_b128 v[114:117], v0 offset:38912
	v_add_u32_e32 v0, v101, v98
	ds_read_b128 v[118:121], v0 offset:49152
	ds_read_b128 v[126:129], v0 offset:51200
	ds_read_b128 v[130:133], v0 offset:53248
	ds_read_b128 v[134:137], v0 offset:55296
	v_add_u32_e32 v0, v99, v100
	ds_read_b128 v[138:141], v0 offset:32768
	ds_read_b128 v[142:145], v0 offset:34816
	ds_read_b128 v[146:149], v0 offset:36864
	ds_read_b128 v[150:153], v0 offset:38912
	v_add_u32_e32 v0, v99, v98
	ds_read_b128 v[98:101], v0 offset:49152
	ds_read_b128 v[192:195], v0 offset:51200
	ds_read_b128 v[196:199], v0 offset:53248
	ds_read_b128 v[200:203], v0 offset:55296
	s_setprio 1
	s_waitcnt lgkmcnt(11)
	v_mfma_f32_16x16x32_bf16 v[94:97], v[118:121], v[102:105], v[94:97]
	s_waitcnt lgkmcnt(10)
	v_mfma_f32_16x16x32_bf16 v[90:93], v[126:129], v[102:105], v[90:93]
	s_waitcnt lgkmcnt(9)
	v_mfma_f32_16x16x32_bf16 v[86:89], v[130:133], v[102:105], v[86:89]
	s_waitcnt lgkmcnt(8)
	v_mfma_f32_16x16x32_bf16 v[82:85], v[134:137], v[102:105], v[82:85]
	v_mfma_f32_16x16x32_bf16 v[78:81], v[118:121], v[106:109], v[78:81]
	v_mfma_f32_16x16x32_bf16 v[74:77], v[126:129], v[106:109], v[74:77]
	v_mfma_f32_16x16x32_bf16 v[70:73], v[130:133], v[106:109], v[70:73]
	v_mfma_f32_16x16x32_bf16 v[66:69], v[134:137], v[106:109], v[66:69]
	v_mfma_f32_16x16x32_bf16 v[62:65], v[118:121], v[110:113], v[62:65]
	v_mfma_f32_16x16x32_bf16 v[58:61], v[126:129], v[110:113], v[58:61]
	v_mfma_f32_16x16x32_bf16 v[54:57], v[130:133], v[110:113], v[54:57]
	v_mfma_f32_16x16x32_bf16 v[50:53], v[134:137], v[110:113], v[50:53]
	v_mfma_f32_16x16x32_bf16 v[46:49], v[118:121], v[114:117], v[46:49]
	v_mfma_f32_16x16x32_bf16 v[42:45], v[126:129], v[114:117], v[42:45]
	v_mfma_f32_16x16x32_bf16 v[38:41], v[130:133], v[114:117], v[38:41]
	v_mfma_f32_16x16x32_bf16 v[34:37], v[134:137], v[114:117], v[34:37]
	s_waitcnt lgkmcnt(3)
	v_mfma_f32_16x16x32_bf16 v[94:97], v[98:101], v[138:141], v[94:97]
	s_waitcnt lgkmcnt(2)
	v_mfma_f32_16x16x32_bf16 v[90:93], v[192:195], v[138:141], v[90:93]
	s_waitcnt lgkmcnt(1)
	v_mfma_f32_16x16x32_bf16 v[86:89], v[196:199], v[138:141], v[86:89]
	s_waitcnt lgkmcnt(0)
	v_mfma_f32_16x16x32_bf16 v[82:85], v[200:203], v[138:141], v[82:85]
	v_mfma_f32_16x16x32_bf16 v[78:81], v[98:101], v[142:145], v[78:81]
	v_mfma_f32_16x16x32_bf16 v[74:77], v[192:195], v[142:145], v[74:77]
	v_mfma_f32_16x16x32_bf16 v[70:73], v[196:199], v[142:145], v[70:73]
	v_mfma_f32_16x16x32_bf16 v[66:69], v[200:203], v[142:145], v[66:69]
	v_mfma_f32_16x16x32_bf16 v[62:65], v[98:101], v[146:149], v[62:65]
	v_mfma_f32_16x16x32_bf16 v[58:61], v[192:195], v[146:149], v[58:61]
	v_mfma_f32_16x16x32_bf16 v[54:57], v[196:199], v[146:149], v[54:57]
	v_mfma_f32_16x16x32_bf16 v[50:53], v[200:203], v[146:149], v[50:53]
	v_mfma_f32_16x16x32_bf16 v[46:49], v[98:101], v[150:153], v[46:49]
	v_mfma_f32_16x16x32_bf16 v[42:45], v[192:195], v[150:153], v[42:45]
	v_mfma_f32_16x16x32_bf16 v[38:41], v[196:199], v[150:153], v[38:41]
	v_mfma_f32_16x16x32_bf16 v[34:37], v[200:203], v[150:153], v[34:37]
	s_setprio 0
	s_waitcnt vmcnt(0)
	s_add_i32 s42, s42, s20
	s_cmpk_gt_i32 s42, 0x7ff
	s_cselect_b64 s[40:41], -1, 0
	s_cmpk_lt_i32 s42, 0x800
	s_barrier
; DEVI int opaque_tid() { int t = __builtin_amdgcn_workitem_id_x(); asm volatile("" : "+v"(t)); return t; }
; DEVI int k_rot(int mt, int nt, int nk) { return (((mt & 7) + (nt & 7)) & 7) * nk >> 3; }
;   const int tid = opaque_tid();
;   const int lrow = tid >> 3, lpos = tid & 7;
;   const int gch = (lpos ^ (lrow & 7)) * 8 + koff * 64;
;   char* ab = smem + tid * 16;
; #pragma unroll
;   for (int i = 0; i < 4; ++i)
;     __builtin_amdgcn_global_load_lds((const unsigned*)(A + (unsigned)(arow(m0 + lrow + 32 * i) + gch)), (unsigned*)(ab + i * 4096), 16, 0, 0);
; #pragma unroll
;   for (int i = 0; i < NF; ++i)
;     __builtin_amdgcn_global_load_lds((const unsigned*)(Bt + (unsigned)((n0 + lrow + 32 * i) * ldb + gch)), (unsigned*)(ab + 16384 + i * 4096), 16, 0, 0);
; }
; template <int EPI>
; DEVI void phase_gemm(const Params& p, const bf16* A, int lda, const bf16* Bt, int K, int NT, bf16* dst, int ldd, char* smem, bool nostore = false,
;                      const float* lng = nullptr, const float* lnb = nullptr) {
;     ...
;     if (t + (int)gridDim.x < 256 * NT) {
;       int mt2, nt2; tile_swz(t + gridDim.x, 256, NT, mt2, nt2);
;       gemm_prefetch0<4>(A, RowLinear{lda}, Bt, K, mt2 * 128, nt2 * 128, smem, KROT ? k_rot(mt2, nt2, K >> 6) : 0);
;     }
	s_cbranch_scc0 .LBB0_1488
	s_lshl_b32 s10, s42, 8
	s_and_b32 s10, s10, 0x700
	s_ashr_i32 s11, s42, 3
	s_add_i32 s10, s10, s11
	s_ashr_i32 s37, s10, 31
	s_lshr_b32 s37, s37, 26
	s_add_i32 s37, s10, s37
	v_mov_b32_e32 v0, v154
	s_lshl_b32 s37, s37, 4
	s_lshl_b32 s11, s11, 7
	s_and_b32 s37, s37, 0xfffffc00
	v_ashrrev_i32_e32 v100, 3, v0
	s_and_b32 s11, s11, 0x380
	v_xor_b32_e32 v98, v100, v0
	s_or_b32 s11, s37, s11
	v_lshlrev_b32_e32 v98, 3, v98
	v_and_b32_e32 v101, 56, v98
	v_lshlrev_b32_e32 v102, 4, v0
	v_add_u32_e32 v0, s11, v100
	v_lshl_or_b32 v0, v0, 10, v101
	v_readfirstlane_b32 s11, v102
	v_lshl_add_u64 v[98:99], v[0:1], 1, s[14:15]
	s_mov_b32 m0, s11
	v_add_u32_e32 v103, 0x1000, v102
	global_load_lds_dwordx4 v[98:99], off
	v_add_u32_e32 v98, 0x8000, v0
	v_mov_b32_e32 v99, v1
	v_readfirstlane_b32 s11, v103
	v_lshl_add_u64 v[98:99], v[98:99], 1, s[14:15]
	s_mov_b32 m0, s11
	v_add_u32_e32 v103, 0x2000, v102
	s_lshl_b32 s10, s10, 4
	global_load_lds_dwordx4 v[98:99], off
	v_add_u32_e32 v98, 0x10000, v0
	v_mov_b32_e32 v99, v1
	v_readfirstlane_b32 s11, v103
	s_sub_i32 s10, s10, s37
	v_lshl_add_u64 v[98:99], v[98:99], 1, s[14:15]
	s_mov_b32 m0, s11
	v_add_u32_e32 v0, 0x18000, v0
	s_and_b32 s10, s10, 0x3fff80
	global_load_lds_dwordx4 v[98:99], off
	v_lshl_add_u64 v[98:99], v[0:1], 1, s[14:15]
	v_add_u32_e32 v0, 0x3000, v102
	s_nop 0
	v_readfirstlane_b32 s11, v0
	v_add_u32_e32 v0, s10, v100
	v_add_u32_e32 v100, 0x4000, v102
	s_mov_b32 m0, s11
	v_lshl_or_b32 v0, v0, 10, v101
	v_readfirstlane_b32 s10, v100
	global_load_lds_dwordx4 v[98:99], off
	v_lshl_add_u64 v[98:99], v[0:1], 1, s[8:9]
	s_mov_b32 m0, s10
	v_add_u32_e32 v100, 0x5000, v102
	global_load_lds_dwordx4 v[98:99], off
	v_add_u32_e32 v98, 0x8000, v0
	v_mov_b32_e32 v99, v1
	v_readfirstlane_b32 s10, v100
	v_lshl_add_u64 v[98:99], v[98:99], 1, s[8:9]
	s_mov_b32 m0, s10
	v_add_u32_e32 v100, 0x6000, v102
	global_load_lds_dwordx4 v[98:99], off
	v_add_u32_e32 v98, 0x10000, v0
	v_mov_b32_e32 v99, v1
	v_readfirstlane_b32 s10, v100
	v_lshl_add_u64 v[98:99], v[98:99], 1, s[8:9]
	s_mov_b32 m0, s10
	v_add_u32_e32 v0, 0x18000, v0
	global_load_lds_dwordx4 v[98:99], off
	v_lshl_add_u64 v[98:99], v[0:1], 1, s[8:9]
	v_add_u32_e32 v0, 0x7000, v102
	s_nop 0
	v_readfirstlane_b32 s10, v0
	s_mov_b32 m0, s10
	s_nop 0
	global_load_lds_dwordx4 v[98:99], off

; DEVI int k_rot(int mt, int nt, int nk) { return (((mt & 7) + (nt & 7)) & 7) * nk >> 3; }
;     ...
;   if (!PRE) GL_ISSUE(0, 0)
;   asm volatile("s_waitcnt vmcnt(0)" ::: "memory");
;   __syncthreads();
;   const int swz = fr & 7;
;   for (int kt = 0; kt < nk; ++kt) {
;     if (kt + 1 < nk) GL_ISSUE(kt + 1, (kt + 1) & 1)
;     const char* As = smem + (kt & 1) * 32768;
;     const char* Bs = As + 16384;
;     if (DEEP) {
;     bf16x8 af[2][4], bfr[2][NF];
; #pragma unroll
;     for (int ks = 0; ks < 2; ++ks) {
;       const int co = ((ks * 4 + fq) ^ swz) * 16;
; #pragma unroll
;       for (int m = 0; m < 4; ++m) af[ks][m] = *(const bf16x8*)(As + (wr * 64 + m * 16 + fr) * 128 + co);
; #pragma unroll
;       for (int n = 0; n < NF; ++n) bfr[ks][n] = *(const bf16x8*)(Bs + (wc * 16 * NF + n * 16 + fr) * 128 + co);
;     }
;     __builtin_amdgcn_s_setprio(1);
; #pragma unroll
;     for (int ks = 0; ks < 2; ++ks)
; #pragma unroll
;       for (int m = 0; m < 4; ++m)
; #pragma unroll
;         for (int n = 0; n < NF; ++n) {
;           if (SWAP) acc[m][n] = __builtin_amdgcn_mfma_f32_16x16x32_bf16(bfr[ks][n], af[ks][m], acc[m][n], 0, 0, 0);
;           else acc[m][n] = __builtin_amdgcn_mfma_f32_16x16x32_bf16(af[ks][m], bfr[ks][n], acc[m][n], 0, 0, 0);
;         }
;     __builtin_amdgcn_s_setprio(0);
;     __builtin_amdgcn_sched_group_barrier(0x100, 4 + NF, 0);
; #pragma unroll
;     for (int i = 0; i < 4 + NF; ++i) { __builtin_amdgcn_sched_group_barrier(0x008, 2, 0); __builtin_amdgcn_sched_group_barrier(0x100, 1, 0); }
;     __builtin_amdgcn_sched_group_barrier(0x008, 8 * NF - 2 * (4 + NF), 0);
; template <int EPI>
; DEVI void phase_gemm(const Params& p, const bf16* A, int lda, const bf16* Bt, int K, int NT, bf16* dst, int ldd, char* smem, bool nostore = false,
;                      const float* lng = nullptr, const float* lnb = nullptr) {
;     ...
;   for (; t < 256 * NT; t += gridDim.x) {
;     int mt, nt; tile_swz(t, 256, NT, mt, nt);
;     f32x4 acc[4][4]; zero_acc(acc);
;     gemm_mainloop_g<4, true, RowLinear, true, DEEP_FRAG != 0>(acc, A, RowLinear{lda}, 64, Bt, K, K, mt * 128, nt * 128, smem, KROT ? k_rot(mt, nt, K >> 6) : 0);
.LBB0_1614:
	s_lshl_b32 s11, s40, 6
	s_and_b32 s41, s11, 0x1c0
	s_ashr_i32 s11, s40, 3
	s_add_i32 s41, s41, s11
	s_ashr_i32 s38, s41, 31
	s_lshr_b32 s38, s38, 28
	s_lshl_b32 s10, s13, 4
	s_add_i32 s38, s41, s38
	s_and_b32 s10, s10, 0x1c00
	s_ashr_i32 s38, s38, 4
	s_lshl_b32 s42, s11, 7
	v_mov_b32_e32 v0, v154
	s_lshl_b32 s11, s11, 4
	s_and_b32 s43, s42, 0x380
	s_lshl_b32 s42, s38, 8
	s_add_i32 s10, s10, s11
	v_ashrrev_i32_e32 v3, 3, v0
	v_lshrrev_b32_e32 v2, 4, v0
	v_xor_b32_e32 v4, v3, v0
	v_bfe_u32 v5, v0, 4, 2
	v_and_b32_e32 v6, 7, v0
	v_and_b32_e32 v7, 15, v0
	v_lshlrev_b32_e32 v70, 4, v0
	v_lshrrev_b32_e32 v8, 1, v0
	v_lshlrev_b32_e32 v0, 7, v0
	s_sub_i32 s10, s10, s42
	v_and_b32_e32 v66, 0x2780, v0
	v_bitop3_b32 v0, v2, v6, 3 bitop3:0x6c
	s_lshl_b32 s10, s10, 10
	s_lshl_b32 s39, s38, 10
	v_lshlrev_b32_e32 v4, 3, v4
	v_lshlrev_b32_e32 v69, 4, v0
	v_bitop3_b32 v0, v5, v6, 4 bitop3:0x36
	s_and_b32 s10, s10, 0xfffe0000
	v_and_b32_e32 v4, 56, v4
	s_waitcnt vmcnt(0)
	v_lshlrev_b32_e32 v67, 4, v0
	v_lshl_add_u32 v0, v3, 10, s10
	s_or_b32 s43, s43, s39
	v_and_or_b32 v7, v8, s79, v7
	v_or_b32_e32 v71, v0, v4
	v_add_u32_e32 v0, s43, v3
	v_mov_b32_e32 v2, 0
	v_lshlrev_b32_e32 v68, 7, v7
	v_lshl_or_b32 v72, v0, 10, v4
	s_mov_b32 s39, 0
	s_mov_b32 s38, 0
	v_mov_b32_e32 v3, v2
	v_mov_b32_e32 v4, v2
	v_mov_b32_e32 v5, v2
	v_mov_b32_e32 v6, v2
	v_mov_b32_e32 v7, v2
	v_mov_b32_e32 v8, v2
	v_mov_b32_e32 v9, v2
	v_mov_b32_e32 v10, v2
	v_mov_b32_e32 v11, v2
	v_mov_b32_e32 v12, v2
	v_mov_b32_e32 v13, v2
	v_mov_b32_e32 v14, v2
	v_mov_b32_e32 v15, v2
	v_mov_b32_e32 v16, v2
	v_mov_b32_e32 v17, v2
	v_mov_b32_e32 v18, v2
	v_mov_b32_e32 v19, v2
	v_mov_b32_e32 v20, v2
	v_mov_b32_e32 v21, v2
	v_mov_b32_e32 v22, v2
	v_mov_b32_e32 v23, v2
	v_mov_b32_e32 v24, v2
	v_mov_b32_e32 v25, v2
	v_mov_b32_e32 v26, v2
	v_mov_b32_e32 v27, v2
	v_mov_b32_e32 v28, v2
	v_mov_b32_e32 v29, v2
	v_mov_b32_e32 v30, v2
	v_mov_b32_e32 v31, v2
	v_mov_b32_e32 v32, v2
	v_mov_b32_e32 v33, v2
	v_mov_b32_e32 v34, v2
	v_mov_b32_e32 v35, v2
	v_mov_b32_e32 v36, v2
	v_mov_b32_e32 v37, v2
	v_mov_b32_e32 v38, v2
	v_mov_b32_e32 v39, v2
	v_mov_b32_e32 v40, v2
	v_mov_b32_e32 v41, v2
	v_mov_b32_e32 v42, v2
	v_mov_b32_e32 v43, v2
	v_mov_b32_e32 v44, v2
	v_mov_b32_e32 v45, v2
	v_mov_b32_e32 v46, v2
	v_mov_b32_e32 v47, v2
	v_mov_b32_e32 v48, v2
	v_mov_b32_e32 v49, v2
	v_mov_b32_e32 v58, v2
	v_mov_b32_e32 v59, v2
	v_mov_b32_e32 v60, v2
	v_mov_b32_e32 v61, v2
	v_mov_b32_e32 v62, v2
	v_mov_b32_e32 v63, v2
	v_mov_b32_e32 v64, v2
	v_mov_b32_e32 v65, v2
	v_mov_b32_e32 v50, v2
	v_mov_b32_e32 v51, v2
	v_mov_b32_e32 v52, v2
	v_mov_b32_e32 v53, v2
	v_mov_b32_e32 v54, v2
	v_mov_b32_e32 v55, v2
	v_mov_b32_e32 v56, v2
	v_mov_b32_e32 v57, v2
	v_lshlrev_b32_e32 v232, 1, v72
	v_add_u32_e32 v233, 0x10000, v232
	v_add_u32_e32 v234, 0x20000, v232
	v_add_u32_e32 v235, 0x30000, v232
	v_lshlrev_b32_e32 v236, 1, v71
	v_add_u32_e32 v237, 0x10000, v236
	v_add_u32_e32 v238, 0x20000, v236
	v_add_u32_e32 v239, 0x30000, v236
	v_readfirstlane_b32 s68, v70
	s_add_u32 s64, s8, 0x80
	s_addc_u32 s65, s9, 0
	s_add_u32 s66, s36, 0x80
	s_addc_u32 s67, s37, 0
	s_waitcnt vmcnt(0) lgkmcnt(0)
	s_barrier
.LBB0_1615:
	s_and_b32 s10, s39, 0x8000
	v_or_b32_e32 v0, s10, v69
	v_add_u32_e32 v73, v0, v68
	v_add_u32_e32 v0, v0, v66
	ds_read_b128 v[90:93], v0 offset:16384
	ds_read_b128 v[94:97], v0 offset:18432
	ds_read_b128 v[98:101], v0 offset:20480
	ds_read_b128 v[102:105], v0 offset:22528
	v_or_b32_e32 v0, s10, v67
	ds_read_b128 v[74:77], v73
	ds_read_b128 v[78:81], v73 offset:2048
	ds_read_b128 v[82:85], v73 offset:4096
	ds_read_b128 v[86:89], v73 offset:6144
	s_add_i32 s50, s39, 0x8000
	s_and_b32 s69, s50, 0x8000
	s_add_i32 s69, s69, s68
	v_add_u32_e32 v73, v0, v68
	v_add_u32_e32 v0, v0, v66
	s_mov_b32 m0, s69
	s_nop 0
	global_load_lds_dwordx4 v232, s[64:65]
	ds_read_b128 v[106:109], v73
	s_add_i32 m0, s69, 0x1000
	s_nop 0
	global_load_lds_dwordx4 v233, s[64:65]
	ds_read_b128 v[110:113], v73 offset:2048
	s_add_i32 m0, s69, 0x2000
	s_nop 0
	global_load_lds_dwordx4 v234, s[64:65]
	ds_read_b128 v[114:117], v73 offset:4096
	s_add_i32 m0, s69, 0x3000
	s_nop 0
	global_load_lds_dwordx4 v235, s[64:65]
	ds_read_b128 v[118:121], v73 offset:6144
	s_add_i32 m0, s69, 0x4000
	s_nop 0
	global_load_lds_dwordx4 v236, s[66:67]
	ds_read_b128 v[126:129], v0 offset:16384
	s_add_i32 m0, s69, 0x5000
	s_nop 0
	global_load_lds_dwordx4 v237, s[66:67]
	ds_read_b128 v[130:133], v0 offset:18432
	s_add_i32 m0, s69, 0x6000
	s_nop 0
	global_load_lds_dwordx4 v238, s[66:67]
	ds_read_b128 v[134:137], v0 offset:20480
	s_add_i32 m0, s69, 0x7000
	s_nop 0
	global_load_lds_dwordx4 v239, s[66:67]
	ds_read_b128 v[138:141], v0 offset:22528
	s_add_u32 s64, s64, 0x80
	s_addc_u32 s65, s65, 0
	s_add_u32 s66, s66, 0x80
	s_addc_u32 s67, s67, 0
	s_setprio 1
	s_waitcnt lgkmcnt(11)
	v_mfma_f32_16x16x32_bf16 v[62:65], v[90:93], v[74:77], v[62:65]
	v_mfma_f32_16x16x32_bf16 v[58:61], v[94:97], v[74:77], v[58:61]
	v_mfma_f32_16x16x32_bf16 v[46:49], v[98:101], v[74:77], v[46:49]
	v_mfma_f32_16x16x32_bf16 v[42:45], v[102:105], v[74:77], v[42:45]
	s_waitcnt lgkmcnt(10)
	v_mfma_f32_16x16x32_bf16 v[38:41], v[90:93], v[78:81], v[38:41]
	v_mfma_f32_16x16x32_bf16 v[34:37], v[94:97], v[78:81], v[34:37]
	v_mfma_f32_16x16x32_bf16 v[30:33], v[98:101], v[78:81], v[30:33]
	v_mfma_f32_16x16x32_bf16 v[26:29], v[102:105], v[78:81], v[26:29]
	s_waitcnt lgkmcnt(9)
	v_mfma_f32_16x16x32_bf16 v[22:25], v[90:93], v[82:85], v[22:25]
	v_mfma_f32_16x16x32_bf16 v[18:21], v[94:97], v[82:85], v[18:21]
	v_mfma_f32_16x16x32_bf16 v[14:17], v[98:101], v[82:85], v[14:17]
	v_mfma_f32_16x16x32_bf16 v[10:13], v[102:105], v[82:85], v[10:13]
	s_waitcnt lgkmcnt(8)
; DEVI int k_rot(int mt, int nt, int nk) { return (((mt & 7) + (nt & 7)) & 7) * nk >> 3; }
;     ...
;     if (DEEP) {
;     bf16x8 af[2][4], bfr[2][NF];
; #pragma unroll
;     for (int ks = 0; ks < 2; ++ks) {
;       const int co = ((ks * 4 + fq) ^ swz) * 16;
; #pragma unroll
;       for (int m = 0; m < 4; ++m) af[ks][m] = *(const bf16x8*)(As + (wr * 64 + m * 16 + fr) * 128 + co);
; #pragma unroll
;       for (int n = 0; n < NF; ++n) bfr[ks][n] = *(const bf16x8*)(Bs + (wc * 16 * NF + n * 16 + fr) * 128 + co);
;     }
;     __builtin_amdgcn_s_setprio(1);
; #pragma unroll
;     for (int ks = 0; ks < 2; ++ks)
; #pragma unroll
;       for (int m = 0; m < 4; ++m)
; #pragma unroll
;         for (int n = 0; n < NF; ++n) {
;           if (SWAP) acc[m][n] = __builtin_amdgcn_mfma_f32_16x16x32_bf16(bfr[ks][n], af[ks][m], acc[m][n], 0, 0, 0);
;           else acc[m][n] = __builtin_amdgcn_mfma_f32_16x16x32_bf16(af[ks][m], bfr[ks][n], acc[m][n], 0, 0, 0);
;         }
;     __builtin_amdgcn_s_setprio(0);
;     __builtin_amdgcn_sched_group_barrier(0x100, 4 + NF, 0);
; #pragma unroll
;     for (int i = 0; i < 4 + NF; ++i) { __builtin_amdgcn_sched_group_barrier(0x008, 2, 0); __builtin_amdgcn_sched_group_barrier(0x100, 1, 0); }
;     __builtin_amdgcn_sched_group_barrier(0x008, 8 * NF - 2 * (4 + NF), 0);
; template <int EPI>
; DEVI void phase_gemm(const Params& p, const bf16* A, int lda, const bf16* Bt, int K, int NT, bf16* dst, int ldd, char* smem, bool nostore = false,
;                      const float* lng = nullptr, const float* lnb = nullptr) {
;     ...
;   for (; t < 256 * NT; t += gridDim.x) {
;     int mt, nt; tile_swz(t, 256, NT, mt, nt);
;     f32x4 acc[4][4]; zero_acc(acc);
;     gemm_mainloop_g<4, true, RowLinear, true, DEEP_FRAG != 0>(acc, A, RowLinear{lda}, 64, Bt, K, K, mt * 128, nt * 128, smem, KROT ? k_rot(mt, nt, K >> 6) : 0);
;     if (t + (int)gridDim.x < 256 * NT) {
	v_mfma_f32_16x16x32_bf16 v[6:9], v[90:93], v[86:89], v[6:9]
	v_mfma_f32_16x16x32_bf16 v[2:5], v[94:97], v[86:89], v[2:5]
	v_mfma_f32_16x16x32_bf16 v[50:53], v[98:101], v[86:89], v[50:53]
	v_mfma_f32_16x16x32_bf16 v[54:57], v[102:105], v[86:89], v[54:57]
	s_waitcnt lgkmcnt(3)
	v_mfma_f32_16x16x32_bf16 v[62:65], v[126:129], v[106:109], v[62:65]
	s_waitcnt lgkmcnt(2)
	v_mfma_f32_16x16x32_bf16 v[58:61], v[130:133], v[106:109], v[58:61]
	s_waitcnt lgkmcnt(1)
	v_mfma_f32_16x16x32_bf16 v[46:49], v[134:137], v[106:109], v[46:49]
	s_waitcnt lgkmcnt(0)
	v_mfma_f32_16x16x32_bf16 v[42:45], v[138:141], v[106:109], v[42:45]
	v_mfma_f32_16x16x32_bf16 v[38:41], v[126:129], v[110:113], v[38:41]
	v_mfma_f32_16x16x32_bf16 v[34:37], v[130:133], v[110:113], v[34:37]
	v_mfma_f32_16x16x32_bf16 v[30:33], v[134:137], v[110:113], v[30:33]
	v_mfma_f32_16x16x32_bf16 v[26:29], v[138:141], v[110:113], v[26:29]
	v_mfma_f32_16x16x32_bf16 v[22:25], v[126:129], v[114:117], v[22:25]
	v_mfma_f32_16x16x32_bf16 v[18:21], v[130:133], v[114:117], v[18:21]
	v_mfma_f32_16x16x32_bf16 v[14:17], v[134:137], v[114:117], v[14:17]
	v_mfma_f32_16x16x32_bf16 v[10:13], v[138:141], v[114:117], v[10:13]
	v_mfma_f32_16x16x32_bf16 v[6:9], v[126:129], v[118:121], v[6:9]
	v_mfma_f32_16x16x32_bf16 v[2:5], v[130:133], v[118:121], v[2:5]
	v_mfma_f32_16x16x32_bf16 v[50:53], v[134:137], v[118:121], v[50:53]
	v_mfma_f32_16x16x32_bf16 v[54:57], v[138:141], v[118:121], v[54:57]
	s_setprio 0
	s_waitcnt vmcnt(0)
	s_add_i32 s38, s38, 64
	s_cmpk_eq_i32 s38, 0x3c0
	s_mov_b32 s39, s50
	s_waitcnt vmcnt(0)
	s_barrier
	s_cbranch_scc0 .LBB0_1615
	v_add_u32_e32 v0, v69, v68
	ds_read_b128 v[70:73], v0 offset:32768
	ds_read_b128 v[74:77], v0 offset:34816
	ds_read_b128 v[78:81], v0 offset:36864
	ds_read_b128 v[82:85], v0 offset:38912
	v_add_u32_e32 v0, v69, v66
	ds_read_b128 v[86:89], v0 offset:49152
	ds_read_b128 v[90:93], v0 offset:51200
	ds_read_b128 v[94:97], v0 offset:53248
	ds_read_b128 v[98:101], v0 offset:55296
	v_add_u32_e32 v0, v67, v68
	ds_read_b128 v[102:105], v0 offset:32768
	ds_read_b128 v[106:109], v0 offset:34816
	ds_read_b128 v[110:113], v0 offset:36864
	ds_read_b128 v[114:117], v0 offset:38912
	v_add_u32_e32 v0, v67, v66
	ds_read_b128 v[66:69], v0 offset:49152
	ds_read_b128 v[118:121], v0 offset:51200
	ds_read_b128 v[126:129], v0 offset:53248
	ds_read_b128 v[130:133], v0 offset:55296
	s_setprio 1
	s_waitcnt lgkmcnt(11)
	v_mfma_f32_16x16x32_bf16 v[62:65], v[86:89], v[70:73], v[62:65]
	s_waitcnt lgkmcnt(10)
	v_mfma_f32_16x16x32_bf16 v[58:61], v[90:93], v[70:73], v[58:61]
	s_waitcnt lgkmcnt(9)
	v_mfma_f32_16x16x32_bf16 v[46:49], v[94:97], v[70:73], v[46:49]
	s_waitcnt lgkmcnt(8)
	v_mfma_f32_16x16x32_bf16 v[42:45], v[98:101], v[70:73], v[42:45]
	v_mfma_f32_16x16x32_bf16 v[38:41], v[86:89], v[74:77], v[38:41]
	v_mfma_f32_16x16x32_bf16 v[34:37], v[90:93], v[74:77], v[34:37]
	v_mfma_f32_16x16x32_bf16 v[30:33], v[94:97], v[74:77], v[30:33]
	v_mfma_f32_16x16x32_bf16 v[26:29], v[98:101], v[74:77], v[26:29]
	v_mfma_f32_16x16x32_bf16 v[22:25], v[86:89], v[78:81], v[22:25]
	v_mfma_f32_16x16x32_bf16 v[18:21], v[90:93], v[78:81], v[18:21]
	v_mfma_f32_16x16x32_bf16 v[14:17], v[94:97], v[78:81], v[14:17]
	v_mfma_f32_16x16x32_bf16 v[10:13], v[98:101], v[78:81], v[10:13]
	v_mfma_f32_16x16x32_bf16 v[6:9], v[86:89], v[82:85], v[6:9]
	v_mfma_f32_16x16x32_bf16 v[2:5], v[90:93], v[82:85], v[2:5]
	v_mfma_f32_16x16x32_bf16 v[70:73], v[94:97], v[82:85], v[50:53]
	v_mfma_f32_16x16x32_bf16 v[74:77], v[98:101], v[82:85], v[54:57]
	s_waitcnt lgkmcnt(3)
	v_mfma_f32_16x16x32_bf16 v[62:65], v[66:69], v[102:105], v[62:65]
	s_waitcnt lgkmcnt(2)
	v_mfma_f32_16x16x32_bf16 v[58:61], v[118:121], v[102:105], v[58:61]
	s_waitcnt lgkmcnt(1)
	v_mfma_f32_16x16x32_bf16 v[54:57], v[126:129], v[102:105], v[46:49]
	s_waitcnt lgkmcnt(0)
	v_mfma_f32_16x16x32_bf16 v[50:53], v[130:133], v[102:105], v[42:45]
	v_mfma_f32_16x16x32_bf16 v[46:49], v[66:69], v[106:109], v[38:41]
	v_mfma_f32_16x16x32_bf16 v[42:45], v[118:121], v[106:109], v[34:37]
	v_mfma_f32_16x16x32_bf16 v[38:41], v[126:129], v[106:109], v[30:33]
	v_mfma_f32_16x16x32_bf16 v[34:37], v[130:133], v[106:109], v[26:29]
	v_mfma_f32_16x16x32_bf16 v[30:33], v[66:69], v[110:113], v[22:25]
	v_mfma_f32_16x16x32_bf16 v[26:29], v[118:121], v[110:113], v[18:21]
	v_mfma_f32_16x16x32_bf16 v[22:25], v[126:129], v[110:113], v[14:17]
	v_mfma_f32_16x16x32_bf16 v[18:21], v[130:133], v[110:113], v[10:13]
	v_mfma_f32_16x16x32_bf16 v[14:17], v[66:69], v[114:117], v[6:9]
	v_mfma_f32_16x16x32_bf16 v[10:13], v[118:121], v[114:117], v[2:5]
	v_mfma_f32_16x16x32_bf16 v[6:9], v[126:129], v[114:117], v[70:73]
	v_mfma_f32_16x16x32_bf16 v[2:5], v[130:133], v[114:117], v[74:77]
	s_setprio 0
	s_waitcnt vmcnt(0)
	s_add_i32 s40, s40, s20
	s_cmpk_gt_i32 s40, 0x1ff
	s_cselect_b64 s[38:39], -1, 0
	s_cmpk_lt_i32 s40, 0x200
	s_barrier
; DEVI int opaque_tid() { int t = __builtin_amdgcn_workitem_id_x(); asm volatile("" : "+v"(t)); return t; }
; DEVI int k_rot(int mt, int nt, int nk) { return (((mt & 7) + (nt & 7)) & 7) * nk >> 3; }
;   const int tid = opaque_tid();
;   const int lrow = tid >> 3, lpos = tid & 7;
;   const int gch = (lpos ^ (lrow & 7)) * 8 + koff * 64;
;   char* ab = smem + tid * 16;
; #pragma unroll
;   for (int i = 0; i < 4; ++i)
;     __builtin_amdgcn_global_load_lds((const unsigned*)(A + (unsigned)(arow(m0 + lrow + 32 * i) + gch)), (unsigned*)(ab + i * 4096), 16, 0, 0);
; #pragma unroll
;   for (int i = 0; i < NF; ++i)
;     __builtin_amdgcn_global_load_lds((const unsigned*)(Bt + (unsigned)((n0 + lrow + 32 * i) * ldb + gch)), (unsigned*)(ab + 16384 + i * 4096), 16, 0, 0);
; }
; template <int EPI>
; DEVI void phase_gemm(const Params& p, const bf16* A, int lda, const bf16* Bt, int K, int NT, bf16* dst, int ldd, char* smem, bool nostore = false,
;                      const float* lng = nullptr, const float* lnb = nullptr) {
;     ...
;     if (t + (int)gridDim.x < 256 * NT) {
;       int mt2, nt2; tile_swz(t + gridDim.x, 256, NT, mt2, nt2);
;       gemm_prefetch0<4>(A, RowLinear{lda}, Bt, K, mt2 * 128, nt2 * 128, smem, KROT ? k_rot(mt2, nt2, K >> 6) : 0);
;     }
	s_cbranch_scc0 .LBB0_1613
	s_lshl_b32 s10, s40, 6
	s_and_b32 s10, s10, 0x1c0
	s_ashr_i32 s11, s40, 3
	s_add_i32 s10, s10, s11
	s_ashr_i32 s50, s10, 31
	s_lshr_b32 s50, s50, 28
	s_add_i32 s50, s10, s50
	v_mov_b32_e32 v0, v154
	s_ashr_i32 s50, s50, 4
	s_lshl_b32 s11, s11, 7
	s_lshl_b32 s51, s50, 10
	v_ashrrev_i32_e32 v68, 3, v0
	s_and_b32 s11, s11, 0x380
	v_xor_b32_e32 v66, v68, v0
	s_or_b32 s11, s51, s11
	v_lshlrev_b32_e32 v66, 3, v66
	v_and_b32_e32 v69, 56, v66
	v_lshlrev_b32_e32 v70, 4, v0
	v_add_u32_e32 v0, s11, v68
	v_lshl_or_b32 v0, v0, 10, v69
	v_readfirstlane_b32 s11, v70
	v_lshl_add_u64 v[66:67], v[0:1], 1, s[8:9]
	s_mov_b32 m0, s11
	v_add_u32_e32 v71, 0x1000, v70
	global_load_lds_dwordx4 v[66:67], off
	v_add_u32_e32 v66, 0x8000, v0
	v_mov_b32_e32 v67, v1
	v_readfirstlane_b32 s11, v71
	v_lshl_add_u64 v[66:67], v[66:67], 1, s[8:9]
	s_mov_b32 m0, s11
	v_add_u32_e32 v71, 0x2000, v70
	s_lshl_b32 s50, s50, 8
	s_lshl_b32 s10, s10, 4
	global_load_lds_dwordx4 v[66:67], off
	v_add_u32_e32 v66, 0x10000, v0
	v_mov_b32_e32 v67, v1
	v_readfirstlane_b32 s11, v71
	s_sub_i32 s10, s10, s50
	v_lshl_add_u64 v[66:67], v[66:67], 1, s[8:9]
	s_mov_b32 m0, s11
	v_add_u32_e32 v0, 0x18000, v0
	s_and_b32 s10, s10, 0x3fff80
	global_load_lds_dwordx4 v[66:67], off
	v_lshl_add_u64 v[66:67], v[0:1], 1, s[8:9]
	v_add_u32_e32 v0, 0x3000, v70
	s_nop 0
	v_readfirstlane_b32 s11, v0
	v_add_u32_e32 v0, s10, v68
	v_add_u32_e32 v68, 0x4000, v70
	s_mov_b32 m0, s11
	v_lshl_or_b32 v0, v0, 10, v69
	v_readfirstlane_b32 s10, v68
	global_load_lds_dwordx4 v[66:67], off
	v_lshl_add_u64 v[66:67], v[0:1], 1, s[36:37]
	s_mov_b32 m0, s10
	v_add_u32_e32 v68, 0x5000, v70
	global_load_lds_dwordx4 v[66:67], off
	v_add_u32_e32 v66, 0x8000, v0
	v_mov_b32_e32 v67, v1
	v_readfirstlane_b32 s10, v68
	v_lshl_add_u64 v[66:67], v[66:67], 1, s[36:37]
	s_mov_b32 m0, s10
	v_add_u32_e32 v68, 0x6000, v70
	global_load_lds_dwordx4 v[66:67], off
	v_add_u32_e32 v66, 0x10000, v0
	v_mov_b32_e32 v67, v1
	v_readfirstlane_b32 s10, v68
	v_lshl_add_u64 v[66:67], v[66:67], 1, s[36:37]
	s_mov_b32 m0, s10
	v_add_u32_e32 v0, 0x18000, v0
	global_load_lds_dwordx4 v[66:67], off
	v_lshl_add_u64 v[66:67], v[0:1], 1, s[36:37]
	v_add_u32_e32 v0, 0x7000, v70
	s_nop 0
	v_readfirstlane_b32 s10, v0
	s_mov_b32 m0, s10
	s_nop 0
	global_load_lds_dwordx4 v[66:67], off
	s_branch .LBB0_1613

; DEVI int k_rot(int mt, int nt, int nk) { return (((mt & 7) + (nt & 7)) & 7) * nk >> 3; }
;     ...
;   if (!PRE) GL_ISSUE(0, 0)
;   asm volatile("s_waitcnt vmcnt(0)" ::: "memory");
;   __syncthreads();
;   const int swz = fr & 7;
;   for (int kt = 0; kt < nk; ++kt) {
;     if (kt + 1 < nk) GL_ISSUE(kt + 1, (kt + 1) & 1)
;     const char* As = smem + (kt & 1) * 32768;
;     const char* Bs = As + 16384;
;     if (DEEP) {
;     bf16x8 af[2][4], bfr[2][NF];
; #pragma unroll
;     for (int ks = 0; ks < 2; ++ks) {
;       const int co = ((ks * 4 + fq) ^ swz) * 16;
; #pragma unroll
;       for (int m = 0; m < 4; ++m) af[ks][m] = *(const bf16x8*)(As + (wr * 64 + m * 16 + fr) * 128 + co);
; #pragma unroll
;       for (int n = 0; n < NF; ++n) bfr[ks][n] = *(const bf16x8*)(Bs + (wc * 16 * NF + n * 16 + fr) * 128 + co);
;     }
;     __builtin_amdgcn_s_setprio(1);
; #pragma unroll
;     for (int ks = 0; ks < 2; ++ks)
; #pragma unroll
;       for (int m = 0; m < 4; ++m)
; #pragma unroll
;         for (int n = 0; n < NF; ++n) {
;           if (SWAP) acc[m][n] = __builtin_amdgcn_mfma_f32_16x16x32_bf16(bfr[ks][n], af[ks][m], acc[m][n], 0, 0, 0);
;           else acc[m][n] = __builtin_amdgcn_mfma_f32_16x16x32_bf16(af[ks][m], bfr[ks][n], acc[m][n], 0, 0, 0);
;         }
;     __builtin_amdgcn_s_setprio(0);
;     __builtin_amdgcn_sched_group_barrier(0x100, 4 + NF, 0);
; #pragma unroll
;     for (int i = 0; i < 4 + NF; ++i) { __builtin_amdgcn_sched_group_barrier(0x008, 2, 0); __builtin_amdgcn_sched_group_barrier(0x100, 1, 0); }
;     __builtin_amdgcn_sched_group_barrier(0x008, 8 * NF - 2 * (4 + NF), 0);
; template <int EPI>
; DEVI void phase_gemm(const Params& p, const bf16* A, int lda, const bf16* Bt, int K, int NT, bf16* dst, int ldd, char* smem, bool nostore = false,
;                      const float* lng = nullptr, const float* lnb = nullptr) {
;     ...
;   for (; t < 256 * NT; t += gridDim.x) {
;     int mt, nt; tile_swz(t, 256, NT, mt, nt);
;     f32x4 acc[4][4]; zero_acc(acc);
;     gemm_mainloop_g<4, true, RowLinear, true, DEEP_FRAG != 0>(acc, A, RowLinear{lda}, 64, Bt, K, K, mt * 128, nt * 128, smem, KROT ? k_rot(mt, nt, K >> 6) : 0);
.LBB0_1732:
	s_lshl_b32 s6, s13, 4
	s_and_b32 s10, s6, 0x7000
	s_lshl_b32 s6, s42, 8
	s_and_b32 s7, s6, 0x700
	s_ashr_i32 s11, s42, 3
	s_add_i32 s7, s7, s11
	s_ashr_i32 s6, s7, 31
	s_lshr_b32 s6, s6, 26
	s_add_i32 s6, s7, s6
	s_lshl_b32 s6, s6, 4
	v_mov_b32_e32 v0, v154
	s_and_b32 s36, s6, 0xfffffc00
	s_lshl_b32 s6, s11, 7
	s_lshl_b32 s11, s11, 4
	v_ashrrev_i32_e32 v35, 3, v0
	v_lshrrev_b32_e32 v34, 4, v0
	v_xor_b32_e32 v36, v35, v0
	v_bfe_u32 v37, v0, 4, 2
	v_and_b32_e32 v38, 7, v0
	v_and_b32_e32 v39, 15, v0
	v_lshlrev_b32_e32 v102, 4, v0
	v_lshrrev_b32_e32 v40, 1, v0
	v_lshlrev_b32_e32 v0, 7, v0
	s_add_i32 s10, s10, s11
	s_and_b32 s6, s6, 0x380
	v_and_b32_e32 v98, 0x2780, v0
	v_bitop3_b32 v0, v34, v38, 3 bitop3:0x6c
	s_sub_i32 s10, s10, s36
	v_lshlrev_b32_e32 v36, 3, v36
	v_lshlrev_b32_e32 v101, 4, v0
	v_bitop3_b32 v0, v37, v38, 4 bitop3:0x36
	s_or_b32 s6, s6, s36
	s_lshl_b32 s10, s10, 8
	v_and_b32_e32 v36, 56, v36
	s_waitcnt vmcnt(0)
	v_lshlrev_b32_e32 v99, 4, v0
	v_add_u32_e32 v0, s6, v35
	s_and_b32 s10, s10, 0xffff8000
	v_and_or_b32 v39, v40, s79, v39
	v_lshl_or_b32 v103, v0, 8, v36
	v_lshl_add_u32 v0, v35, 8, s10
	v_mov_b32_e32 v34, 0
	v_lshlrev_b32_e32 v100, 7, v39
	v_or_b32_e32 v104, v0, v36
	s_mov_b32 s43, 0
	s_mov_b32 s37, 0
	v_mov_b32_e32 v35, v34
	v_mov_b32_e32 v36, v34
	v_mov_b32_e32 v37, v34
	v_mov_b32_e32 v38, v34
	v_mov_b32_e32 v39, v34
	v_mov_b32_e32 v40, v34
	v_mov_b32_e32 v41, v34
	v_mov_b32_e32 v42, v34
	v_mov_b32_e32 v43, v34
	v_mov_b32_e32 v44, v34
	v_mov_b32_e32 v45, v34
	v_mov_b32_e32 v46, v34
	v_mov_b32_e32 v47, v34
	v_mov_b32_e32 v48, v34
	v_mov_b32_e32 v49, v34
	v_mov_b32_e32 v50, v34
	v_mov_b32_e32 v51, v34
	v_mov_b32_e32 v52, v34
	v_mov_b32_e32 v53, v34
	v_mov_b32_e32 v54, v34
	v_mov_b32_e32 v55, v34
	v_mov_b32_e32 v56, v34
	v_mov_b32_e32 v57, v34
	v_mov_b32_e32 v58, v34
	v_mov_b32_e32 v59, v34
	v_mov_b32_e32 v60, v34
	v_mov_b32_e32 v61, v34
	v_mov_b32_e32 v62, v34
	v_mov_b32_e32 v63, v34
	v_mov_b32_e32 v64, v34
	v_mov_b32_e32 v65, v34
	v_mov_b32_e32 v66, v34
	v_mov_b32_e32 v67, v34
	v_mov_b32_e32 v68, v34
	v_mov_b32_e32 v69, v34
	v_mov_b32_e32 v70, v34
	v_mov_b32_e32 v71, v34
	v_mov_b32_e32 v72, v34
	v_mov_b32_e32 v73, v34
	v_mov_b32_e32 v74, v34
	v_mov_b32_e32 v75, v34
	v_mov_b32_e32 v76, v34
	v_mov_b32_e32 v77, v34
	v_mov_b32_e32 v78, v34
	v_mov_b32_e32 v79, v34
	v_mov_b32_e32 v80, v34
	v_mov_b32_e32 v81, v34
	v_mov_b32_e32 v82, v34
	v_mov_b32_e32 v83, v34
	v_mov_b32_e32 v84, v34
	v_mov_b32_e32 v85, v34
	v_mov_b32_e32 v86, v34
	v_mov_b32_e32 v87, v34
	v_mov_b32_e32 v88, v34
	v_mov_b32_e32 v89, v34
	v_mov_b32_e32 v90, v34
	v_mov_b32_e32 v91, v34
	v_mov_b32_e32 v92, v34
	v_mov_b32_e32 v93, v34
	v_mov_b32_e32 v94, v34
	v_mov_b32_e32 v95, v34
	v_mov_b32_e32 v96, v34
	v_mov_b32_e32 v97, v34
	v_lshlrev_b32_e32 v232, 1, v103
	v_add_u32_e32 v233, 0x4000, v232
	v_add_u32_e32 v234, 0x8000, v232
	v_add_u32_e32 v235, 0xc000, v232
	v_lshlrev_b32_e32 v236, 1, v104
	v_add_u32_e32 v237, 0x4000, v236
	v_add_u32_e32 v238, 0x8000, v236
	v_add_u32_e32 v239, 0xc000, v236
	v_readfirstlane_b32 s68, v102
	s_add_u32 s64, s38, 0x80
	s_addc_u32 s65, s39, 0
	s_add_u32 s66, s40, 0x80
	s_addc_u32 s67, s41, 0
	s_waitcnt vmcnt(0) lgkmcnt(0)
	s_barrier
.LBB0_1733:
	s_and_b32 s10, s43, 0x8000
	v_or_b32_e32 v0, s10, v101
	v_add_u32_e32 v105, v0, v100
	v_add_u32_e32 v0, v0, v98
	ds_read_b128 v[126:129], v0 offset:16384
	ds_read_b128 v[130:133], v0 offset:18432
	ds_read_b128 v[134:137], v0 offset:20480
	ds_read_b128 v[138:141], v0 offset:22528
	v_or_b32_e32 v0, s10, v99
	ds_read_b128 v[106:109], v105
	ds_read_b128 v[110:113], v105 offset:2048
	ds_read_b128 v[114:117], v105 offset:4096
	ds_read_b128 v[118:121], v105 offset:6144
	s_add_i32 s50, s43, 0x8000
	s_and_b32 s69, s50, 0x8000
	s_add_i32 s69, s69, s68
	v_add_u32_e32 v105, v0, v100
	v_add_u32_e32 v0, v0, v98
	s_mov_b32 m0, s69
	s_nop 0
	global_load_lds_dwordx4 v232, s[64:65]
	ds_read_b128 v[142:145], v105
	s_add_i32 m0, s69, 0x1000
	s_nop 0
	global_load_lds_dwordx4 v233, s[64:65]
	ds_read_b128 v[146:149], v105 offset:2048
	s_add_i32 m0, s69, 0x2000
	s_nop 0
	global_load_lds_dwordx4 v234, s[64:65]
	ds_read_b128 v[150:153], v105 offset:4096
	s_add_i32 m0, s69, 0x3000
	s_nop 0
	global_load_lds_dwordx4 v235, s[64:65]
	ds_read_b128 v[192:195], v105 offset:6144
	s_add_i32 m0, s69, 0x4000
	s_nop 0
	global_load_lds_dwordx4 v236, s[66:67]
	ds_read_b128 v[196:199], v0 offset:16384
	s_add_i32 m0, s69, 0x5000
	s_nop 0
	global_load_lds_dwordx4 v237, s[66:67]
	ds_read_b128 v[200:203], v0 offset:18432
	s_add_i32 m0, s69, 0x6000
	s_nop 0
	global_load_lds_dwordx4 v238, s[66:67]
	ds_read_b128 v[204:207], v0 offset:20480
	s_add_i32 m0, s69, 0x7000
	s_nop 0
	global_load_lds_dwordx4 v239, s[66:67]
	ds_read_b128 v[208:211], v0 offset:22528
	s_add_u32 s64, s64, 0x80
	s_addc_u32 s65, s65, 0
	s_add_u32 s66, s66, 0x80
	s_addc_u32 s67, s67, 0
	s_setprio 1
	s_waitcnt lgkmcnt(11)
	v_mfma_f32_16x16x32_bf16 v[94:97], v[126:129], v[106:109], v[94:97]
	v_mfma_f32_16x16x32_bf16 v[90:93], v[130:133], v[106:109], v[90:93]
	v_mfma_f32_16x16x32_bf16 v[86:89], v[134:137], v[106:109], v[86:89]
	v_mfma_f32_16x16x32_bf16 v[82:85], v[138:141], v[106:109], v[82:85]
	s_waitcnt lgkmcnt(10)
	v_mfma_f32_16x16x32_bf16 v[78:81], v[126:129], v[110:113], v[78:81]
	v_mfma_f32_16x16x32_bf16 v[74:77], v[130:133], v[110:113], v[74:77]
	v_mfma_f32_16x16x32_bf16 v[70:73], v[134:137], v[110:113], v[70:73]
	v_mfma_f32_16x16x32_bf16 v[66:69], v[138:141], v[110:113], v[66:69]
	s_waitcnt lgkmcnt(9)
	v_mfma_f32_16x16x32_bf16 v[62:65], v[126:129], v[114:117], v[62:65]
	v_mfma_f32_16x16x32_bf16 v[58:61], v[130:133], v[114:117], v[58:61]
	v_mfma_f32_16x16x32_bf16 v[54:57], v[134:137], v[114:117], v[54:57]
	v_mfma_f32_16x16x32_bf16 v[50:53], v[138:141], v[114:117], v[50:53]
	s_waitcnt lgkmcnt(8)
; DEVI int k_rot(int mt, int nt, int nk) { return (((mt & 7) + (nt & 7)) & 7) * nk >> 3; }
;     ...
;     if (DEEP) {
;     bf16x8 af[2][4], bfr[2][NF];
; #pragma unroll
;     for (int ks = 0; ks < 2; ++ks) {
;       const int co = ((ks * 4 + fq) ^ swz) * 16;
; #pragma unroll
;       for (int m = 0; m < 4; ++m) af[ks][m] = *(const bf16x8*)(As + (wr * 64 + m * 16 + fr) * 128 + co);
; #pragma unroll
;       for (int n = 0; n < NF; ++n) bfr[ks][n] = *(const bf16x8*)(Bs + (wc * 16 * NF + n * 16 + fr) * 128 + co);
;     }
;     __builtin_amdgcn_s_setprio(1);
; #pragma unroll
;     for (int ks = 0; ks < 2; ++ks)
; #pragma unroll
;       for (int m = 0; m < 4; ++m)
; #pragma unroll
;         for (int n = 0; n < NF; ++n) {
;           if (SWAP) acc[m][n] = __builtin_amdgcn_mfma_f32_16x16x32_bf16(bfr[ks][n], af[ks][m], acc[m][n], 0, 0, 0);
;           else acc[m][n] = __builtin_amdgcn_mfma_f32_16x16x32_bf16(af[ks][m], bfr[ks][n], acc[m][n], 0, 0, 0);
;         }
;     __builtin_amdgcn_s_setprio(0);
;     __builtin_amdgcn_sched_group_barrier(0x100, 4 + NF, 0);
; #pragma unroll
;     for (int i = 0; i < 4 + NF; ++i) { __builtin_amdgcn_sched_group_barrier(0x008, 2, 0); __builtin_amdgcn_sched_group_barrier(0x100, 1, 0); }
;     __builtin_amdgcn_sched_group_barrier(0x008, 8 * NF - 2 * (4 + NF), 0);
; template <int EPI>
; DEVI void phase_gemm(const Params& p, const bf16* A, int lda, const bf16* Bt, int K, int NT, bf16* dst, int ldd, char* smem, bool nostore = false,
;                      const float* lng = nullptr, const float* lnb = nullptr) {
;     ...
;   for (; t < 256 * NT; t += gridDim.x) {
;     int mt, nt; tile_swz(t, 256, NT, mt, nt);
;     f32x4 acc[4][4]; zero_acc(acc);
;     gemm_mainloop_g<4, true, RowLinear, true, DEEP_FRAG != 0>(acc, A, RowLinear{lda}, 64, Bt, K, K, mt * 128, nt * 128, smem, KROT ? k_rot(mt, nt, K >> 6) : 0);
;     if (t + (int)gridDim.x < 256 * NT) {
	v_mfma_f32_16x16x32_bf16 v[46:49], v[126:129], v[118:121], v[46:49]
	v_mfma_f32_16x16x32_bf16 v[42:45], v[130:133], v[118:121], v[42:45]
	v_mfma_f32_16x16x32_bf16 v[38:41], v[134:137], v[118:121], v[38:41]
	v_mfma_f32_16x16x32_bf16 v[34:37], v[138:141], v[118:121], v[34:37]
	s_waitcnt lgkmcnt(3)
	v_mfma_f32_16x16x32_bf16 v[94:97], v[196:199], v[142:145], v[94:97]
	s_waitcnt lgkmcnt(2)
	v_mfma_f32_16x16x32_bf16 v[90:93], v[200:203], v[142:145], v[90:93]
	s_waitcnt lgkmcnt(1)
	v_mfma_f32_16x16x32_bf16 v[86:89], v[204:207], v[142:145], v[86:89]
	s_waitcnt lgkmcnt(0)
	v_mfma_f32_16x16x32_bf16 v[82:85], v[208:211], v[142:145], v[82:85]
	v_mfma_f32_16x16x32_bf16 v[78:81], v[196:199], v[146:149], v[78:81]
	v_mfma_f32_16x16x32_bf16 v[74:77], v[200:203], v[146:149], v[74:77]
	v_mfma_f32_16x16x32_bf16 v[70:73], v[204:207], v[146:149], v[70:73]
	v_mfma_f32_16x16x32_bf16 v[66:69], v[208:211], v[146:149], v[66:69]
	v_mfma_f32_16x16x32_bf16 v[62:65], v[196:199], v[150:153], v[62:65]
	v_mfma_f32_16x16x32_bf16 v[58:61], v[200:203], v[150:153], v[58:61]
	v_mfma_f32_16x16x32_bf16 v[54:57], v[204:207], v[150:153], v[54:57]
	v_mfma_f32_16x16x32_bf16 v[50:53], v[208:211], v[150:153], v[50:53]
	v_mfma_f32_16x16x32_bf16 v[46:49], v[196:199], v[192:195], v[46:49]
	v_mfma_f32_16x16x32_bf16 v[42:45], v[200:203], v[192:195], v[42:45]
	v_mfma_f32_16x16x32_bf16 v[38:41], v[204:207], v[192:195], v[38:41]
	v_mfma_f32_16x16x32_bf16 v[34:37], v[208:211], v[192:195], v[34:37]
	s_setprio 0
	s_waitcnt vmcnt(0)
	s_add_i32 s37, s37, 64
	s_cmpk_eq_i32 s37, 0xc0
	s_mov_b32 s43, s50
	s_waitcnt vmcnt(0)
	s_barrier
	s_cbranch_scc0 .LBB0_1733
	v_add_u32_e32 v0, v101, v100
	ds_read_b128 v[102:105], v0 offset:32768
	ds_read_b128 v[106:109], v0 offset:34816
	ds_read_b128 v[110:113], v0 offset:36864
	ds_read_b128 v[114:117], v0 offset:38912
	v_add_u32_e32 v0, v101, v98
	ds_read_b128 v[118:121], v0 offset:49152
	ds_read_b128 v[126:129], v0 offset:51200
	ds_read_b128 v[130:133], v0 offset:53248
	ds_read_b128 v[134:137], v0 offset:55296
	v_add_u32_e32 v0, v99, v100
	ds_read_b128 v[138:141], v0 offset:32768
	ds_read_b128 v[142:145], v0 offset:34816
	ds_read_b128 v[146:149], v0 offset:36864
	ds_read_b128 v[150:153], v0 offset:38912
	v_add_u32_e32 v0, v99, v98
	ds_read_b128 v[98:101], v0 offset:49152
	ds_read_b128 v[192:195], v0 offset:51200
	ds_read_b128 v[196:199], v0 offset:53248
	ds_read_b128 v[200:203], v0 offset:55296
	s_setprio 1
	s_waitcnt lgkmcnt(11)
	v_mfma_f32_16x16x32_bf16 v[94:97], v[118:121], v[102:105], v[94:97]
	s_waitcnt lgkmcnt(10)
	v_mfma_f32_16x16x32_bf16 v[90:93], v[126:129], v[102:105], v[90:93]
	s_waitcnt lgkmcnt(9)
	v_mfma_f32_16x16x32_bf16 v[86:89], v[130:133], v[102:105], v[86:89]
	s_waitcnt lgkmcnt(8)
	v_mfma_f32_16x16x32_bf16 v[82:85], v[134:137], v[102:105], v[82:85]
	v_mfma_f32_16x16x32_bf16 v[78:81], v[118:121], v[106:109], v[78:81]
	v_mfma_f32_16x16x32_bf16 v[74:77], v[126:129], v[106:109], v[74:77]
	v_mfma_f32_16x16x32_bf16 v[70:73], v[130:133], v[106:109], v[70:73]
	v_mfma_f32_16x16x32_bf16 v[66:69], v[134:137], v[106:109], v[66:69]
	v_mfma_f32_16x16x32_bf16 v[62:65], v[118:121], v[110:113], v[62:65]
	v_mfma_f32_16x16x32_bf16 v[58:61], v[126:129], v[110:113], v[58:61]
	v_mfma_f32_16x16x32_bf16 v[54:57], v[130:133], v[110:113], v[54:57]
	v_mfma_f32_16x16x32_bf16 v[50:53], v[134:137], v[110:113], v[50:53]
	v_mfma_f32_16x16x32_bf16 v[46:49], v[118:121], v[114:117], v[46:49]
	v_mfma_f32_16x16x32_bf16 v[42:45], v[126:129], v[114:117], v[42:45]
	v_mfma_f32_16x16x32_bf16 v[38:41], v[130:133], v[114:117], v[38:41]
	v_mfma_f32_16x16x32_bf16 v[34:37], v[134:137], v[114:117], v[34:37]
	s_waitcnt lgkmcnt(3)
	v_mfma_f32_16x16x32_bf16 v[94:97], v[98:101], v[138:141], v[94:97]
	s_waitcnt lgkmcnt(2)
	v_mfma_f32_16x16x32_bf16 v[90:93], v[192:195], v[138:141], v[90:93]
	s_waitcnt lgkmcnt(1)
	v_mfma_f32_16x16x32_bf16 v[86:89], v[196:199], v[138:141], v[86:89]
	s_waitcnt lgkmcnt(0)
	v_mfma_f32_16x16x32_bf16 v[82:85], v[200:203], v[138:141], v[82:85]
	v_mfma_f32_16x16x32_bf16 v[78:81], v[98:101], v[142:145], v[78:81]
	v_mfma_f32_16x16x32_bf16 v[74:77], v[192:195], v[142:145], v[74:77]
	v_mfma_f32_16x16x32_bf16 v[70:73], v[196:199], v[142:145], v[70:73]
	v_mfma_f32_16x16x32_bf16 v[66:69], v[200:203], v[142:145], v[66:69]
	v_mfma_f32_16x16x32_bf16 v[62:65], v[98:101], v[146:149], v[62:65]
	v_mfma_f32_16x16x32_bf16 v[58:61], v[192:195], v[146:149], v[58:61]
	v_mfma_f32_16x16x32_bf16 v[54:57], v[196:199], v[146:149], v[54:57]
	v_mfma_f32_16x16x32_bf16 v[50:53], v[200:203], v[146:149], v[50:53]
	v_mfma_f32_16x16x32_bf16 v[46:49], v[98:101], v[150:153], v[46:49]
	v_mfma_f32_16x16x32_bf16 v[42:45], v[192:195], v[150:153], v[42:45]
	v_mfma_f32_16x16x32_bf16 v[38:41], v[196:199], v[150:153], v[38:41]
	v_mfma_f32_16x16x32_bf16 v[34:37], v[200:203], v[150:153], v[34:37]
	s_setprio 0
	s_waitcnt vmcnt(0)
	s_add_i32 s42, s42, s20
	s_cmpk_gt_i32 s42, 0x7ff
	s_cselect_b64 s[50:51], -1, 0
	s_cmpk_lt_i32 s42, 0x800
	s_barrier
; DEVI int opaque_tid() { int t = __builtin_amdgcn_workitem_id_x(); asm volatile("" : "+v"(t)); return t; }
; DEVI int k_rot(int mt, int nt, int nk) { return (((mt & 7) + (nt & 7)) & 7) * nk >> 3; }
;   const int tid = opaque_tid();
;   const int lrow = tid >> 3, lpos = tid & 7;
;   const int gch = (lpos ^ (lrow & 7)) * 8 + koff * 64;
;   char* ab = smem + tid * 16;
; #pragma unroll
;   for (int i = 0; i < 4; ++i)
;     __builtin_amdgcn_global_load_lds((const unsigned*)(A + (unsigned)(arow(m0 + lrow + 32 * i) + gch)), (unsigned*)(ab + i * 4096), 16, 0, 0);
; #pragma unroll
;   for (int i = 0; i < NF; ++i)
;     __builtin_amdgcn_global_load_lds((const unsigned*)(Bt + (unsigned)((n0 + lrow + 32 * i) * ldb + gch)), (unsigned*)(ab + 16384 + i * 4096), 16, 0, 0);
; }
; template <int EPI>
; DEVI void phase_gemm(const Params& p, const bf16* A, int lda, const bf16* Bt, int K, int NT, bf16* dst, int ldd, char* smem, bool nostore = false,
;                      const float* lng = nullptr, const float* lnb = nullptr) {
;     ...
;     if (t + (int)gridDim.x < 256 * NT) {
;       int mt2, nt2; tile_swz(t + gridDim.x, 256, NT, mt2, nt2);
;       gemm_prefetch0<4>(A, RowLinear{lda}, Bt, K, mt2 * 128, nt2 * 128, smem, KROT ? k_rot(mt2, nt2, K >> 6) : 0);
;     }
	s_cbranch_scc0 .LBB0_1736
	s_lshl_b32 s10, s42, 8
	s_and_b32 s10, s10, 0x700
	s_ashr_i32 s11, s42, 3
	s_add_i32 s10, s10, s11
	s_ashr_i32 s37, s10, 31
	s_lshr_b32 s37, s37, 26
	s_add_i32 s37, s10, s37
	v_mov_b32_e32 v0, v154
	s_lshl_b32 s37, s37, 4
	s_lshl_b32 s11, s11, 7
	s_and_b32 s37, s37, 0xfffffc00
	v_ashrrev_i32_e32 v100, 3, v0
	s_and_b32 s11, s11, 0x380
	v_xor_b32_e32 v98, v100, v0
	s_or_b32 s11, s37, s11
	v_lshlrev_b32_e32 v98, 3, v98
	v_and_b32_e32 v101, 56, v98
	v_lshlrev_b32_e32 v102, 4, v0
	v_add_u32_e32 v0, s11, v100
	v_lshl_or_b32 v0, v0, 8, v101
	v_readfirstlane_b32 s11, v102
	v_lshl_add_u64 v[98:99], v[0:1], 1, s[38:39]
	s_mov_b32 m0, s11
	v_add_u32_e32 v103, 0x1000, v102
	global_load_lds_dwordx4 v[98:99], off
	v_add_u32_e32 v98, 0x2000, v0
	v_mov_b32_e32 v99, v1
	v_readfirstlane_b32 s11, v103
	v_lshl_add_u64 v[98:99], v[98:99], 1, s[38:39]
	s_mov_b32 m0, s11
	v_add_u32_e32 v103, 0x2000, v102
	s_lshl_b32 s10, s10, 4
	global_load_lds_dwordx4 v[98:99], off
	v_add_u32_e32 v98, 0x4000, v0
	v_mov_b32_e32 v99, v1
	v_readfirstlane_b32 s11, v103
	s_sub_i32 s10, s10, s37
	v_lshl_add_u64 v[98:99], v[98:99], 1, s[38:39]
	s_mov_b32 m0, s11
	v_add_u32_e32 v0, 0x6000, v0
	s_and_b32 s10, s10, 0xffff80
	global_load_lds_dwordx4 v[98:99], off
	v_lshl_add_u64 v[98:99], v[0:1], 1, s[38:39]
	v_add_u32_e32 v0, 0x3000, v102
	s_nop 0
	v_readfirstlane_b32 s11, v0
	v_add_u32_e32 v0, s10, v100
	v_add_u32_e32 v100, 0x4000, v102
	s_mov_b32 m0, s11
	v_lshl_or_b32 v0, v0, 8, v101
	v_readfirstlane_b32 s10, v100
	global_load_lds_dwordx4 v[98:99], off
	v_lshl_add_u64 v[98:99], v[0:1], 1, s[40:41]
	s_mov_b32 m0, s10
	v_add_u32_e32 v100, 0x5000, v102
	global_load_lds_dwordx4 v[98:99], off
	v_add_u32_e32 v98, 0x2000, v0
	v_mov_b32_e32 v99, v1
	v_readfirstlane_b32 s10, v100
	v_lshl_add_u64 v[98:99], v[98:99], 1, s[40:41]
	s_mov_b32 m0, s10
	v_add_u32_e32 v100, 0x6000, v102
	global_load_lds_dwordx4 v[98:99], off
	v_add_u32_e32 v98, 0x4000, v0
	v_mov_b32_e32 v99, v1
	v_readfirstlane_b32 s10, v100
	v_lshl_add_u64 v[98:99], v[98:99], 1, s[40:41]
	s_mov_b32 m0, s10
	v_add_u32_e32 v0, 0x6000, v0
	global_load_lds_dwordx4 v[98:99], off
	v_lshl_add_u64 v[98:99], v[0:1], 1, s[40:41]
	v_add_u32_e32 v0, 0x7000, v102
	s_nop 0
	v_readfirstlane_b32 s10, v0
	s_mov_b32 m0, s10
	s_nop 0
	global_load_lds_dwordx4 v[98:99], off

; DEVI int k_rot(int mt, int nt, int nk) { return (((mt & 7) + (nt & 7)) & 7) * nk >> 3; }
;     ...
;   if (!PRE) GL_ISSUE(0, 0)
;   asm volatile("s_waitcnt vmcnt(0)" ::: "memory");
;   __syncthreads();
;   const int swz = fr & 7;
;   for (int kt = 0; kt < nk; ++kt) {
;     if (kt + 1 < nk) GL_ISSUE(kt + 1, (kt + 1) & 1)
;     const char* As = smem + (kt & 1) * 32768;
;     const char* Bs = As + 16384;
;     if (DEEP) {
;     bf16x8 af[2][4], bfr[2][NF];
; #pragma unroll
;     for (int ks = 0; ks < 2; ++ks) {
;       const int co = ((ks * 4 + fq) ^ swz) * 16;
; #pragma unroll
;       for (int m = 0; m < 4; ++m) af[ks][m] = *(const bf16x8*)(As + (wr * 64 + m * 16 + fr) * 128 + co);
; #pragma unroll
;       for (int n = 0; n < NF; ++n) bfr[ks][n] = *(const bf16x8*)(Bs + (wc * 16 * NF + n * 16 + fr) * 128 + co);
;     }
;     __builtin_amdgcn_s_setprio(1);
; #pragma unroll
;     for (int ks = 0; ks < 2; ++ks)
; #pragma unroll
;       for (int m = 0; m < 4; ++m)
; #pragma unroll
;         for (int n = 0; n < NF; ++n) {
;           if (SWAP) acc[m][n] = __builtin_amdgcn_mfma_f32_16x16x32_bf16(bfr[ks][n], af[ks][m], acc[m][n], 0, 0, 0);
;           else acc[m][n] = __builtin_amdgcn_mfma_f32_16x16x32_bf16(af[ks][m], bfr[ks][n], acc[m][n], 0, 0, 0);
;         }
;     __builtin_amdgcn_s_setprio(0);
;     __builtin_amdgcn_sched_group_barrier(0x100, 4 + NF, 0);
; #pragma unroll
;     for (int i = 0; i < 4 + NF; ++i) { __builtin_amdgcn_sched_group_barrier(0x008, 2, 0); __builtin_amdgcn_sched_group_barrier(0x100, 1, 0); }
;     __builtin_amdgcn_sched_group_barrier(0x008, 8 * NF - 2 * (4 + NF), 0);
; template <int EPI>
; DEVI void phase_gemm(const Params& p, const bf16* A, int lda, const bf16* Bt, int K, int NT, bf16* dst, int ldd, char* smem, bool nostore = false,
;                      const float* lng = nullptr, const float* lnb = nullptr) {
;     ...
;   for (; t < 256 * NT; t += gridDim.x) {
;     int mt, nt; tile_swz(t, 256, NT, mt, nt);
;     f32x4 acc[4][4]; zero_acc(acc);
;     gemm_mainloop_g<4, true, RowLinear, true, DEEP_FRAG != 0>(acc, A, RowLinear{lda}, 64, Bt, K, K, mt * 128, nt * 128, smem, KROT ? k_rot(mt, nt, K >> 6) : 0);
.LBB0_1862:
	s_lshl_b32 s11, s7, 10
	s_and_b32 s40, s11, 0x1c00
	s_ashr_i32 s11, s7, 3
	s_add_i32 s40, s40, s11
	s_ashr_i32 s13, s40, 31
	s_lshr_b32 s13, s13, 24
	s_lshl_b32 s10, s6, 4
	s_add_i32 s13, s40, s13
	s_and_b32 s10, s10, 0x1c000
	s_ashr_i32 s13, s13, 8
	s_lshl_b32 s39, s11, 7
	v_mov_b32_e32 v0, v154
	s_lshl_b32 s11, s11, 4
	s_lshl_b32 s41, s13, 12
	s_add_i32 s10, s10, s11
	v_ashrrev_i32_e32 v3, 3, v0
	v_lshrrev_b32_e32 v2, 4, v0
	v_xor_b32_e32 v4, v3, v0
	v_bfe_u32 v5, v0, 4, 2
	v_and_b32_e32 v6, 7, v0
	v_and_b32_e32 v7, 15, v0
	v_lshlrev_b32_e32 v70, 4, v0
	v_lshrrev_b32_e32 v8, 1, v0
	v_lshlrev_b32_e32 v0, 7, v0
	s_sub_i32 s10, s10, s41
	v_and_b32_e32 v66, 0x2780, v0
	v_bitop3_b32 v0, v2, v6, 3 bitop3:0x6c
	s_lshl_b32 s10, s10, 10
	s_lshl_b32 s38, s13, 10
	s_and_b32 s39, s39, 0x380
	v_lshlrev_b32_e32 v4, 3, v4
	v_lshlrev_b32_e32 v69, 4, v0
	v_bitop3_b32 v0, v5, v6, 4 bitop3:0x36
	s_and_b32 s10, s10, 0xfffe0000
	v_and_b32_e32 v4, 56, v4
	s_waitcnt vmcnt(0)
	v_lshlrev_b32_e32 v67, 4, v0
	v_lshl_add_u32 v0, v3, 10, s10
	s_or_b32 s13, s39, s38
	v_and_or_b32 v7, v8, s79, v7
	v_or_b32_e32 v71, v0, v4
	v_add_u32_e32 v0, s13, v3
	v_mov_b32_e32 v2, 0
	v_lshlrev_b32_e32 v68, 7, v7
	v_lshl_or_b32 v72, v0, 10, v4
	s_mov_b32 s39, 0
	s_mov_b32 s38, 0
	v_mov_b32_e32 v3, v2
	v_mov_b32_e32 v4, v2
	v_mov_b32_e32 v5, v2
	v_mov_b32_e32 v6, v2
	v_mov_b32_e32 v7, v2
	v_mov_b32_e32 v8, v2
	v_mov_b32_e32 v9, v2
	v_mov_b32_e32 v10, v2
	v_mov_b32_e32 v11, v2
	v_mov_b32_e32 v12, v2
	v_mov_b32_e32 v13, v2
	v_mov_b32_e32 v14, v2
	v_mov_b32_e32 v15, v2
	v_mov_b32_e32 v16, v2
	v_mov_b32_e32 v17, v2
	v_mov_b32_e32 v18, v2
	v_mov_b32_e32 v19, v2
	v_mov_b32_e32 v20, v2
	v_mov_b32_e32 v21, v2
	v_mov_b32_e32 v22, v2
	v_mov_b32_e32 v23, v2
	v_mov_b32_e32 v24, v2
	v_mov_b32_e32 v25, v2
	v_mov_b32_e32 v26, v2
	v_mov_b32_e32 v27, v2
	v_mov_b32_e32 v28, v2
	v_mov_b32_e32 v29, v2
	v_mov_b32_e32 v30, v2
	v_mov_b32_e32 v31, v2
	v_mov_b32_e32 v32, v2
	v_mov_b32_e32 v33, v2
	v_mov_b32_e32 v34, v2
	v_mov_b32_e32 v35, v2
	v_mov_b32_e32 v36, v2
	v_mov_b32_e32 v37, v2
	v_mov_b32_e32 v38, v2
	v_mov_b32_e32 v39, v2
	v_mov_b32_e32 v40, v2
	v_mov_b32_e32 v41, v2
	v_mov_b32_e32 v42, v2
	v_mov_b32_e32 v43, v2
	v_mov_b32_e32 v44, v2
	v_mov_b32_e32 v45, v2
	v_mov_b32_e32 v46, v2
	v_mov_b32_e32 v47, v2
	v_mov_b32_e32 v48, v2
	v_mov_b32_e32 v49, v2
	v_mov_b32_e32 v50, v2
	v_mov_b32_e32 v51, v2
	v_mov_b32_e32 v52, v2
	v_mov_b32_e32 v53, v2
	v_mov_b32_e32 v54, v2
	v_mov_b32_e32 v55, v2
	v_mov_b32_e32 v56, v2
	v_mov_b32_e32 v57, v2
	v_mov_b32_e32 v58, v2
	v_mov_b32_e32 v59, v2
	v_mov_b32_e32 v60, v2
	v_mov_b32_e32 v61, v2
	v_mov_b32_e32 v62, v2
	v_mov_b32_e32 v63, v2
	v_mov_b32_e32 v64, v2
	v_mov_b32_e32 v65, v2
	v_lshlrev_b32_e32 v232, 1, v72
	v_add_u32_e32 v233, 0x10000, v232
	v_add_u32_e32 v234, 0x20000, v232
	v_add_u32_e32 v235, 0x30000, v232
	v_lshlrev_b32_e32 v236, 1, v71
	v_add_u32_e32 v237, 0x10000, v236
	v_add_u32_e32 v238, 0x20000, v236
	v_add_u32_e32 v239, 0x30000, v236
	v_readfirstlane_b32 s68, v70
	s_add_u32 s64, s8, 0x80
	s_addc_u32 s65, s9, 0
	s_add_u32 s66, s36, 0x80
	s_addc_u32 s67, s37, 0
	s_waitcnt vmcnt(0) lgkmcnt(0)
	s_barrier
.LBB0_1863:
	s_and_b32 s10, s39, 0x8000
	v_or_b32_e32 v0, s10, v69
	v_add_u32_e32 v73, v0, v68
	v_add_u32_e32 v0, v0, v66
	ds_read_b128 v[90:93], v0 offset:16384
	ds_read_b128 v[94:97], v0 offset:18432
	ds_read_b128 v[98:101], v0 offset:20480
	ds_read_b128 v[102:105], v0 offset:22528
	v_or_b32_e32 v0, s10, v67
	ds_read_b128 v[74:77], v73
	ds_read_b128 v[78:81], v73 offset:2048
	ds_read_b128 v[82:85], v73 offset:4096
	ds_read_b128 v[86:89], v73 offset:6144
	s_add_i32 s42, s39, 0x8000
	s_and_b32 s69, s42, 0x8000
	s_add_i32 s69, s69, s68
	v_add_u32_e32 v73, v0, v68
	v_add_u32_e32 v0, v0, v66
	s_mov_b32 m0, s69
	s_nop 0
	global_load_lds_dwordx4 v232, s[64:65]
	ds_read_b128 v[106:109], v73
	s_add_i32 m0, s69, 0x1000
	s_nop 0
	global_load_lds_dwordx4 v233, s[64:65]
	ds_read_b128 v[110:113], v73 offset:2048
	s_add_i32 m0, s69, 0x2000
	s_nop 0
	global_load_lds_dwordx4 v234, s[64:65]
	ds_read_b128 v[114:117], v73 offset:4096
	s_add_i32 m0, s69, 0x3000
	s_nop 0
	global_load_lds_dwordx4 v235, s[64:65]
	ds_read_b128 v[118:121], v73 offset:6144
	s_add_i32 m0, s69, 0x4000
	s_nop 0
	global_load_lds_dwordx4 v236, s[66:67]
	ds_read_b128 v[126:129], v0 offset:16384
	s_add_i32 m0, s69, 0x5000
	s_nop 0
	global_load_lds_dwordx4 v237, s[66:67]
	ds_read_b128 v[130:133], v0 offset:18432
	s_add_i32 m0, s69, 0x6000
	s_nop 0
	global_load_lds_dwordx4 v238, s[66:67]
	ds_read_b128 v[134:137], v0 offset:20480
	s_add_i32 m0, s69, 0x7000
	s_nop 0
	global_load_lds_dwordx4 v239, s[66:67]
	ds_read_b128 v[138:141], v0 offset:22528
	s_add_u32 s64, s64, 0x80
	s_addc_u32 s65, s65, 0
	s_add_u32 s66, s66, 0x80
	s_addc_u32 s67, s67, 0
	s_setprio 1
	s_waitcnt lgkmcnt(11)
	v_mfma_f32_16x16x32_bf16 v[62:65], v[90:93], v[74:77], v[62:65]
	v_mfma_f32_16x16x32_bf16 v[58:61], v[94:97], v[74:77], v[58:61]
	v_mfma_f32_16x16x32_bf16 v[54:57], v[98:101], v[74:77], v[54:57]
	v_mfma_f32_16x16x32_bf16 v[50:53], v[102:105], v[74:77], v[50:53]
	s_waitcnt lgkmcnt(10)
	v_mfma_f32_16x16x32_bf16 v[46:49], v[90:93], v[78:81], v[46:49]
	v_mfma_f32_16x16x32_bf16 v[42:45], v[94:97], v[78:81], v[42:45]
	v_mfma_f32_16x16x32_bf16 v[38:41], v[98:101], v[78:81], v[38:41]
	v_mfma_f32_16x16x32_bf16 v[34:37], v[102:105], v[78:81], v[34:37]
	s_waitcnt lgkmcnt(9)
	v_mfma_f32_16x16x32_bf16 v[30:33], v[90:93], v[82:85], v[30:33]
	v_mfma_f32_16x16x32_bf16 v[26:29], v[94:97], v[82:85], v[26:29]
	v_mfma_f32_16x16x32_bf16 v[22:25], v[98:101], v[82:85], v[22:25]
	v_mfma_f32_16x16x32_bf16 v[18:21], v[102:105], v[82:85], v[18:21]
	s_waitcnt lgkmcnt(8)
; DEVI int k_rot(int mt, int nt, int nk) { return (((mt & 7) + (nt & 7)) & 7) * nk >> 3; }
;     ...
;     if (DEEP) {
;     bf16x8 af[2][4], bfr[2][NF];
; #pragma unroll
;     for (int ks = 0; ks < 2; ++ks) {
;       const int co = ((ks * 4 + fq) ^ swz) * 16;
; #pragma unroll
;       for (int m = 0; m < 4; ++m) af[ks][m] = *(const bf16x8*)(As + (wr * 64 + m * 16 + fr) * 128 + co);
; #pragma unroll
;       for (int n = 0; n < NF; ++n) bfr[ks][n] = *(const bf16x8*)(Bs + (wc * 16 * NF + n * 16 + fr) * 128 + co);
;     }
;     __builtin_amdgcn_s_setprio(1);
; #pragma unroll
;     for (int ks = 0; ks < 2; ++ks)
; #pragma unroll
;       for (int m = 0; m < 4; ++m)
; #pragma unroll
;         for (int n = 0; n < NF; ++n) {
;           if (SWAP) acc[m][n] = __builtin_amdgcn_mfma_f32_16x16x32_bf16(bfr[ks][n], af[ks][m], acc[m][n], 0, 0, 0);
;           else acc[m][n] = __builtin_amdgcn_mfma_f32_16x16x32_bf16(af[ks][m], bfr[ks][n], acc[m][n], 0, 0, 0);
;         }
;     __builtin_amdgcn_s_setprio(0);
;     __builtin_amdgcn_sched_group_barrier(0x100, 4 + NF, 0);
; #pragma unroll
;     for (int i = 0; i < 4 + NF; ++i) { __builtin_amdgcn_sched_group_barrier(0x008, 2, 0); __builtin_amdgcn_sched_group_barrier(0x100, 1, 0); }
;     __builtin_amdgcn_sched_group_barrier(0x008, 8 * NF - 2 * (4 + NF), 0);
; template <int EPI>
; DEVI void phase_gemm(const Params& p, const bf16* A, int lda, const bf16* Bt, int K, int NT, bf16* dst, int ldd, char* smem, bool nostore = false,
;                      const float* lng = nullptr, const float* lnb = nullptr) {
;     ...
;   for (; t < 256 * NT; t += gridDim.x) {
;     int mt, nt; tile_swz(t, 256, NT, mt, nt);
;     f32x4 acc[4][4]; zero_acc(acc);
;     gemm_mainloop_g<4, true, RowLinear, true, DEEP_FRAG != 0>(acc, A, RowLinear{lda}, 64, Bt, K, K, mt * 128, nt * 128, smem, KROT ? k_rot(mt, nt, K >> 6) : 0);
;     if (t + (int)gridDim.x < 256 * NT) {
	v_mfma_f32_16x16x32_bf16 v[14:17], v[90:93], v[86:89], v[14:17]
	v_mfma_f32_16x16x32_bf16 v[10:13], v[94:97], v[86:89], v[10:13]
	v_mfma_f32_16x16x32_bf16 v[6:9], v[98:101], v[86:89], v[6:9]
	v_mfma_f32_16x16x32_bf16 v[2:5], v[102:105], v[86:89], v[2:5]
	s_waitcnt lgkmcnt(3)
	v_mfma_f32_16x16x32_bf16 v[62:65], v[126:129], v[106:109], v[62:65]
	s_waitcnt lgkmcnt(2)
	v_mfma_f32_16x16x32_bf16 v[58:61], v[130:133], v[106:109], v[58:61]
	s_waitcnt lgkmcnt(1)
	v_mfma_f32_16x16x32_bf16 v[54:57], v[134:137], v[106:109], v[54:57]
	s_waitcnt lgkmcnt(0)
	v_mfma_f32_16x16x32_bf16 v[50:53], v[138:141], v[106:109], v[50:53]
	v_mfma_f32_16x16x32_bf16 v[46:49], v[126:129], v[110:113], v[46:49]
	v_mfma_f32_16x16x32_bf16 v[42:45], v[130:133], v[110:113], v[42:45]
	v_mfma_f32_16x16x32_bf16 v[38:41], v[134:137], v[110:113], v[38:41]
	v_mfma_f32_16x16x32_bf16 v[34:37], v[138:141], v[110:113], v[34:37]
	v_mfma_f32_16x16x32_bf16 v[30:33], v[126:129], v[114:117], v[30:33]
	v_mfma_f32_16x16x32_bf16 v[26:29], v[130:133], v[114:117], v[26:29]
	v_mfma_f32_16x16x32_bf16 v[22:25], v[134:137], v[114:117], v[22:25]
	v_mfma_f32_16x16x32_bf16 v[18:21], v[138:141], v[114:117], v[18:21]
	v_mfma_f32_16x16x32_bf16 v[14:17], v[126:129], v[118:121], v[14:17]
	v_mfma_f32_16x16x32_bf16 v[10:13], v[130:133], v[118:121], v[10:13]
	v_mfma_f32_16x16x32_bf16 v[6:9], v[134:137], v[118:121], v[6:9]
	v_mfma_f32_16x16x32_bf16 v[2:5], v[138:141], v[118:121], v[2:5]
	s_setprio 0
	s_waitcnt vmcnt(0)
	s_add_i32 s38, s38, 64
	s_cmpk_eq_i32 s38, 0x3c0
	s_mov_b32 s39, s42
	s_waitcnt vmcnt(0)
	s_barrier
	s_cbranch_scc0 .LBB0_1863
	v_add_u32_e32 v0, v69, v68
	ds_read_b128 v[70:73], v0 offset:32768
	ds_read_b128 v[74:77], v0 offset:34816
	ds_read_b128 v[78:81], v0 offset:36864
	ds_read_b128 v[82:85], v0 offset:38912
	v_add_u32_e32 v0, v69, v66
	ds_read_b128 v[86:89], v0 offset:49152
	ds_read_b128 v[90:93], v0 offset:51200
	ds_read_b128 v[94:97], v0 offset:53248
	ds_read_b128 v[98:101], v0 offset:55296
	v_add_u32_e32 v0, v67, v68
	ds_read_b128 v[102:105], v0 offset:32768
	ds_read_b128 v[106:109], v0 offset:34816
	ds_read_b128 v[110:113], v0 offset:36864
	ds_read_b128 v[114:117], v0 offset:38912
	v_add_u32_e32 v0, v67, v66
	ds_read_b128 v[66:69], v0 offset:49152
	ds_read_b128 v[118:121], v0 offset:51200
	ds_read_b128 v[126:129], v0 offset:53248
	ds_read_b128 v[130:133], v0 offset:55296
	s_setprio 1
	s_waitcnt lgkmcnt(11)
	v_mfma_f32_16x16x32_bf16 v[62:65], v[86:89], v[70:73], v[62:65]
	s_waitcnt lgkmcnt(10)
	v_mfma_f32_16x16x32_bf16 v[58:61], v[90:93], v[70:73], v[58:61]
	s_waitcnt lgkmcnt(9)
	v_mfma_f32_16x16x32_bf16 v[54:57], v[94:97], v[70:73], v[54:57]
	s_waitcnt lgkmcnt(8)
	v_mfma_f32_16x16x32_bf16 v[50:53], v[98:101], v[70:73], v[50:53]
	v_mfma_f32_16x16x32_bf16 v[46:49], v[86:89], v[74:77], v[46:49]
	v_mfma_f32_16x16x32_bf16 v[42:45], v[90:93], v[74:77], v[42:45]
	v_mfma_f32_16x16x32_bf16 v[38:41], v[94:97], v[74:77], v[38:41]
	v_mfma_f32_16x16x32_bf16 v[34:37], v[98:101], v[74:77], v[34:37]
	v_mfma_f32_16x16x32_bf16 v[30:33], v[86:89], v[78:81], v[30:33]
	v_mfma_f32_16x16x32_bf16 v[26:29], v[90:93], v[78:81], v[26:29]
	v_mfma_f32_16x16x32_bf16 v[22:25], v[94:97], v[78:81], v[22:25]
	v_mfma_f32_16x16x32_bf16 v[18:21], v[98:101], v[78:81], v[18:21]
	v_mfma_f32_16x16x32_bf16 v[14:17], v[86:89], v[82:85], v[14:17]
	v_mfma_f32_16x16x32_bf16 v[10:13], v[90:93], v[82:85], v[10:13]
	v_mfma_f32_16x16x32_bf16 v[6:9], v[94:97], v[82:85], v[6:9]
	v_mfma_f32_16x16x32_bf16 v[2:5], v[98:101], v[82:85], v[2:5]
	s_waitcnt lgkmcnt(3)
	v_mfma_f32_16x16x32_bf16 v[62:65], v[66:69], v[102:105], v[62:65]
	s_waitcnt lgkmcnt(2)
	v_mfma_f32_16x16x32_bf16 v[58:61], v[118:121], v[102:105], v[58:61]
	s_waitcnt lgkmcnt(1)
	v_mfma_f32_16x16x32_bf16 v[54:57], v[126:129], v[102:105], v[54:57]
	s_waitcnt lgkmcnt(0)
	v_mfma_f32_16x16x32_bf16 v[50:53], v[130:133], v[102:105], v[50:53]
	v_mfma_f32_16x16x32_bf16 v[46:49], v[66:69], v[106:109], v[46:49]
	v_mfma_f32_16x16x32_bf16 v[42:45], v[118:121], v[106:109], v[42:45]
	v_mfma_f32_16x16x32_bf16 v[38:41], v[126:129], v[106:109], v[38:41]
	v_mfma_f32_16x16x32_bf16 v[34:37], v[130:133], v[106:109], v[34:37]
	v_mfma_f32_16x16x32_bf16 v[30:33], v[66:69], v[110:113], v[30:33]
	v_mfma_f32_16x16x32_bf16 v[26:29], v[118:121], v[110:113], v[26:29]
	v_mfma_f32_16x16x32_bf16 v[22:25], v[126:129], v[110:113], v[22:25]
	v_mfma_f32_16x16x32_bf16 v[18:21], v[130:133], v[110:113], v[18:21]
	v_mfma_f32_16x16x32_bf16 v[14:17], v[66:69], v[114:117], v[14:17]
	v_mfma_f32_16x16x32_bf16 v[10:13], v[118:121], v[114:117], v[10:13]
	v_mfma_f32_16x16x32_bf16 v[6:9], v[126:129], v[114:117], v[6:9]
	v_mfma_f32_16x16x32_bf16 v[2:5], v[130:133], v[114:117], v[2:5]
	s_setprio 0
	s_waitcnt vmcnt(0)
	s_add_i32 s7, s7, s20
	s_cmpk_gt_i32 s7, 0x1fff
	s_cselect_b64 s[38:39], -1, 0
	s_cmpk_lt_i32 s7, 0x2000
	s_barrier
; DEVI int opaque_tid() { int t = __builtin_amdgcn_workitem_id_x(); asm volatile("" : "+v"(t)); return t; }
; DEVI int k_rot(int mt, int nt, int nk) { return (((mt & 7) + (nt & 7)) & 7) * nk >> 3; }
;   const int tid = opaque_tid();
;   const int lrow = tid >> 3, lpos = tid & 7;
;   const int gch = (lpos ^ (lrow & 7)) * 8 + koff * 64;
;   char* ab = smem + tid * 16;
; #pragma unroll
;   for (int i = 0; i < 4; ++i)
;     __builtin_amdgcn_global_load_lds((const unsigned*)(A + (unsigned)(arow(m0 + lrow + 32 * i) + gch)), (unsigned*)(ab + i * 4096), 16, 0, 0);
; #pragma unroll
;   for (int i = 0; i < NF; ++i)
;     __builtin_amdgcn_global_load_lds((const unsigned*)(Bt + (unsigned)((n0 + lrow + 32 * i) * ldb + gch)), (unsigned*)(ab + 16384 + i * 4096), 16, 0, 0);
; }
; template <int EPI>
; DEVI void phase_gemm(const Params& p, const bf16* A, int lda, const bf16* Bt, int K, int NT, bf16* dst, int ldd, char* smem, bool nostore = false,
;                      const float* lng = nullptr, const float* lnb = nullptr) {
;     ...
;     if (t + (int)gridDim.x < 256 * NT) {
;       int mt2, nt2; tile_swz(t + gridDim.x, 256, NT, mt2, nt2);
;       gemm_prefetch0<4>(A, RowLinear{lda}, Bt, K, mt2 * 128, nt2 * 128, smem, KROT ? k_rot(mt2, nt2, K >> 6) : 0);
;     }
	s_cbranch_scc0 .LBB0_1861
	s_lshl_b32 s10, s7, 10
	s_and_b32 s10, s10, 0x1c00
	s_ashr_i32 s11, s7, 3
	s_add_i32 s10, s10, s11
	s_ashr_i32 s42, s10, 31
	s_lshr_b32 s42, s42, 24
	s_add_i32 s42, s10, s42
	v_mov_b32_e32 v0, v154
	s_ashr_i32 s42, s42, 8
	s_lshl_b32 s11, s11, 7
	s_lshl_b32 s43, s42, 10
	v_ashrrev_i32_e32 v68, 3, v0
	s_and_b32 s11, s11, 0x380
	v_xor_b32_e32 v66, v68, v0
	s_or_b32 s11, s43, s11
	v_lshlrev_b32_e32 v66, 3, v66
	v_and_b32_e32 v69, 56, v66
	v_lshlrev_b32_e32 v70, 4, v0
	v_add_u32_e32 v0, s11, v68
	v_lshl_or_b32 v0, v0, 10, v69
	v_readfirstlane_b32 s11, v70
	v_lshl_add_u64 v[66:67], v[0:1], 1, s[8:9]
	s_mov_b32 m0, s11
	v_add_u32_e32 v71, 0x1000, v70
	global_load_lds_dwordx4 v[66:67], off
	v_add_u32_e32 v66, 0x8000, v0
	v_mov_b32_e32 v67, v1
	v_readfirstlane_b32 s11, v71
	v_lshl_add_u64 v[66:67], v[66:67], 1, s[8:9]
	s_mov_b32 m0, s11
	v_add_u32_e32 v71, 0x2000, v70
	s_lshl_b32 s42, s42, 12
	s_lshl_b32 s10, s10, 4
	global_load_lds_dwordx4 v[66:67], off
	v_add_u32_e32 v66, 0x10000, v0
	v_mov_b32_e32 v67, v1
	v_readfirstlane_b32 s11, v71
	s_sub_i32 s10, s10, s42
	v_lshl_add_u64 v[66:67], v[66:67], 1, s[8:9]
	s_mov_b32 m0, s11
	v_add_u32_e32 v0, 0x18000, v0
	s_and_b32 s10, s10, 0x3fff80
	global_load_lds_dwordx4 v[66:67], off
	v_lshl_add_u64 v[66:67], v[0:1], 1, s[8:9]
	v_add_u32_e32 v0, 0x3000, v70
	s_nop 0
	v_readfirstlane_b32 s11, v0
	v_add_u32_e32 v0, s10, v68
	v_add_u32_e32 v68, 0x4000, v70
	s_mov_b32 m0, s11
	v_lshl_or_b32 v0, v0, 10, v69
	v_readfirstlane_b32 s10, v68
	global_load_lds_dwordx4 v[66:67], off
	v_lshl_add_u64 v[66:67], v[0:1], 1, s[36:37]
	s_mov_b32 m0, s10
	v_add_u32_e32 v68, 0x5000, v70
	global_load_lds_dwordx4 v[66:67], off
	v_add_u32_e32 v66, 0x8000, v0
	v_mov_b32_e32 v67, v1
	v_readfirstlane_b32 s10, v68
	v_lshl_add_u64 v[66:67], v[66:67], 1, s[36:37]
	s_mov_b32 m0, s10
	v_add_u32_e32 v68, 0x6000, v70
	global_load_lds_dwordx4 v[66:67], off
	v_add_u32_e32 v66, 0x10000, v0
	v_mov_b32_e32 v67, v1
	v_readfirstlane_b32 s10, v68
	v_lshl_add_u64 v[66:67], v[66:67], 1, s[36:37]
	s_mov_b32 m0, s10
	v_add_u32_e32 v0, 0x18000, v0
	global_load_lds_dwordx4 v[66:67], off
	v_lshl_add_u64 v[66:67], v[0:1], 1, s[36:37]
	v_add_u32_e32 v0, 0x7000, v70
	s_nop 0
	v_readfirstlane_b32 s10, v0
	s_mov_b32 m0, s10
	s_nop 0
	global_load_lds_dwordx4 v[66:67], off
	s_branch .LBB0_1861

; DEVI int k_rot(int mt, int nt, int nk) { return (((mt & 7) + (nt & 7)) & 7) * nk >> 3; }
;     ...
;   if (!PRE) GL_ISSUE(0, 0)
;   asm volatile("s_waitcnt vmcnt(0)" ::: "memory");
;   __syncthreads();
;   const int swz = fr & 7;
;   for (int kt = 0; kt < nk; ++kt) {
;     if (kt + 1 < nk) GL_ISSUE(kt + 1, (kt + 1) & 1)
;     const char* As = smem + (kt & 1) * 32768;
;     const char* Bs = As + 16384;
;     if (DEEP) {
;     bf16x8 af[2][4], bfr[2][NF];
; #pragma unroll
;     for (int ks = 0; ks < 2; ++ks) {
;       const int co = ((ks * 4 + fq) ^ swz) * 16;
; #pragma unroll
;       for (int m = 0; m < 4; ++m) af[ks][m] = *(const bf16x8*)(As + (wr * 64 + m * 16 + fr) * 128 + co);
; #pragma unroll
;       for (int n = 0; n < NF; ++n) bfr[ks][n] = *(const bf16x8*)(Bs + (wc * 16 * NF + n * 16 + fr) * 128 + co);
;     }
;     __builtin_amdgcn_s_setprio(1);
; #pragma unroll
;     for (int ks = 0; ks < 2; ++ks)
; #pragma unroll
;       for (int m = 0; m < 4; ++m)
; #pragma unroll
;         for (int n = 0; n < NF; ++n) {
;           if (SWAP) acc[m][n] = __builtin_amdgcn_mfma_f32_16x16x32_bf16(bfr[ks][n], af[ks][m], acc[m][n], 0, 0, 0);
;           else acc[m][n] = __builtin_amdgcn_mfma_f32_16x16x32_bf16(af[ks][m], bfr[ks][n], acc[m][n], 0, 0, 0);
;         }
;     __builtin_amdgcn_s_setprio(0);
;     __builtin_amdgcn_sched_group_barrier(0x100, 4 + NF, 0);
; #pragma unroll
;     for (int i = 0; i < 4 + NF; ++i) { __builtin_amdgcn_sched_group_barrier(0x008, 2, 0); __builtin_amdgcn_sched_group_barrier(0x100, 1, 0); }
;     __builtin_amdgcn_sched_group_barrier(0x008, 8 * NF - 2 * (4 + NF), 0);
; template <int EPI>
; DEVI void phase_gemm(const Params& p, const bf16* A, int lda, const bf16* Bt, int K, int NT, bf16* dst, int ldd, char* smem, bool nostore = false,
;                      const float* lng = nullptr, const float* lnb = nullptr) {
;     ...
;   for (; t < 256 * NT; t += gridDim.x) {
;     int mt, nt; tile_swz(t, 256, NT, mt, nt);
;     f32x4 acc[4][4]; zero_acc(acc);
;     gemm_mainloop_g<4, true, RowLinear, true, DEEP_FRAG != 0>(acc, A, RowLinear{lda}, 64, Bt, K, K, mt * 128, nt * 128, smem, KROT ? k_rot(mt, nt, K >> 6) : 0);
.LBB0_1913:
	s_lshl_b32 s6, s13, 4
	s_and_b32 s10, s6, 0x7000
	s_lshl_b32 s6, s38, 8
	s_and_b32 s7, s6, 0x700
	s_ashr_i32 s11, s38, 3
	s_add_i32 s7, s7, s11
	s_ashr_i32 s6, s7, 31
	s_lshr_b32 s6, s6, 26
	s_add_i32 s6, s7, s6
	s_lshl_b32 s6, s6, 4
	v_mov_b32_e32 v0, v154
	s_and_b32 s36, s6, 0xfffffc00
	s_lshl_b32 s6, s11, 7
	s_lshl_b32 s11, s11, 4
	v_ashrrev_i32_e32 v35, 3, v0
	v_lshrrev_b32_e32 v34, 4, v0
	v_xor_b32_e32 v36, v35, v0
	v_bfe_u32 v37, v0, 4, 2
	v_and_b32_e32 v38, 7, v0
	v_and_b32_e32 v39, 15, v0
	v_lshlrev_b32_e32 v102, 4, v0
	v_lshrrev_b32_e32 v40, 1, v0
	v_lshlrev_b32_e32 v0, 7, v0
	s_add_i32 s10, s10, s11
	s_and_b32 s6, s6, 0x380
	v_and_b32_e32 v98, 0x2780, v0
	v_bitop3_b32 v0, v34, v38, 3 bitop3:0x6c
	s_sub_i32 s10, s10, s36
	v_lshlrev_b32_e32 v36, 3, v36
	v_lshlrev_b32_e32 v101, 4, v0
	v_bitop3_b32 v0, v37, v38, 4 bitop3:0x36
	s_or_b32 s6, s6, s36
	s_lshl_b32 s10, s10, 12
	v_and_b32_e32 v36, 56, v36
	s_waitcnt vmcnt(0)
	v_lshlrev_b32_e32 v99, 4, v0
	v_add_u32_e32 v0, s6, v35
	s_and_b32 s10, s10, 0xfff80000
	v_and_or_b32 v39, v40, s79, v39
	v_lshl_or_b32 v103, v0, 12, v36
	v_lshl_add_u32 v0, v35, 12, s10
	v_mov_b32_e32 v34, 0
	v_lshlrev_b32_e32 v100, 7, v39
	v_or_b32_e32 v104, v0, v36
	s_mov_b32 s11, 0
	s_mov_b32 s10, 0
	v_mov_b32_e32 v35, v34
	v_mov_b32_e32 v36, v34
	v_mov_b32_e32 v37, v34
	v_mov_b32_e32 v38, v34
	v_mov_b32_e32 v39, v34
	v_mov_b32_e32 v40, v34
	v_mov_b32_e32 v41, v34
	v_mov_b32_e32 v42, v34
	v_mov_b32_e32 v43, v34
	v_mov_b32_e32 v44, v34
	v_mov_b32_e32 v45, v34
	v_mov_b32_e32 v46, v34
	v_mov_b32_e32 v47, v34
	v_mov_b32_e32 v48, v34
	v_mov_b32_e32 v49, v34
	v_mov_b32_e32 v50, v34
	v_mov_b32_e32 v51, v34
	v_mov_b32_e32 v52, v34
	v_mov_b32_e32 v53, v34
	v_mov_b32_e32 v54, v34
	v_mov_b32_e32 v55, v34
	v_mov_b32_e32 v56, v34
	v_mov_b32_e32 v57, v34
	v_mov_b32_e32 v58, v34
	v_mov_b32_e32 v59, v34
	v_mov_b32_e32 v60, v34
	v_mov_b32_e32 v61, v34
	v_mov_b32_e32 v62, v34
	v_mov_b32_e32 v63, v34
	v_mov_b32_e32 v64, v34
	v_mov_b32_e32 v65, v34
	v_mov_b32_e32 v66, v34
	v_mov_b32_e32 v67, v34
	v_mov_b32_e32 v68, v34
	v_mov_b32_e32 v69, v34
	v_mov_b32_e32 v70, v34
	v_mov_b32_e32 v71, v34
	v_mov_b32_e32 v72, v34
	v_mov_b32_e32 v73, v34
	v_mov_b32_e32 v74, v34
	v_mov_b32_e32 v75, v34
	v_mov_b32_e32 v76, v34
	v_mov_b32_e32 v77, v34
	v_mov_b32_e32 v78, v34
	v_mov_b32_e32 v79, v34
	v_mov_b32_e32 v80, v34
	v_mov_b32_e32 v81, v34
	v_mov_b32_e32 v82, v34
	v_mov_b32_e32 v83, v34
	v_mov_b32_e32 v84, v34
	v_mov_b32_e32 v85, v34
	v_mov_b32_e32 v86, v34
	v_mov_b32_e32 v87, v34
	v_mov_b32_e32 v88, v34
	v_mov_b32_e32 v89, v34
	v_mov_b32_e32 v90, v34
	v_mov_b32_e32 v91, v34
	v_mov_b32_e32 v92, v34
	v_mov_b32_e32 v93, v34
	v_mov_b32_e32 v94, v34
	v_mov_b32_e32 v95, v34
	v_mov_b32_e32 v96, v34
	v_mov_b32_e32 v97, v34
	v_lshlrev_b32_e32 v232, 1, v103
	v_add_u32_e32 v233, 0x40000, v232
	v_add_u32_e32 v234, 0x80000, v232
	v_add_u32_e32 v235, 0xc0000, v232
	v_lshlrev_b32_e32 v236, 1, v104
	v_add_u32_e32 v237, 0x40000, v236
	v_add_u32_e32 v238, 0x80000, v236
	v_add_u32_e32 v239, 0xc0000, v236
	v_readfirstlane_b32 s68, v102
	s_add_u32 s64, s14, 0x80
	s_addc_u32 s65, s15, 0
	s_add_u32 s66, s8, 0x80
	s_addc_u32 s67, s9, 0
	s_waitcnt vmcnt(0) lgkmcnt(0)
	s_barrier
.LBB0_1914:
	s_and_b32 s11, s11, 0x8000
	v_or_b32_e32 v0, s11, v101
	v_add_u32_e32 v105, v0, v100
	v_add_u32_e32 v0, v0, v98
	ds_read_b128 v[126:129], v0 offset:16384
	ds_read_b128 v[130:133], v0 offset:18432
	ds_read_b128 v[134:137], v0 offset:20480
	ds_read_b128 v[138:141], v0 offset:22528
	v_or_b32_e32 v0, s11, v99
	ds_read_b128 v[106:109], v105
	ds_read_b128 v[110:113], v105 offset:2048
	ds_read_b128 v[114:117], v105 offset:4096
	ds_read_b128 v[118:121], v105 offset:6144
	s_add_i32 s37, s11, 0x8000
	s_and_b32 s69, s37, 0x8000
	s_add_i32 s69, s69, s68
	v_add_u32_e32 v105, v0, v100
	v_add_u32_e32 v0, v0, v98
	s_mov_b32 m0, s69
	s_nop 0
	global_load_lds_dwordx4 v232, s[64:65]
	ds_read_b128 v[142:145], v105
	s_add_i32 m0, s69, 0x1000
	s_nop 0
	global_load_lds_dwordx4 v233, s[64:65]
	ds_read_b128 v[146:149], v105 offset:2048
	s_add_i32 m0, s69, 0x2000
	s_nop 0
	global_load_lds_dwordx4 v234, s[64:65]
	ds_read_b128 v[150:153], v105 offset:4096
	s_add_i32 m0, s69, 0x3000
	s_nop 0
	global_load_lds_dwordx4 v235, s[64:65]
	ds_read_b128 v[192:195], v105 offset:6144
	s_add_i32 m0, s69, 0x4000
	s_nop 0
	global_load_lds_dwordx4 v236, s[66:67]
	ds_read_b128 v[196:199], v0 offset:16384
	s_add_i32 m0, s69, 0x5000
	s_nop 0
	global_load_lds_dwordx4 v237, s[66:67]
	ds_read_b128 v[200:203], v0 offset:18432
	s_add_i32 m0, s69, 0x6000
	s_nop 0
	global_load_lds_dwordx4 v238, s[66:67]
	ds_read_b128 v[204:207], v0 offset:20480
	s_add_i32 m0, s69, 0x7000
	s_nop 0
	global_load_lds_dwordx4 v239, s[66:67]
	ds_read_b128 v[208:211], v0 offset:22528
	s_add_u32 s64, s64, 0x80
	s_addc_u32 s65, s65, 0
	s_add_u32 s66, s66, 0x80
	s_addc_u32 s67, s67, 0
	s_setprio 1
	s_waitcnt lgkmcnt(11)
	v_mfma_f32_16x16x32_bf16 v[94:97], v[126:129], v[106:109], v[94:97]
	v_mfma_f32_16x16x32_bf16 v[90:93], v[130:133], v[106:109], v[90:93]
	v_mfma_f32_16x16x32_bf16 v[86:89], v[134:137], v[106:109], v[86:89]
	v_mfma_f32_16x16x32_bf16 v[82:85], v[138:141], v[106:109], v[82:85]
	s_waitcnt lgkmcnt(10)
	v_mfma_f32_16x16x32_bf16 v[78:81], v[126:129], v[110:113], v[78:81]
	v_mfma_f32_16x16x32_bf16 v[74:77], v[130:133], v[110:113], v[74:77]
	v_mfma_f32_16x16x32_bf16 v[70:73], v[134:137], v[110:113], v[70:73]
	v_mfma_f32_16x16x32_bf16 v[66:69], v[138:141], v[110:113], v[66:69]
	s_waitcnt lgkmcnt(9)
; DEVI int k_rot(int mt, int nt, int nk) { return (((mt & 7) + (nt & 7)) & 7) * nk >> 3; }
;     ...
;     if (DEEP) {
;     bf16x8 af[2][4], bfr[2][NF];
; #pragma unroll
;     for (int ks = 0; ks < 2; ++ks) {
;       const int co = ((ks * 4 + fq) ^ swz) * 16;
; #pragma unroll
;       for (int m = 0; m < 4; ++m) af[ks][m] = *(const bf16x8*)(As + (wr * 64 + m * 16 + fr) * 128 + co);
; #pragma unroll
;       for (int n = 0; n < NF; ++n) bfr[ks][n] = *(const bf16x8*)(Bs + (wc * 16 * NF + n * 16 + fr) * 128 + co);
;     }
;     __builtin_amdgcn_s_setprio(1);
; #pragma unroll
;     for (int ks = 0; ks < 2; ++ks)
; #pragma unroll
;       for (int m = 0; m < 4; ++m)
; #pragma unroll
;         for (int n = 0; n < NF; ++n) {
;           if (SWAP) acc[m][n] = __builtin_amdgcn_mfma_f32_16x16x32_bf16(bfr[ks][n], af[ks][m], acc[m][n], 0, 0, 0);
;           else acc[m][n] = __builtin_amdgcn_mfma_f32_16x16x32_bf16(af[ks][m], bfr[ks][n], acc[m][n], 0, 0, 0);
;         }
;     __builtin_amdgcn_s_setprio(0);
;     __builtin_amdgcn_sched_group_barrier(0x100, 4 + NF, 0);
; #pragma unroll
;     for (int i = 0; i < 4 + NF; ++i) { __builtin_amdgcn_sched_group_barrier(0x008, 2, 0); __builtin_amdgcn_sched_group_barrier(0x100, 1, 0); }
;     __builtin_amdgcn_sched_group_barrier(0x008, 8 * NF - 2 * (4 + NF), 0);
; template <int EPI>
; DEVI void phase_gemm(const Params& p, const bf16* A, int lda, const bf16* Bt, int K, int NT, bf16* dst, int ldd, char* smem, bool nostore = false,
;                      const float* lng = nullptr, const float* lnb = nullptr) {
;     ...
;   for (; t < 256 * NT; t += gridDim.x) {
;     int mt, nt; tile_swz(t, 256, NT, mt, nt);
;     f32x4 acc[4][4]; zero_acc(acc);
;     gemm_mainloop_g<4, true, RowLinear, true, DEEP_FRAG != 0>(acc, A, RowLinear{lda}, 64, Bt, K, K, mt * 128, nt * 128, smem, KROT ? k_rot(mt, nt, K >> 6) : 0);
;     if (t + (int)gridDim.x < 256 * NT) {
	v_mfma_f32_16x16x32_bf16 v[62:65], v[126:129], v[114:117], v[62:65]
	v_mfma_f32_16x16x32_bf16 v[58:61], v[130:133], v[114:117], v[58:61]
	v_mfma_f32_16x16x32_bf16 v[54:57], v[134:137], v[114:117], v[54:57]
	v_mfma_f32_16x16x32_bf16 v[50:53], v[138:141], v[114:117], v[50:53]
	s_waitcnt lgkmcnt(8)
	v_mfma_f32_16x16x32_bf16 v[46:49], v[126:129], v[118:121], v[46:49]
	v_mfma_f32_16x16x32_bf16 v[42:45], v[130:133], v[118:121], v[42:45]
	v_mfma_f32_16x16x32_bf16 v[38:41], v[134:137], v[118:121], v[38:41]
	v_mfma_f32_16x16x32_bf16 v[34:37], v[138:141], v[118:121], v[34:37]
	s_waitcnt lgkmcnt(3)
	v_mfma_f32_16x16x32_bf16 v[94:97], v[196:199], v[142:145], v[94:97]
	s_waitcnt lgkmcnt(2)
	v_mfma_f32_16x16x32_bf16 v[90:93], v[200:203], v[142:145], v[90:93]
	s_waitcnt lgkmcnt(1)
	v_mfma_f32_16x16x32_bf16 v[86:89], v[204:207], v[142:145], v[86:89]
	s_waitcnt lgkmcnt(0)
	v_mfma_f32_16x16x32_bf16 v[82:85], v[208:211], v[142:145], v[82:85]
	v_mfma_f32_16x16x32_bf16 v[78:81], v[196:199], v[146:149], v[78:81]
	v_mfma_f32_16x16x32_bf16 v[74:77], v[200:203], v[146:149], v[74:77]
	v_mfma_f32_16x16x32_bf16 v[70:73], v[204:207], v[146:149], v[70:73]
	v_mfma_f32_16x16x32_bf16 v[66:69], v[208:211], v[146:149], v[66:69]
	v_mfma_f32_16x16x32_bf16 v[62:65], v[196:199], v[150:153], v[62:65]
	v_mfma_f32_16x16x32_bf16 v[58:61], v[200:203], v[150:153], v[58:61]
	v_mfma_f32_16x16x32_bf16 v[54:57], v[204:207], v[150:153], v[54:57]
	v_mfma_f32_16x16x32_bf16 v[50:53], v[208:211], v[150:153], v[50:53]
	v_mfma_f32_16x16x32_bf16 v[46:49], v[196:199], v[192:195], v[46:49]
	v_mfma_f32_16x16x32_bf16 v[42:45], v[200:203], v[192:195], v[42:45]
	v_mfma_f32_16x16x32_bf16 v[38:41], v[204:207], v[192:195], v[38:41]
	v_mfma_f32_16x16x32_bf16 v[34:37], v[208:211], v[192:195], v[34:37]
	s_setprio 0
	s_waitcnt vmcnt(0)
	s_add_i32 s10, s10, 64
	s_cmpk_eq_i32 s10, 0xfc0
	s_mov_b32 s11, s37
	s_waitcnt vmcnt(0)
	s_barrier
	s_cbranch_scc0 .LBB0_1914
	v_add_u32_e32 v0, v101, v100
	ds_read_b128 v[102:105], v0 offset:32768
	ds_read_b128 v[106:109], v0 offset:34816
	ds_read_b128 v[110:113], v0 offset:36864
	ds_read_b128 v[114:117], v0 offset:38912
	v_add_u32_e32 v0, v101, v98
	ds_read_b128 v[118:121], v0 offset:49152
	ds_read_b128 v[126:129], v0 offset:51200
	ds_read_b128 v[130:133], v0 offset:53248
	ds_read_b128 v[134:137], v0 offset:55296
	v_add_u32_e32 v0, v99, v100
	ds_read_b128 v[138:141], v0 offset:32768
	ds_read_b128 v[142:145], v0 offset:34816
	ds_read_b128 v[146:149], v0 offset:36864
	ds_read_b128 v[150:153], v0 offset:38912
	v_add_u32_e32 v0, v99, v98
	ds_read_b128 v[98:101], v0 offset:49152
	ds_read_b128 v[192:195], v0 offset:51200
	ds_read_b128 v[196:199], v0 offset:53248
	ds_read_b128 v[200:203], v0 offset:55296
	s_setprio 1
	s_waitcnt lgkmcnt(11)
	v_mfma_f32_16x16x32_bf16 v[94:97], v[118:121], v[102:105], v[94:97]
	s_waitcnt lgkmcnt(10)
	v_mfma_f32_16x16x32_bf16 v[90:93], v[126:129], v[102:105], v[90:93]
	s_waitcnt lgkmcnt(9)
	v_mfma_f32_16x16x32_bf16 v[86:89], v[130:133], v[102:105], v[86:89]
	s_waitcnt lgkmcnt(8)
	v_mfma_f32_16x16x32_bf16 v[82:85], v[134:137], v[102:105], v[82:85]
	v_mfma_f32_16x16x32_bf16 v[78:81], v[118:121], v[106:109], v[78:81]
	v_mfma_f32_16x16x32_bf16 v[74:77], v[126:129], v[106:109], v[74:77]
	v_mfma_f32_16x16x32_bf16 v[70:73], v[130:133], v[106:109], v[70:73]
	v_mfma_f32_16x16x32_bf16 v[66:69], v[134:137], v[106:109], v[66:69]
	v_mfma_f32_16x16x32_bf16 v[62:65], v[118:121], v[110:113], v[62:65]
	v_mfma_f32_16x16x32_bf16 v[58:61], v[126:129], v[110:113], v[58:61]
	v_mfma_f32_16x16x32_bf16 v[54:57], v[130:133], v[110:113], v[54:57]
	v_mfma_f32_16x16x32_bf16 v[50:53], v[134:137], v[110:113], v[50:53]
	v_mfma_f32_16x16x32_bf16 v[46:49], v[118:121], v[114:117], v[46:49]
	v_mfma_f32_16x16x32_bf16 v[42:45], v[126:129], v[114:117], v[42:45]
	v_mfma_f32_16x16x32_bf16 v[38:41], v[130:133], v[114:117], v[38:41]
	v_mfma_f32_16x16x32_bf16 v[34:37], v[134:137], v[114:117], v[34:37]
	s_waitcnt lgkmcnt(3)
	v_mfma_f32_16x16x32_bf16 v[94:97], v[98:101], v[138:141], v[94:97]
	s_waitcnt lgkmcnt(2)
	v_mfma_f32_16x16x32_bf16 v[90:93], v[192:195], v[138:141], v[90:93]
	s_waitcnt lgkmcnt(1)
	v_mfma_f32_16x16x32_bf16 v[86:89], v[196:199], v[138:141], v[86:89]
	s_waitcnt lgkmcnt(0)
	v_mfma_f32_16x16x32_bf16 v[82:85], v[200:203], v[138:141], v[82:85]
	v_mfma_f32_16x16x32_bf16 v[78:81], v[98:101], v[142:145], v[78:81]
	v_mfma_f32_16x16x32_bf16 v[74:77], v[192:195], v[142:145], v[74:77]
	v_mfma_f32_16x16x32_bf16 v[70:73], v[196:199], v[142:145], v[70:73]
	v_mfma_f32_16x16x32_bf16 v[66:69], v[200:203], v[142:145], v[66:69]
	v_mfma_f32_16x16x32_bf16 v[62:65], v[98:101], v[146:149], v[62:65]
	v_mfma_f32_16x16x32_bf16 v[58:61], v[192:195], v[146:149], v[58:61]
	v_mfma_f32_16x16x32_bf16 v[54:57], v[196:199], v[146:149], v[54:57]
	v_mfma_f32_16x16x32_bf16 v[50:53], v[200:203], v[146:149], v[50:53]
	v_mfma_f32_16x16x32_bf16 v[46:49], v[98:101], v[150:153], v[46:49]
	v_mfma_f32_16x16x32_bf16 v[42:45], v[192:195], v[150:153], v[42:45]
	v_mfma_f32_16x16x32_bf16 v[38:41], v[196:199], v[150:153], v[38:41]
	v_mfma_f32_16x16x32_bf16 v[34:37], v[200:203], v[150:153], v[34:37]
	s_setprio 0
	s_waitcnt vmcnt(0)
	s_add_i32 s38, s38, s20
	s_cmpk_gt_i32 s38, 0x7ff
	s_cselect_b64 s[10:11], -1, 0
	s_cmpk_lt_i32 s38, 0x800
	s_barrier
; DEVI int opaque_tid() { int t = __builtin_amdgcn_workitem_id_x(); asm volatile("" : "+v"(t)); return t; }
; DEVI int k_rot(int mt, int nt, int nk) { return (((mt & 7) + (nt & 7)) & 7) * nk >> 3; }
;   const int tid = opaque_tid();
;   const int lrow = tid >> 3, lpos = tid & 7;
;   const int gch = (lpos ^ (lrow & 7)) * 8 + koff * 64;
;   char* ab = smem + tid * 16;
; #pragma unroll
;   for (int i = 0; i < 4; ++i)
;     __builtin_amdgcn_global_load_lds((const unsigned*)(A + (unsigned)(arow(m0 + lrow + 32 * i) + gch)), (unsigned*)(ab + i * 4096), 16, 0, 0);
; #pragma unroll
;   for (int i = 0; i < NF; ++i)
;     __builtin_amdgcn_global_load_lds((const unsigned*)(Bt + (unsigned)((n0 + lrow + 32 * i) * ldb + gch)), (unsigned*)(ab + 16384 + i * 4096), 16, 0, 0);
; }
; template <int EPI>
; DEVI void phase_gemm(const Params& p, const bf16* A, int lda, const bf16* Bt, int K, int NT, bf16* dst, int ldd, char* smem, bool nostore = false,
;                      const float* lng = nullptr, const float* lnb = nullptr) {
;     ...
;     if (t + (int)gridDim.x < 256 * NT) {
;       int mt2, nt2; tile_swz(t + gridDim.x, 256, NT, mt2, nt2);
;       gemm_prefetch0<4>(A, RowLinear{lda}, Bt, K, mt2 * 128, nt2 * 128, smem, KROT ? k_rot(mt2, nt2, K >> 6) : 0);
;     }
	s_cbranch_scc0 .LBB0_1917
	s_lshl_b32 s37, s38, 8
	s_and_b32 s37, s37, 0x700
	s_ashr_i32 s39, s38, 3
	s_add_i32 s37, s37, s39
	s_ashr_i32 s40, s37, 31
	s_lshr_b32 s40, s40, 26
	s_add_i32 s40, s37, s40
	v_mov_b32_e32 v0, v154
	s_lshl_b32 s40, s40, 4
	s_lshl_b32 s39, s39, 7
	s_and_b32 s40, s40, 0xfffffc00
	v_ashrrev_i32_e32 v100, 3, v0
	s_and_b32 s39, s39, 0x380
	v_xor_b32_e32 v98, v100, v0
	s_or_b32 s39, s40, s39
	v_lshlrev_b32_e32 v98, 3, v98
	v_and_b32_e32 v101, 56, v98
	v_lshlrev_b32_e32 v102, 4, v0
	v_add_u32_e32 v0, s39, v100
	v_lshl_or_b32 v0, v0, 12, v101
	v_readfirstlane_b32 s39, v102
	v_lshl_add_u64 v[98:99], v[0:1], 1, s[14:15]
	s_mov_b32 m0, s39
	v_add_u32_e32 v103, 0x1000, v102
	global_load_lds_dwordx4 v[98:99], off
	v_add_u32_e32 v98, 0x20000, v0
	v_mov_b32_e32 v99, v1
	v_readfirstlane_b32 s39, v103
	v_lshl_add_u64 v[98:99], v[98:99], 1, s[14:15]
	s_mov_b32 m0, s39
	v_add_u32_e32 v103, 0x2000, v102
	s_lshl_b32 s37, s37, 4
	global_load_lds_dwordx4 v[98:99], off
	v_add_u32_e32 v98, 0x40000, v0
	v_mov_b32_e32 v99, v1
	v_readfirstlane_b32 s39, v103
	s_sub_i32 s37, s37, s40
	v_lshl_add_u64 v[98:99], v[98:99], 1, s[14:15]
	s_mov_b32 m0, s39
	v_add_u32_e32 v0, 0x60000, v0
	s_and_b32 s37, s37, 0xfff80
	global_load_lds_dwordx4 v[98:99], off
	v_lshl_add_u64 v[98:99], v[0:1], 1, s[14:15]
	v_add_u32_e32 v0, 0x3000, v102
	s_nop 0
	v_readfirstlane_b32 s39, v0
	v_add_u32_e32 v0, s37, v100
	v_add_u32_e32 v100, 0x4000, v102
	s_mov_b32 m0, s39
	v_lshl_or_b32 v0, v0, 12, v101
	v_readfirstlane_b32 s37, v100
	global_load_lds_dwordx4 v[98:99], off
	v_lshl_add_u64 v[98:99], v[0:1], 1, s[8:9]
	s_mov_b32 m0, s37
	v_add_u32_e32 v100, 0x5000, v102
	global_load_lds_dwordx4 v[98:99], off
	v_add_u32_e32 v98, 0x20000, v0
	v_mov_b32_e32 v99, v1
	v_readfirstlane_b32 s37, v100
	v_lshl_add_u64 v[98:99], v[98:99], 1, s[8:9]
	s_mov_b32 m0, s37
	v_add_u32_e32 v100, 0x6000, v102
	global_load_lds_dwordx4 v[98:99], off
	v_add_u32_e32 v98, 0x40000, v0
	v_mov_b32_e32 v99, v1
	v_readfirstlane_b32 s37, v100
	v_lshl_add_u64 v[98:99], v[98:99], 1, s[8:9]
	s_mov_b32 m0, s37
	v_add_u32_e32 v0, 0x60000, v0
	global_load_lds_dwordx4 v[98:99], off
	v_lshl_add_u64 v[98:99], v[0:1], 1, s[8:9]
	v_add_u32_e32 v0, 0x7000, v102
	s_nop 0
	v_readfirstlane_b32 s37, v0
	s_mov_b32 m0, s37
	s_nop 0
	global_load_lds_dwordx4 v[98:99], off
